# ATT: K image in st_16x32 XOR-swizzled subtile layout, conflict-free ds_read_b128 K fragments (was 2-way conflicted at pitch 144)
# baseline (speedup 1.0000x reference)
; __device__ __forceinline__ int otid(int wv) { int t; asm volatile("v_mbcnt_lo_u32_b32 %0, -1, 0\n\tv_mbcnt_hi_u32_b32 %0, -1, %0\n\tv_lshl_add_u32 %0, %1, 6, %0" : "=&v"(t) : "s"(wv)); return t; }
; __device__ void att_phase(int wv, const Params& p, unsigned char* lds) {
;     const int tid = otid(wv), lane = tid & 63, w = __builtin_amdgcn_readfirstlane(tid >> 6), lr = lane & 15, lq = lane >> 4;
;     bf16_t* qkv = (bf16_t*)(p.ws + WS_BIG1);
;     constexpr int KP = 72, VP = 392;
;     bf16_t* KL = (bf16_t*)lds; bf16_t* VTL = KL + 384 * KP;
;     for (int unit = blockIdx.x; unit < 1024; unit += gridDim.x) {
;         const int B = unit >> 2, kh = unit & 3;
;         const int sb = B < 64 ? 0 : (B < 128 ? 64 : 128), se = B < 64 ? 64 : (B < 128 ? 128 : 256);
; #pragma unroll
;         for (int ps = 0; ps < 6; ++ps) { const int idx = tid + ps * NTHR, s = idx >> 3, c8 = (idx & 7) * 8; const int kb = B - 1 + (s >> 7);
;             bf16x8 kv = {0, 0, 0, 0, 0, 0, 0, 0}, vv = {0, 0, 0, 0, 0, 0, 0, 0};
;             if (kb >= sb && kb < se) { const bf16_t* rp = qkv + (size_t)(kb * 128 + (s & 127)) * 1536 + 64 * kh + c8; kv = *(const bf16x8*)(rp + 1024); vv = *(const bf16x8*)(rp + 1280); }
;             *(bf16x8*)(KL + s * KP + c8) = kv;
; #pragma unroll
;             for (int e = 0; e < 8; ++e) VTL[(c8 + e) * VP + s] = (bf16_t)vv[e]; }
.LBB0_290:
	s_cmp_eq_u32 s94, 1
	s_cselect_b64 s[4:5], -1, 0
	s_cmp_lg_u32 s94, 1
	s_cbranch_scc1 .LBB0_308
	v_mbcnt_lo_u32_b32 v2, -1, 0
	v_mbcnt_hi_u32_b32 v2, -1, v2
	v_lshl_add_u32 v2, s33, 6, v2
	s_and_b64 vcc, exec, s[0:1]
	v_readfirstlane_b32 s0, v2
	s_cbranch_vccnz .LBB0_308
	v_lshlrev_b32_e32 v1, 3, v2
	v_and_b32_e32 v10, 64, v250
	v_and_b32_e32 v7, 56, v1
	v_xor_b32_e32 v1, 16, v250
	v_add_u32_e32 v10, 64, v10
	v_cmp_lt_i32_e32 vcc, v1, v10
	v_xor_b32_e32 v11, 32, v250
	v_and_b32_e32 v3, 15, v2
	v_cndmask_b32_e32 v1, v250, v1, vcc
	v_cmp_lt_i32_e32 vcc, v11, v10
	v_bfe_u32 v6, v2, 4, 2
	v_ashrrev_i32_e32 v115, 10, v2
	v_cndmask_b32_e32 v10, v250, v11, vcc
	v_ashrrev_i32_e32 v11, 3, v2
	v_add_u32_e32 v13, 0x200, v2
	v_add_u32_e32 v15, 0x400, v2
	v_add_u32_e32 v17, 0x600, v2
	v_add_u32_e32 v19, 0x800, v2
	v_add_u32_e32 v2, 0xa00, v2
	s_movk_i32 s1, 0x90
	v_ashrrev_i32_e32 v14, 3, v13
	v_ashrrev_i32_e32 v16, 3, v15
	v_ashrrev_i32_e32 v18, 3, v17
	v_ashrrev_i32_e32 v20, 3, v19
	v_ashrrev_i32_e32 v21, 3, v2
	v_mul_lo_u32 v12, v11, s1
	v_ashrrev_i32_e32 v117, 10, v13
	v_mul_lo_u32 v13, v14, s1
	v_ashrrev_i32_e32 v119, 10, v15
	v_mul_lo_u32 v15, v16, s1
	v_ashrrev_i32_e32 v121, 10, v17
	v_mul_lo_u32 v17, v18, s1
	v_ashrrev_i32_e32 v123, 10, v19
	v_mul_lo_u32 v19, v20, s1
	v_ashrrev_i32_e32 v125, 10, v2
	v_mul_lo_u32 v22, v21, s1
	v_mov_b32_e32 v2, 0x3100
	s_movk_i32 s1, 0x310
	v_lshlrev_b32_e32 v4, 1, v7
	v_mov_b32_e32 v5, v0
	v_mad_u32_u24 v25, v3, s1, v2
	v_mov_b32_e32 v2, 0x6200
	v_add_u32_e32 v8, 0, v4
	v_lshl_add_u64 v[102:103], s[76:77], 0, v[4:5]
	s_ashr_i32 s16, s0, 7
	s_and_b32 s0, s0, 64
	v_lshlrev_b32_e32 v4, 3, v6
	v_lshlrev_b32_e32 v5, 4, v6
	v_lshlrev_b32_e32 v6, 2, v6
	v_mad_u32_u24 v26, v3, s1, v2
	v_mov_b32_e32 v2, 0x9300
	v_mul_u32_u24_e32 v23, 0x90, v3
	v_mul_u32_u24_e32 v24, 0x310, v3
	v_mad_u32_u24 v27, v3, s1, v2
	v_or_b32_e32 v2, s0, v3
	v_sub_u32_e32 v3, v6, v3
	v_sub_u32_e32 v127, v2, v6
	v_subrev_u32_e32 v3, s0, v3
	v_mul_u32_u24_e32 v6, 0xc00, v2
	v_add_u32_e32 v9, 0, v5
	v_add_u32_e32 v128, 0xf3, v3
	v_mul_hi_u32_u24_e32 v3, 0xc00, v2
	v_or_b32_e32 v2, v6, v5
	v_readlane_b32 s0, v254, 51
	v_lshlrev_b32_e32 v114, 2, v10
	v_sub_u32_e32 v10, v9, v4
	v_and_b32_e32 v116, 0x7f, v11
	v_lshl_add_u32 v11, v11, 1, 0
	v_mul_u32_u24_e32 v7, 0x310, v7
	v_and_b32_e32 v118, 0x7f, v14
	v_lshl_add_u32 v14, v14, 1, 0
	v_and_b32_e32 v120, 0x7f, v16
	v_lshl_add_u32 v16, v16, 1, 0
	v_and_b32_e32 v122, 0x7f, v18
	v_lshl_add_u32 v18, v18, 1, 0
	v_and_b32_e32 v124, 0x7f, v20
	v_lshl_add_u32 v20, v20, 1, 0
	v_and_b32_e32 v126, 0x7f, v21
	v_lshl_add_u32 v21, v21, 1, 0
	v_lshl_add_u64 v[104:105], s[30:31], 0, v[2:3]
	v_or_b32_e32 v2, v6, v4
	v_readlane_b32 s1, v254, 52
	v_lshlrev_b32_e32 v1, 2, v1
	s_lshl_b32 s17, s16, 6
	v_lshl_add_u64 v[106:107], s[0:1], 0, v[2:3]
	v_add_u32_e32 v129, v8, v12
	v_add_u32_e32 v130, v11, v7
	v_add_u32_e32 v131, v8, v13
	v_add_u32_e32 v132, v14, v7
	v_add_u32_e32 v133, v8, v15
	v_add_u32_e32 v134, v16, v7
	v_add_u32_e32 v135, v8, v17
	v_add_u32_e32 v136, v18, v7
	v_add_u32_e32 v137, v8, v19
	v_add_u32_e32 v138, v20, v7
	v_add_u32_e32 v139, v8, v22
	v_add_u32_e32 v140, v21, v7
	v_add_u32_e32 v141, v9, v23
	v_add_u32_e32 v142, v10, v24
	v_add_u32_e32 v143, v10, v25
	v_add_u32_e32 v144, v10, v26
	v_add_u32_e32 v145, v10, v27
	v_mbcnt_lo_u32_b32 v131, -1, 0
	v_mbcnt_hi_u32_b32 v131, -1, v131
	v_and_b32_e32 v133, 15, v131
	v_lshrrev_b32_e32 v135, 4, v131
	v_lshlrev_b32_e32 v135, 4, v135
	v_lshl_add_u32 v141, v133, 6, v135
	v_and_b32_e32 v133, 8, v133
	v_lshlrev_b32_e32 v133, 2, v133
	v_xor_b32_e32 v141, v141, v133
	v_lshl_add_u32 v131, s33, 6, v131
	v_lshrrev_b32_e32 v133, 3, v131
	v_and_b32_e32 v135, 15, v133
	v_lshrrev_b32_e32 v133, 4, v133
	v_and_b32_e32 v137, 7, v131
	v_lshrrev_b32_e32 v139, 2, v137
	v_and_b32_e32 v137, 3, v137
	v_lshl_add_u32 v133, v133, 1, v139
	v_lshlrev_b32_e32 v137, 4, v137
	v_lshl_add_u32 v137, v135, 6, v137
	v_and_b32_e32 v135, 8, v135
	v_lshlrev_b32_e32 v135, 2, v135
	v_xor_b32_e32 v137, v137, v135
	v_lshl_add_u32 v129, v133, 10, v137
	s_mov_b32 s20, s2
	s_mov_b32 s21, s2

; __device__ __forceinline__ f32x4 mfma16(bf16x8 a, bf16x8 b, f32x4 c) { return __builtin_amdgcn_mfma_f32_16x16x32_bf16(a, b, c, 0, 0, 0); }
; __device__ void att_phase(int wv, const Params& p, unsigned char* lds) {
;     ...
;         for (int ps = 0; ps < 6; ++ps) { const int idx = tid + ps * NTHR, s = idx >> 3, c8 = (idx & 7) * 8; const int kb = B - 1 + (s >> 7);
;             bf16x8 kv = {0, 0, 0, 0, 0, 0, 0, 0}, vv = {0, 0, 0, 0, 0, 0, 0, 0};
;             if (kb >= sb && kb < se) { const bf16_t* rp = qkv + (size_t)(kb * 128 + (s & 127)) * 1536 + 64 * kh + c8; kv = *(const bf16x8*)(rp + 1024); vv = *(const bf16x8*)(rp + 1280); }
;             *(bf16x8*)(KL + s * KP + c8) = kv;
; #pragma unroll
;             for (int e = 0; e < 8; ++e) VTL[(c8 + e) * VP + s] = (bf16_t)vv[e]; }
;         __syncthreads();
;         const int gq = w >> 1, h = 4 * kh + gq;
;         const float slope = exp2f(-0.5f * (float)(h + 1)), sink = p.b_sinks[h];
;         for (int rb = 0; rb < 4; ++rb) {
;             const int qrow = 64 * (w & 1) + 16 * rb + lr;
;             const size_t tokq = (size_t)B * 128 + qrow;
;             bf16x8 qf[2];
; #pragma unroll
;             for (int kk = 0; kk < 2; ++kk) qf[kk] = *(const bf16x8*)(qkv + tokq * 1536 + 64 * h + 32 * kk + 8 * lq);
;             f32x4 sc[24];
; #pragma unroll
;             for (int cb = 0; cb < 24; ++cb) { f32x4 a = {0, 0, 0, 0};
; #pragma unroll
;                 for (int kk = 0; kk < 2; ++kk) { const bf16x8 kf = *(const bf16x8*)(KL + (16 * cb + lr) * KP + 32 * kk + 8 * lq); a = mfma16(kf, qf[kk], a); }
;                 sc[cb] = a; }
;             float mx = sink;
; #pragma unroll
;             for (int cb = 0; cb < 24; ++cb) { const int kb = B - 1 + (cb >> 3); const bool bval = (kb >= sb && kb < se);
; #pragma unroll
;                 for (int j = 0; j < 4; ++j) { const int krel = 16 * cb + 4 * lq + j - 128;
;                     int dist = qrow - krel; dist = dist < 0 ? -dist : dist;
;                     const float v = (bval && dist <= 128) ? sc[cb][j] * 0.125f - slope * (float)dist : -1e30f;
;                     sc[cb][j] = v; mx = fmaxf(mx, v); } }
.Latt_ld_5:
	s_or_b64 exec, exec, s[0:1]
	s_mov_b32 s22, 0
	s_lshl_b32 s6, s6, 2
	s_add_i32 s6, s6, s16
	s_add_i32 s7, s6, 1
	s_waitcnt vmcnt(0)
	v_lshl_add_u32 v130, s33, 6, v250
	v_lshrrev_b32_e32 v127, 3, v130
	v_and_b32_e32 v130, 7, v130
	v_lshlrev_b32_e32 v130, 4, v130
	v_mul_u32_u24_e32 v127, 0xa0, v127
	v_add_u32_e32 v130, v127, v130
	v_add_u32_e32 v130, 0xd800, v130
	ds_write_b128 v129, v[180:183]
	ds_write_b128 v130, v[184:187]
	ds_write_b128 v129, v[188:191] offset:8192
	ds_write_b128 v130, v[192:195] offset:10240
	ds_write_b128 v129, v[196:199] offset:16384
	ds_write_b128 v130, v[200:203] offset:20480
	ds_write_b128 v129, v[204:207] offset:24576
	ds_write_b128 v130, v[208:211] offset:30720
	ds_write_b128 v129, v[212:215] offset:32768
	ds_write_b128 v130, v[216:219] offset:40960
	ds_write_b128 v129, v[220:223] offset:40960
	ds_write_b128 v130, v[224:227] offset:51200
	v_cvt_f32_i32_e32 v2, s7
	s_and_b32 s0, s20, 3
	s_lshl_b32 s0, s0, 8
	s_add_i32 s0, s17, s0
	s_ashr_i32 s1, s0, 31
	v_mul_f32_e32 v3, -0.5, v2
	s_mov_b32 s7, 0xc2fc0000
	s_lshl_b64 s[0:1], s[0:1], 1
	v_cmp_gt_f32_e32 vcc, s7, v3
	s_and_b64 s[14:15], vcc, exec
	s_cselect_b32 s14, 0xffffffc0, 0
	s_ashr_i32 s7, s6, 31
	s_lshl_b64 s[6:7], s[6:7], 2
	s_add_u32 s6, s58, s6
	s_addc_u32 s7, s59, s7
	s_waitcnt lgkmcnt(0)
	s_barrier
	global_load_dword v146, v0, s[6:7]
	v_mov_b32_e32 v3, 0x42800000
	v_cndmask_b32_e32 v3, 0, v3, vcc
	v_fmac_f32_e32 v3, -0.5, v2
	v_exp_f32_e32 v2, v3
	s_cmp_gt_i32 s23, s11
	s_cselect_b64 s[6:7], -1, 0
	s_cmp_le_i32 s23, s10
	v_ldexp_f32 v109, v2, s14
	s_cselect_b64 s[14:15], -1, 0
	s_and_b64 s[6:7], s[6:7], s[14:15]
	s_cmp_ge_i32 s23, s11
	s_cselect_b64 s[14:15], -1, 0
	s_cmp_lt_i32 s23, s10
	s_cselect_b64 s[46:47], -1, 0
	s_and_b64 s[14:15], s[14:15], s[46:47]
	s_add_i32 s36, s23, 1
	s_cmp_ge_i32 s36, s11
	s_cselect_b64 s[46:47], -1, 0
	s_cmp_lt_i32 s36, s10
	s_cselect_b64 s[10:11], -1, 0
	v_mov_b32_e32 v2, 0x60000
	s_and_b64 s[10:11], s[46:47], s[10:11]
	v_mad_i64_i32 v[110:111], s[46:47], s23, v2, v[104:105]
	v_mad_i64_i32 v[112:113], s[46:47], s23, v2, v[106:107]
	v_mov_b32_e32 v147, v128
	s_mov_b64 s[48:49], 0xc000
	v_lshl_add_u64 v[174:175], v[110:111], 0, s[0:1]
	v_add_co_u32_e32 v174, vcc, 0x83ec000, v174
	s_nop 1
	v_addc_co_u32_e32 v175, vcc, 0, v175, vcc
	v_mov_b32_e32 v180, v20
	v_mov_b32_e32 v181, v21
	v_mov_b32_e32 v182, v22
	v_mov_b32_e32 v183, v23
	v_mov_b32_e32 v184, v24
	v_mov_b32_e32 v185, v25
	v_mov_b32_e32 v186, v26
	v_mov_b32_e32 v187, v27
	v_lshl_add_u64 v[174:175], v[174:175], 0, s[48:49]
	v_mov_b32_e32 v188, v28
	v_mov_b32_e32 v189, v29
	v_mov_b32_e32 v190, v30
	v_mov_b32_e32 v191, v31
	v_mov_b32_e32 v192, v32
	v_mov_b32_e32 v193, v33
	v_mov_b32_e32 v194, v34
	v_mov_b32_e32 v195, v35
	v_lshl_add_u64 v[174:175], v[174:175], 0, s[48:49]
	v_mov_b32_e32 v196, v36
	v_mov_b32_e32 v197, v37
	v_mov_b32_e32 v198, v38
	v_mov_b32_e32 v199, v39
	v_mov_b32_e32 v200, v40
	v_mov_b32_e32 v201, v41
	v_mov_b32_e32 v202, v42
	v_mov_b32_e32 v203, v43
	v_lshl_add_u64 v[174:175], v[174:175], 0, s[48:49]
	v_mov_b32_e32 v204, v44
	v_mov_b32_e32 v205, v45
	v_mov_b32_e32 v206, v46
	v_mov_b32_e32 v207, v47
	v_mov_b32_e32 v208, v48
	v_mov_b32_e32 v209, v49
	v_mov_b32_e32 v210, v50
	v_mov_b32_e32 v211, v51
	s_and_b64 vcc, s[6:7], s[10:11]
	s_cbranch_vccz .Latt_general
	s_mov_b32 s46, 0x3e38aa3b
	s_and_b32 s47, s33, 1
	s_mul_i32 s22, s47, 0x2000
	v_add_u32_e32 v164, s22, v141
	s_mul_i32 s22, s47, 0x2800
	s_add_i32 s22, s22, 0xd800
	v_bfe_u32 v165, v250, 2, 4
	v_mul_u32_u24_e32 v165, 0xa0, v165
	v_and_b32_e32 v166, 3, v250
	v_lshl_add_u32 v165, v166, 3, v165
	v_add_u32_e32 v165, s22, v165
	s_lshl_b32 s47, s47, 2
	v_and_b32_e32 v172, 15, v250
	v_lshrrev_b32_e32 v173, 4, v250
	v_lshlrev_b32_e32 v173, 2, v173
	v_sub_u32_e32 v108, v172, v173
	v_subrev_u32_e32 v110, 1, v108
	v_subrev_u32_e32 v111, 2, v108
	v_subrev_u32_e32 v177, 3, v108
	v_mul_f32_e32 v147, 0xc1000000, v109
	v_mul_f32_e32 v174, 0x43000000, v109
	v_mul_f32_e32 v176, 0x44800000, v109
	v_cvt_f32_i32_e32 v179, v108
	v_mul_f32_e32 v94, v147, v179
	v_mul_f32_e64 v98, v147, |v179|
	v_cvt_f32_i32_e32 v179, v110
	v_mul_f32_e32 v95, v147, v179
	v_mul_f32_e64 v99, v147, |v179|
	v_cvt_f32_i32_e32 v179, v111
	v_mul_f32_e32 v96, v147, v179
	v_mul_f32_e64 v100, v147, |v179|
	v_cvt_f32_i32_e32 v179, v177
	v_mul_f32_e32 v97, v147, v179
	v_mul_f32_e64 v101, v147, |v179|
	v_lshl_add_u64 v[248:249], v[112:113], 0, s[0:1]
	v_sub_f32_e32 v86, v94, v176
	v_sub_f32_e32 v87, v95, v176
	v_sub_f32_e32 v88, v96, v176
	v_sub_f32_e32 v89, v97, v176
	v_cmp_ge_i32_e32 vcc, 0, v108
	s_nop 1
	v_cndmask_b32_e32 v212, v252, v86, vcc
	v_cmp_ge_i32_e32 vcc, 0, v110
	s_nop 1
	v_cndmask_b32_e32 v213, v252, v87, vcc
	v_cmp_ge_i32_e32 vcc, 0, v111
	s_nop 1
	v_cndmask_b32_e32 v214, v252, v88, vcc
	v_cmp_ge_i32_e32 vcc, 0, v177
	s_nop 1
	v_cndmask_b32_e32 v215, v252, v89, vcc
	ds_read_b128 v[148:151], v164
	ds_read_b128 v[152:155], v164 offset:1024
	ds_read_b128 v[156:159], v164 offset:2048
	ds_read_b128 v[160:163], v164 offset:3072
	v_add_f32_e32 v90, v86, v174
	v_add_f32_e32 v91, v87, v174
	v_add_f32_e32 v92, v88, v174
	v_add_f32_e32 v93, v89, v174
	s_waitcnt lgkmcnt(2)
	v_mfma_f32_16x16x32_bf16 v[2:5], v[148:151], v[180:183], v[212:215]
	v_mfma_f32_16x16x32_bf16 v[2:5], v[152:155], v[184:187], v[2:5]
	ds_read_b128 v[148:151], v164 offset:4096
	ds_read_b128 v[152:155], v164 offset:5120
	v_add_f32_e32 v86, v90, v174
	v_add_f32_e32 v87, v91, v174
	v_add_f32_e32 v88, v92, v174
	v_add_f32_e32 v89, v93, v174
	s_waitcnt lgkmcnt(2)
; __device__ __forceinline__ f32x4 mfma16(bf16x8 a, bf16x8 b, f32x4 c) { return __builtin_amdgcn_mfma_f32_16x16x32_bf16(a, b, c, 0, 0, 0); }
; __device__ void att_phase(int wv, const Params& p, unsigned char* lds) {
;     ...
;             for (int cb = 0; cb < 24; ++cb) { f32x4 a = {0, 0, 0, 0};
; #pragma unroll
;                 for (int kk = 0; kk < 2; ++kk) { const bf16x8 kf = *(const bf16x8*)(KL + (16 * cb + lr) * KP + 32 * kk + 8 * lq); a = mfma16(kf, qf[kk], a); }
;                 sc[cb] = a; }
	v_mfma_f32_16x16x32_bf16 v[6:9], v[156:159], v[180:183], v[90:93]
	v_mfma_f32_16x16x32_bf16 v[6:9], v[160:163], v[184:187], v[6:9]
	ds_read_b128 v[156:159], v164 offset:6144
	ds_read_b128 v[160:163], v164 offset:7168
	v_add_f32_e32 v90, v86, v174
	v_add_f32_e32 v91, v87, v174
	v_add_f32_e32 v92, v88, v174
	v_add_f32_e32 v93, v89, v174
	s_waitcnt lgkmcnt(2)
	v_mfma_f32_16x16x32_bf16 v[10:13], v[148:151], v[180:183], v[86:89]
	v_mfma_f32_16x16x32_bf16 v[10:13], v[152:155], v[184:187], v[10:13]
	ds_read_b128 v[148:151], v164 offset:8192
	ds_read_b128 v[152:155], v164 offset:9216
	v_add_f32_e32 v86, v90, v174
	v_add_f32_e32 v87, v91, v174
	v_add_f32_e32 v88, v92, v174
	v_add_f32_e32 v89, v93, v174
	s_waitcnt lgkmcnt(2)
	v_mfma_f32_16x16x32_bf16 v[14:17], v[156:159], v[180:183], v[90:93]
	v_mfma_f32_16x16x32_bf16 v[14:17], v[160:163], v[184:187], v[14:17]
	ds_read_b128 v[156:159], v164 offset:10240
	ds_read_b128 v[160:163], v164 offset:11264
	v_add_f32_e32 v90, v86, v174
	v_add_f32_e32 v91, v87, v174
	v_add_f32_e32 v92, v88, v174
	v_add_f32_e32 v93, v89, v174
	s_waitcnt lgkmcnt(2)
	v_mfma_f32_16x16x32_bf16 v[18:21], v[148:151], v[180:183], v[86:89]
	v_mfma_f32_16x16x32_bf16 v[18:21], v[152:155], v[184:187], v[18:21]
	ds_read_b128 v[148:151], v164 offset:12288
	ds_read_b128 v[152:155], v164 offset:13312
	v_add_f32_e32 v86, v90, v174
	v_add_f32_e32 v87, v91, v174
	v_add_f32_e32 v88, v92, v174
	v_add_f32_e32 v89, v93, v174
	s_waitcnt lgkmcnt(2)
	v_mfma_f32_16x16x32_bf16 v[22:25], v[156:159], v[180:183], v[90:93]
	v_mfma_f32_16x16x32_bf16 v[22:25], v[160:163], v[184:187], v[22:25]
	ds_read_b128 v[156:159], v164 offset:14336
	ds_read_b128 v[160:163], v164 offset:15360
	v_add_f32_e32 v90, v86, v174
	v_add_f32_e32 v91, v87, v174
	v_add_f32_e32 v92, v88, v174
	v_add_f32_e32 v93, v89, v174
	s_waitcnt lgkmcnt(2)
	v_mfma_f32_16x16x32_bf16 v[26:29], v[148:151], v[180:183], v[86:89]
	v_mfma_f32_16x16x32_bf16 v[26:29], v[152:155], v[184:187], v[26:29]
	ds_read_b128 v[148:151], v164 offset:16384
	ds_read_b128 v[152:155], v164 offset:17408
	s_waitcnt lgkmcnt(2)
	v_mfma_f32_16x16x32_bf16 v[30:33], v[156:159], v[180:183], v[90:93]
	v_mfma_f32_16x16x32_bf16 v[30:33], v[160:163], v[184:187], v[30:33]
	ds_read_b128 v[156:159], v164 offset:18432
	ds_read_b128 v[160:163], v164 offset:19456
	v_sub_f32_e64 v86, -v94, v174
	v_sub_f32_e64 v87, -v95, v174
	v_sub_f32_e64 v88, -v96, v174
	v_sub_f32_e64 v89, -v97, v174
	s_waitcnt lgkmcnt(2)
	v_mfma_f32_16x16x32_bf16 v[34:37], v[148:151], v[180:183], v[98:101]
	v_mfma_f32_16x16x32_bf16 v[34:37], v[152:155], v[184:187], v[34:37]
	ds_read_b128 v[148:151], v164 offset:20480
	ds_read_b128 v[152:155], v164 offset:21504
	v_sub_f32_e32 v90, v86, v174
	v_sub_f32_e32 v91, v87, v174
	v_sub_f32_e32 v92, v88, v174
	v_sub_f32_e32 v93, v89, v174
	s_waitcnt lgkmcnt(2)
	v_mfma_f32_16x16x32_bf16 v[38:41], v[156:159], v[180:183], v[86:89]
	v_mfma_f32_16x16x32_bf16 v[38:41], v[160:163], v[184:187], v[38:41]
	ds_read_b128 v[156:159], v164 offset:22528
	ds_read_b128 v[160:163], v164 offset:23552
	v_sub_f32_e32 v86, v90, v174
	v_sub_f32_e32 v87, v91, v174
	v_sub_f32_e32 v88, v92, v174
	v_sub_f32_e32 v89, v93, v174
	s_waitcnt lgkmcnt(2)
	v_mfma_f32_16x16x32_bf16 v[42:45], v[148:151], v[180:183], v[90:93]
	v_mfma_f32_16x16x32_bf16 v[42:45], v[152:155], v[184:187], v[42:45]
	ds_read_b128 v[148:151], v164 offset:24576
	ds_read_b128 v[152:155], v164 offset:25600
	v_sub_f32_e32 v90, v86, v174
	v_sub_f32_e32 v91, v87, v174
	v_sub_f32_e32 v92, v88, v174
	v_sub_f32_e32 v93, v89, v174
	s_waitcnt lgkmcnt(2)
	v_mfma_f32_16x16x32_bf16 v[46:49], v[156:159], v[180:183], v[86:89]
	v_mfma_f32_16x16x32_bf16 v[46:49], v[160:163], v[184:187], v[46:49]
	ds_read_b128 v[156:159], v164 offset:26624
	ds_read_b128 v[160:163], v164 offset:27648
	v_sub_f32_e32 v86, v90, v174
	v_sub_f32_e32 v87, v91, v174
	v_sub_f32_e32 v88, v92, v174
	v_sub_f32_e32 v89, v93, v174
	s_waitcnt lgkmcnt(2)
	v_mfma_f32_16x16x32_bf16 v[50:53], v[148:151], v[180:183], v[90:93]
	v_mfma_f32_16x16x32_bf16 v[50:53], v[152:155], v[184:187], v[50:53]
	ds_read_b128 v[148:151], v164 offset:28672
	ds_read_b128 v[152:155], v164 offset:29696
	v_sub_f32_e32 v90, v86, v174
	v_sub_f32_e32 v91, v87, v174
	v_sub_f32_e32 v92, v88, v174
	v_sub_f32_e32 v93, v89, v174
	s_waitcnt lgkmcnt(2)
	v_mfma_f32_16x16x32_bf16 v[54:57], v[156:159], v[180:183], v[86:89]
	v_mfma_f32_16x16x32_bf16 v[54:57], v[160:163], v[184:187], v[54:57]
	ds_read_b128 v[156:159], v164 offset:30720
	ds_read_b128 v[160:163], v164 offset:31744
	v_sub_f32_e32 v86, v90, v174
	v_sub_f32_e32 v87, v91, v174
	v_sub_f32_e32 v88, v92, v174
	v_sub_f32_e32 v89, v93, v174
	s_waitcnt lgkmcnt(2)
	v_mfma_f32_16x16x32_bf16 v[58:61], v[148:151], v[180:183], v[90:93]
	v_mfma_f32_16x16x32_bf16 v[58:61], v[152:155], v[184:187], v[58:61]
	ds_read_b128 v[148:151], v164 offset:32768
	ds_read_b128 v[152:155], v164 offset:33792
	v_sub_f32_e32 v90, v86, v174
	v_sub_f32_e32 v91, v87, v174
	v_sub_f32_e32 v92, v88, v174
	v_sub_f32_e32 v93, v89, v174
	v_cmp_le_i32_e32 vcc, 0, v108
	s_nop 1
	v_cndmask_b32_e32 v212, v252, v90, vcc
	v_cmp_le_i32_e32 vcc, 0, v110
	s_nop 1
	v_cndmask_b32_e32 v213, v252, v91, vcc
	v_cmp_le_i32_e32 vcc, 0, v111
	s_nop 1
	v_cndmask_b32_e32 v214, v252, v92, vcc
	v_cmp_le_i32_e32 vcc, 0, v177
	s_nop 1
	v_cndmask_b32_e32 v215, v252, v93, vcc
	s_waitcnt lgkmcnt(2)
	v_mfma_f32_16x16x32_bf16 v[62:65], v[156:159], v[180:183], v[86:89]
	v_mfma_f32_16x16x32_bf16 v[62:65], v[160:163], v[184:187], v[62:65]
	s_waitcnt lgkmcnt(0)
	v_mfma_f32_16x16x32_bf16 v[66:69], v[148:151], v[180:183], v[212:215]
	v_mfma_f32_16x16x32_bf16 v[66:69], v[152:155], v[184:187], v[66:69]
	s_waitcnt lgkmcnt(7)
; __device__ void att_phase(int wv, const Params& p, unsigned char* lds) {
;     ...
;             float mx = sink;
; #pragma unroll
;             for (int cb = 0; cb < 24; ++cb) { const int kb = B - 1 + (cb >> 3); const bool bval = (kb >= sb && kb < se);
; #pragma unroll
;                 for (int j = 0; j < 4; ++j) { const int krel = 16 * cb + 4 * lq + j - 128;
;                     int dist = qrow - krel; dist = dist < 0 ? -dist : dist;
;                     const float v = (bval && dist <= 128) ? sc[cb][j] * 0.125f - slope * (float)dist : -1e30f;
;                     sc[cb][j] = v; mx = fmaxf(mx, v); } }
;             mx = fmaxf(mx, __shfl_xor(mx, 16)); mx = fmaxf(mx, __shfl_xor(mx, 32));
;             float sum = 0.f;
; #pragma unroll
;             for (int cb = 0; cb < 24; ++cb)
; #pragma unroll
;                 for (int j = 0; j < 4; ++j) { const float e = __expf(sc[cb][j] - mx); sc[cb][j] = e; sum += e; }
;             sum += __shfl_xor(sum, 16); sum += __shfl_xor(sum, 32);
	ds_read_b64_tr_b16 v[216:217], v165
	ds_read_b64_tr_b16 v[218:219], v165 offset:2560
	ds_read_b64_tr_b16 v[220:221], v165 offset:32
	ds_read_b64_tr_b16 v[222:223], v165 offset:2592
	ds_read_b64_tr_b16 v[224:225], v165 offset:64
	ds_read_b64_tr_b16 v[226:227], v165 offset:2624
	ds_read_b64_tr_b16 v[228:229], v165 offset:96
	ds_read_b64_tr_b16 v[230:231], v165 offset:2656
	v_max3_f32 v169, v2, v3, v4
	v_max3_f32 v172, v5, v6, v7
	v_max3_f32 v169, v8, v9, v169
	v_max3_f32 v172, v10, v11, v172
	v_max3_f32 v169, v12, v13, v169
	v_max3_f32 v172, v14, v15, v172
	v_max3_f32 v169, v16, v17, v169
	v_max3_f32 v172, v18, v19, v172
	v_max3_f32 v169, v20, v21, v169
	v_max3_f32 v172, v22, v23, v172
	v_max3_f32 v169, v24, v25, v169
	v_max3_f32 v172, v26, v27, v172
	v_max3_f32 v169, v28, v29, v169
	v_max3_f32 v172, v30, v31, v172
	v_max3_f32 v169, v32, v33, v169
	v_max3_f32 v172, v34, v35, v172
	v_max3_f32 v169, v36, v37, v169
	v_max3_f32 v172, v38, v39, v172
	v_max3_f32 v169, v40, v41, v169
	v_max3_f32 v172, v42, v43, v172
	v_max3_f32 v169, v44, v45, v169
	v_max3_f32 v172, v46, v47, v172
	v_max3_f32 v169, v48, v49, v169
	v_max3_f32 v172, v50, v51, v172
	v_max3_f32 v169, v52, v53, v169
	v_max3_f32 v172, v54, v55, v172
	v_max3_f32 v169, v56, v57, v169
	v_max3_f32 v172, v58, v59, v172
	v_max3_f32 v169, v60, v61, v169
	v_max3_f32 v172, v62, v63, v172
	v_max3_f32 v169, v64, v65, v169
	v_max3_f32 v172, v66, v67, v172
	v_max3_f32 v169, v68, v69, v169
	v_max_f32_e32 v169, v169, v172
	v_mul_f32_e32 v169, 0x3e000000, v169
	s_waitcnt vmcnt(0)
	v_max_f32_e32 v169, v169, v146
	ds_bpermute_b32 v172, v1, v169
	s_waitcnt lgkmcnt(0)
	v_max_f32_e32 v169, v169, v172
	ds_bpermute_b32 v172, v114, v169
	s_waitcnt lgkmcnt(0)
	v_max_f32_e32 v169, v169, v172
	v_mul_f32_e32 v175, 0xbfb8aa3b, v169
	v_mov_b32_e32 v170, 0
	v_mov_b32_e32 v171, 0
	v_fma_f32 v2, v2, s46, v175
	v_fma_f32 v3, v3, s46, v175
	v_fma_f32 v4, v4, s46, v175
	v_fma_f32 v5, v5, s46, v175
	v_exp_f32_e32 v2, v2
	v_exp_f32_e32 v3, v3
	v_exp_f32_e32 v4, v4
	v_exp_f32_e32 v5, v5
	v_fma_f32 v6, v6, s46, v175
	v_fma_f32 v7, v7, s46, v175
	v_fma_f32 v8, v8, s46, v175
	v_fma_f32 v9, v9, s46, v175
	v_exp_f32_e32 v6, v6
	v_exp_f32_e32 v7, v7
	v_exp_f32_e32 v8, v8
	v_exp_f32_e32 v9, v9
	v_add_f32_e32 v171, v171, v2
	v_add_f32_e32 v170, v170, v3
	v_add_f32_e32 v171, v171, v4
	v_add_f32_e32 v170, v170, v5
	v_fma_f32 v10, v10, s46, v175
	v_fma_f32 v11, v11, s46, v175
	v_fma_f32 v12, v12, s46, v175
	v_fma_f32 v13, v13, s46, v175
	v_exp_f32_e32 v10, v10
	v_exp_f32_e32 v11, v11
	v_exp_f32_e32 v12, v12
	v_exp_f32_e32 v13, v13
	v_add_f32_e32 v171, v171, v6
	v_add_f32_e32 v170, v170, v7
	v_add_f32_e32 v171, v171, v8
	v_add_f32_e32 v170, v170, v9
	v_fma_f32 v14, v14, s46, v175
	v_fma_f32 v15, v15, s46, v175
	v_fma_f32 v16, v16, s46, v175
	v_fma_f32 v17, v17, s46, v175
	v_exp_f32_e32 v14, v14
	v_exp_f32_e32 v15, v15
	v_exp_f32_e32 v16, v16
	v_exp_f32_e32 v17, v17
	v_add_f32_e32 v171, v171, v10
	v_add_f32_e32 v170, v170, v11
	v_add_f32_e32 v171, v171, v12
	v_add_f32_e32 v170, v170, v13
	v_fma_f32 v18, v18, s46, v175
	v_fma_f32 v19, v19, s46, v175
	v_fma_f32 v20, v20, s46, v175
	v_fma_f32 v21, v21, s46, v175
	v_exp_f32_e32 v18, v18
	v_exp_f32_e32 v19, v19
	v_exp_f32_e32 v20, v20
	v_exp_f32_e32 v21, v21
	v_add_f32_e32 v171, v171, v14
	v_add_f32_e32 v170, v170, v15
	v_add_f32_e32 v171, v171, v16
	v_add_f32_e32 v170, v170, v17
	v_fma_f32 v22, v22, s46, v175
	v_fma_f32 v23, v23, s46, v175
	v_fma_f32 v24, v24, s46, v175
	v_fma_f32 v25, v25, s46, v175
	v_exp_f32_e32 v22, v22
	v_exp_f32_e32 v23, v23
	v_exp_f32_e32 v24, v24
	v_exp_f32_e32 v25, v25
	v_add_f32_e32 v171, v171, v18
	v_add_f32_e32 v170, v170, v19
	v_add_f32_e32 v171, v171, v20
	v_add_f32_e32 v170, v170, v21
	v_fma_f32 v26, v26, s46, v175
	v_fma_f32 v27, v27, s46, v175
	v_fma_f32 v28, v28, s46, v175
	v_fma_f32 v29, v29, s46, v175
	v_exp_f32_e32 v26, v26
	v_exp_f32_e32 v27, v27
	v_exp_f32_e32 v28, v28
	v_exp_f32_e32 v29, v29
	v_add_f32_e32 v171, v171, v22
	v_add_f32_e32 v170, v170, v23
	v_add_f32_e32 v171, v171, v24
	v_add_f32_e32 v170, v170, v25
	v_fma_f32 v30, v30, s46, v175
	v_fma_f32 v31, v31, s46, v175
	v_fma_f32 v32, v32, s46, v175
	v_fma_f32 v33, v33, s46, v175
	v_exp_f32_e32 v30, v30
	v_exp_f32_e32 v31, v31
	v_exp_f32_e32 v32, v32
	v_exp_f32_e32 v33, v33
	v_add_f32_e32 v171, v171, v26
	v_add_f32_e32 v170, v170, v27
	v_add_f32_e32 v171, v171, v28
	v_add_f32_e32 v170, v170, v29
	v_fma_f32 v34, v34, s46, v175
	v_fma_f32 v35, v35, s46, v175
	v_fma_f32 v36, v36, s46, v175
	v_fma_f32 v37, v37, s46, v175
	v_exp_f32_e32 v34, v34
	v_exp_f32_e32 v35, v35
	v_exp_f32_e32 v36, v36
	v_exp_f32_e32 v37, v37
	v_add_f32_e32 v171, v171, v30
	v_add_f32_e32 v170, v170, v31
	v_add_f32_e32 v171, v171, v32
	v_add_f32_e32 v170, v170, v33
	v_fma_f32 v38, v38, s46, v175
	v_fma_f32 v39, v39, s46, v175
	v_fma_f32 v40, v40, s46, v175
	v_fma_f32 v41, v41, s46, v175
	v_exp_f32_e32 v38, v38
	v_exp_f32_e32 v39, v39
	v_exp_f32_e32 v40, v40
	v_exp_f32_e32 v41, v41
	v_add_f32_e32 v171, v171, v34
	v_add_f32_e32 v170, v170, v35
	v_add_f32_e32 v171, v171, v36
	v_add_f32_e32 v170, v170, v37
	v_fma_f32 v42, v42, s46, v175
	v_fma_f32 v43, v43, s46, v175
	v_fma_f32 v44, v44, s46, v175
	v_fma_f32 v45, v45, s46, v175
	v_exp_f32_e32 v42, v42
	v_exp_f32_e32 v43, v43
	v_exp_f32_e32 v44, v44
	v_exp_f32_e32 v45, v45
	v_add_f32_e32 v171, v171, v38
	v_add_f32_e32 v170, v170, v39
	v_add_f32_e32 v171, v171, v40
	v_add_f32_e32 v170, v170, v41
	v_fma_f32 v46, v46, s46, v175
	v_fma_f32 v47, v47, s46, v175
	v_fma_f32 v48, v48, s46, v175
	v_fma_f32 v49, v49, s46, v175
	v_exp_f32_e32 v46, v46
	v_exp_f32_e32 v47, v47
	v_exp_f32_e32 v48, v48
; __device__ __forceinline__ unsigned cvt_pk_bf16_asm(float lo, float hi) { unsigned r; asm volatile("v_cvt_pk_bf16_f32 %0, %1, %2" : "=v"(r) : "v"(lo), "v"(hi)); return r; }
; __device__ __forceinline__ f32x4 mfma16(bf16x8 a, bf16x8 b, f32x4 c) { return __builtin_amdgcn_mfma_f32_16x16x32_bf16(a, b, c, 0, 0, 0); }
; __device__ void att_phase(int wv, const Params& p, unsigned char* lds) {
;     ...
;             for (int cb = 0; cb < 24; ++cb)
; #pragma unroll
;                 for (int j = 0; j < 4; ++j) { const float e = __expf(sc[cb][j] - mx); sc[cb][j] = e; sum += e; }
;             sum += __shfl_xor(sum, 16); sum += __shfl_xor(sum, 32);
;             sum += __expf(sink - mx);
;             const float inv = 1.0f / sum;
;             f32x4 oa[4];
; #pragma unroll
;             for (int db = 0; db < 4; ++db) oa[db] = (f32x4){0, 0, 0, 0};
; #pragma unroll
;             for (int ks = 0; ks < 12; ++ks) {
;                 union { bf16x8 v; unsigned u[4]; } pf;
;                 pf.u[0] = cvt_pk_bf16_asm(sc[2 * ks][0], sc[2 * ks][1]); pf.u[1] = cvt_pk_bf16_asm(sc[2 * ks][2], sc[2 * ks][3]);
;                 pf.u[2] = cvt_pk_bf16_asm(sc[2 * ks + 1][0], sc[2 * ks + 1][1]); pf.u[3] = cvt_pk_bf16_asm(sc[2 * ks + 1][2], sc[2 * ks + 1][3]);
; #pragma unroll
;                 for (int db = 0; db < 4; ++db) {
;                     union { bf16x8 v; u32x2 h2[2]; } vf;
;                     const bf16_t* vp = VTL + (16 * db + lr) * VP + 32 * ks + 4 * lq;
;                     vf.h2[0] = *(const u32x2*)vp; vf.h2[1] = *(const u32x2*)(vp + 16);
;                     oa[db] = mfma16(vf.v, pf.v, oa[db]); } }
	v_exp_f32_e32 v49, v49
	v_add_f32_e32 v171, v171, v42
	v_add_f32_e32 v170, v170, v43
	v_add_f32_e32 v171, v171, v44
	v_add_f32_e32 v170, v170, v45
	v_fma_f32 v50, v50, s46, v175
	v_fma_f32 v51, v51, s46, v175
	v_fma_f32 v52, v52, s46, v175
	v_fma_f32 v53, v53, s46, v175
	v_exp_f32_e32 v50, v50
	v_exp_f32_e32 v51, v51
	v_exp_f32_e32 v52, v52
	v_exp_f32_e32 v53, v53
	v_add_f32_e32 v171, v171, v46
	v_add_f32_e32 v170, v170, v47
	v_add_f32_e32 v171, v171, v48
	v_add_f32_e32 v170, v170, v49
	v_fma_f32 v54, v54, s46, v175
	v_fma_f32 v55, v55, s46, v175
	v_fma_f32 v56, v56, s46, v175
	v_fma_f32 v57, v57, s46, v175
	v_exp_f32_e32 v54, v54
	v_exp_f32_e32 v55, v55
	v_exp_f32_e32 v56, v56
	v_exp_f32_e32 v57, v57
	v_add_f32_e32 v171, v171, v50
	v_add_f32_e32 v170, v170, v51
	v_add_f32_e32 v171, v171, v52
	v_add_f32_e32 v170, v170, v53
	v_fma_f32 v58, v58, s46, v175
	v_fma_f32 v59, v59, s46, v175
	v_fma_f32 v60, v60, s46, v175
	v_fma_f32 v61, v61, s46, v175
	v_exp_f32_e32 v58, v58
	v_exp_f32_e32 v59, v59
	v_exp_f32_e32 v60, v60
	v_exp_f32_e32 v61, v61
	v_add_f32_e32 v171, v171, v54
	v_add_f32_e32 v170, v170, v55
	v_add_f32_e32 v171, v171, v56
	v_add_f32_e32 v170, v170, v57
	v_fma_f32 v62, v62, s46, v175
	v_fma_f32 v63, v63, s46, v175
	v_fma_f32 v64, v64, s46, v175
	v_fma_f32 v65, v65, s46, v175
	v_exp_f32_e32 v62, v62
	v_exp_f32_e32 v63, v63
	v_exp_f32_e32 v64, v64
	v_exp_f32_e32 v65, v65
	v_add_f32_e32 v171, v171, v58
	v_add_f32_e32 v170, v170, v59
	v_add_f32_e32 v171, v171, v60
	v_add_f32_e32 v170, v170, v61
	v_fma_f32 v66, v66, s46, v175
	v_fma_f32 v67, v67, s46, v175
	v_fma_f32 v68, v68, s46, v175
	v_fma_f32 v69, v69, s46, v175
	v_exp_f32_e32 v66, v66
	v_exp_f32_e32 v67, v67
	v_exp_f32_e32 v68, v68
	v_exp_f32_e32 v69, v69
	v_add_f32_e32 v171, v171, v62
	v_add_f32_e32 v170, v170, v63
	v_add_f32_e32 v171, v171, v64
	v_add_f32_e32 v170, v170, v65
	v_add_f32_e32 v171, v171, v66
	v_add_f32_e32 v170, v170, v67
	v_add_f32_e32 v171, v171, v68
	v_add_f32_e32 v170, v170, v69
	v_add_f32_e32 v170, v170, v171
	v_cvt_pk_bf16_f32 v2, v2, v3
	v_cvt_pk_bf16_f32 v3, v4, v5
	v_cvt_pk_bf16_f32 v4, v6, v7
	v_cvt_pk_bf16_f32 v5, v8, v9
	v_cvt_pk_bf16_f32 v10, v10, v11
	v_cvt_pk_bf16_f32 v11, v12, v13
	v_cvt_pk_bf16_f32 v12, v14, v15
	v_cvt_pk_bf16_f32 v13, v16, v17
	v_cvt_pk_bf16_f32 v18, v18, v19
	v_cvt_pk_bf16_f32 v19, v20, v21
	v_cvt_pk_bf16_f32 v20, v22, v23
	v_cvt_pk_bf16_f32 v21, v24, v25
	v_cvt_pk_bf16_f32 v26, v26, v27
	v_cvt_pk_bf16_f32 v27, v28, v29
	v_cvt_pk_bf16_f32 v28, v30, v31
	v_cvt_pk_bf16_f32 v29, v32, v33
	v_cvt_pk_bf16_f32 v34, v34, v35
	v_cvt_pk_bf16_f32 v35, v36, v37
	v_cvt_pk_bf16_f32 v36, v38, v39
	v_cvt_pk_bf16_f32 v37, v40, v41
	v_cvt_pk_bf16_f32 v42, v42, v43
	v_cvt_pk_bf16_f32 v43, v44, v45
	v_cvt_pk_bf16_f32 v44, v46, v47
	v_cvt_pk_bf16_f32 v45, v48, v49
	v_cvt_pk_bf16_f32 v50, v50, v51
	v_cvt_pk_bf16_f32 v51, v52, v53
	v_cvt_pk_bf16_f32 v52, v54, v55
	v_cvt_pk_bf16_f32 v53, v56, v57
	v_cvt_pk_bf16_f32 v58, v58, v59
	v_cvt_pk_bf16_f32 v59, v60, v61
	v_cvt_pk_bf16_f32 v60, v62, v63
	v_cvt_pk_bf16_f32 v61, v64, v65
	v_cvt_pk_bf16_f32 v66, v66, v67
	v_cvt_pk_bf16_f32 v67, v68, v69
	v_mov_b32_e32 v68, 0
	v_mov_b32_e32 v69, 0
	ds_bpermute_b32 v172, v1, v170
	v_sub_f32_e32 v173, v146, v169
	v_mul_f32_e32 v173, 0x3fb8aa3b, v173
	v_exp_f32_e32 v173, v173
	s_waitcnt lgkmcnt(0)
	v_add_f32_e32 v170, v170, v172
	ds_bpermute_b32 v172, v114, v170
	s_waitcnt lgkmcnt(7)
	ds_read_b64_tr_b16 v[232:233], v165 offset:5120
	ds_read_b64_tr_b16 v[234:235], v165 offset:7680
	ds_read_b64_tr_b16 v[236:237], v165 offset:5152
	ds_read_b64_tr_b16 v[238:239], v165 offset:7712
	ds_read_b64_tr_b16 v[240:241], v165 offset:5184
	ds_read_b64_tr_b16 v[242:243], v165 offset:7744
	ds_read_b64_tr_b16 v[244:245], v165 offset:5216
	ds_read_b64_tr_b16 v[246:247], v165 offset:7776
	s_waitcnt lgkmcnt(8)
	v_mfma_f32_16x16x32_bf16 v[70:73], v[216:219], v[2:5], 0
	v_mfma_f32_16x16x32_bf16 v[74:77], v[220:223], v[2:5], 0
	v_mfma_f32_16x16x32_bf16 v[78:81], v[224:227], v[2:5], 0
	v_mfma_f32_16x16x32_bf16 v[82:85], v[228:231], v[2:5], 0
	v_add_f32_e32 v170, v170, v172
	v_add_f32_e32 v170, v170, v173
	v_rcp_f32_e32 v147, v170
	s_nop 0
	v_fma_f32 v179, -v170, v147, 1.0
	v_fmac_f32_e32 v147, v179, v147
	s_waitcnt lgkmcnt(7)
	ds_read_b64_tr_b16 v[216:217], v165 offset:10240
	ds_read_b64_tr_b16 v[218:219], v165 offset:12800
	ds_read_b64_tr_b16 v[220:221], v165 offset:10272
	ds_read_b64_tr_b16 v[222:223], v165 offset:12832
	ds_read_b64_tr_b16 v[224:225], v165 offset:10304
	ds_read_b64_tr_b16 v[226:227], v165 offset:12864
	ds_read_b64_tr_b16 v[228:229], v165 offset:10336
	ds_read_b64_tr_b16 v[230:231], v165 offset:12896
	s_waitcnt lgkmcnt(8)
	v_mfma_f32_16x16x32_bf16 v[70:73], v[232:235], v[10:13], v[70:73]
	v_mfma_f32_16x16x32_bf16 v[74:77], v[236:239], v[10:13], v[74:77]
	v_mfma_f32_16x16x32_bf16 v[78:81], v[240:243], v[10:13], v[78:81]
	v_mfma_f32_16x16x32_bf16 v[82:85], v[244:247], v[10:13], v[82:85]
	s_waitcnt lgkmcnt(7)
	ds_read_b64_tr_b16 v[232:233], v165 offset:15360
	ds_read_b64_tr_b16 v[234:235], v165 offset:17920
	ds_read_b64_tr_b16 v[236:237], v165 offset:15392
	ds_read_b64_tr_b16 v[238:239], v165 offset:17952
	ds_read_b64_tr_b16 v[240:241], v165 offset:15424
	ds_read_b64_tr_b16 v[242:243], v165 offset:17984
	ds_read_b64_tr_b16 v[244:245], v165 offset:15456
	ds_read_b64_tr_b16 v[246:247], v165 offset:18016
	s_waitcnt lgkmcnt(8)
	v_mfma_f32_16x16x32_bf16 v[70:73], v[216:219], v[18:21], v[70:73]
	v_mfma_f32_16x16x32_bf16 v[74:77], v[220:223], v[18:21], v[74:77]
	v_mfma_f32_16x16x32_bf16 v[78:81], v[224:227], v[18:21], v[78:81]
	v_mfma_f32_16x16x32_bf16 v[82:85], v[228:231], v[18:21], v[82:85]
	s_waitcnt lgkmcnt(7)
; __device__ __forceinline__ unsigned cvt_pk_bf16_asm(float lo, float hi) { unsigned r; asm volatile("v_cvt_pk_bf16_f32 %0, %1, %2" : "=v"(r) : "v"(lo), "v"(hi)); return r; }
; __device__ __forceinline__ f32x4 mfma16(bf16x8 a, bf16x8 b, f32x4 c) { return __builtin_amdgcn_mfma_f32_16x16x32_bf16(a, b, c, 0, 0, 0); }
; __device__ void att_phase(int wv, const Params& p, unsigned char* lds) {
;     ...
;             for (int cb = 0; cb < 24; ++cb) { f32x4 a = {0, 0, 0, 0};
; #pragma unroll
;                 for (int kk = 0; kk < 2; ++kk) { const bf16x8 kf = *(const bf16x8*)(KL + (16 * cb + lr) * KP + 32 * kk + 8 * lq); a = mfma16(kf, qf[kk], a); }
;                 sc[cb] = a; }
;     ...
;             for (int ks = 0; ks < 12; ++ks) {
;                 union { bf16x8 v; unsigned u[4]; } pf;
;                 pf.u[0] = cvt_pk_bf16_asm(sc[2 * ks][0], sc[2 * ks][1]); pf.u[1] = cvt_pk_bf16_asm(sc[2 * ks][2], sc[2 * ks][3]);
;                 pf.u[2] = cvt_pk_bf16_asm(sc[2 * ks + 1][0], sc[2 * ks + 1][1]); pf.u[3] = cvt_pk_bf16_asm(sc[2 * ks + 1][2], sc[2 * ks + 1][3]);
; #pragma unroll
;                 for (int db = 0; db < 4; ++db) {
;                     union { bf16x8 v; u32x2 h2[2]; } vf;
;                     const bf16_t* vp = VTL + (16 * db + lr) * VP + 32 * ks + 4 * lq;
;                     vf.h2[0] = *(const u32x2*)vp; vf.h2[1] = *(const u32x2*)(vp + 16);
;                     oa[db] = mfma16(vf.v, pf.v, oa[db]); } }
; #pragma unroll
;             for (int db = 0; db < 4; ++db) { const f32x4 o = oa[db] * inv; u32x2 wv; wv.x = cvt_pk_bf16_asm(o[0], o[1]); wv.y = cvt_pk_bf16_asm(o[2], o[3]);
;                 *(u32x2*)(qkv + tokq * 1536 + 64 * h + 16 * db + 4 * lq) = wv; }
	ds_read_b64_tr_b16 v[216:217], v165 offset:20480
	ds_read_b64_tr_b16 v[218:219], v165 offset:23040
	ds_read_b64_tr_b16 v[220:221], v165 offset:20512
	ds_read_b64_tr_b16 v[222:223], v165 offset:23072
	ds_read_b64_tr_b16 v[224:225], v165 offset:20544
	ds_read_b64_tr_b16 v[226:227], v165 offset:23104
	ds_read_b64_tr_b16 v[228:229], v165 offset:20576
	ds_read_b64_tr_b16 v[230:231], v165 offset:23136
	s_waitcnt lgkmcnt(8)
	v_mfma_f32_16x16x32_bf16 v[70:73], v[232:235], v[26:29], v[70:73]
	v_mfma_f32_16x16x32_bf16 v[74:77], v[236:239], v[26:29], v[74:77]
	v_mfma_f32_16x16x32_bf16 v[78:81], v[240:243], v[26:29], v[78:81]
	v_mfma_f32_16x16x32_bf16 v[82:85], v[244:247], v[26:29], v[82:85]
	s_waitcnt lgkmcnt(7)
	ds_read_b64_tr_b16 v[232:233], v165 offset:25600
	ds_read_b64_tr_b16 v[234:235], v165 offset:28160
	ds_read_b64_tr_b16 v[236:237], v165 offset:25632
	ds_read_b64_tr_b16 v[238:239], v165 offset:28192
	ds_read_b64_tr_b16 v[240:241], v165 offset:25664
	ds_read_b64_tr_b16 v[242:243], v165 offset:28224
	ds_read_b64_tr_b16 v[244:245], v165 offset:25696
	ds_read_b64_tr_b16 v[246:247], v165 offset:28256
	s_waitcnt lgkmcnt(8)
	v_mfma_f32_16x16x32_bf16 v[70:73], v[216:219], v[34:37], v[70:73]
	v_mfma_f32_16x16x32_bf16 v[74:77], v[220:223], v[34:37], v[74:77]
	v_mfma_f32_16x16x32_bf16 v[78:81], v[224:227], v[34:37], v[78:81]
	v_mfma_f32_16x16x32_bf16 v[82:85], v[228:231], v[34:37], v[82:85]
	s_waitcnt lgkmcnt(7)
	ds_read_b64_tr_b16 v[216:217], v165 offset:30720
	ds_read_b64_tr_b16 v[218:219], v165 offset:33280
	ds_read_b64_tr_b16 v[220:221], v165 offset:30752
	ds_read_b64_tr_b16 v[222:223], v165 offset:33312
	ds_read_b64_tr_b16 v[224:225], v165 offset:30784
	ds_read_b64_tr_b16 v[226:227], v165 offset:33344
	ds_read_b64_tr_b16 v[228:229], v165 offset:30816
	ds_read_b64_tr_b16 v[230:231], v165 offset:33376
	s_waitcnt lgkmcnt(8)
	v_mfma_f32_16x16x32_bf16 v[70:73], v[232:235], v[42:45], v[70:73]
	v_mfma_f32_16x16x32_bf16 v[74:77], v[236:239], v[42:45], v[74:77]
	v_mfma_f32_16x16x32_bf16 v[78:81], v[240:243], v[42:45], v[78:81]
	v_mfma_f32_16x16x32_bf16 v[82:85], v[244:247], v[42:45], v[82:85]
	s_waitcnt lgkmcnt(7)
	ds_read_b64_tr_b16 v[232:233], v165 offset:35840
	ds_read_b64_tr_b16 v[234:235], v165 offset:38400
	ds_read_b64_tr_b16 v[236:237], v165 offset:35872
	ds_read_b64_tr_b16 v[238:239], v165 offset:38432
	ds_read_b64_tr_b16 v[240:241], v165 offset:35904
	ds_read_b64_tr_b16 v[242:243], v165 offset:38464
	ds_read_b64_tr_b16 v[244:245], v165 offset:35936
	ds_read_b64_tr_b16 v[246:247], v165 offset:38496
	s_waitcnt lgkmcnt(8)
	v_mfma_f32_16x16x32_bf16 v[70:73], v[216:219], v[50:53], v[70:73]
	v_mfma_f32_16x16x32_bf16 v[74:77], v[220:223], v[50:53], v[74:77]
	v_mfma_f32_16x16x32_bf16 v[78:81], v[224:227], v[50:53], v[78:81]
	v_mfma_f32_16x16x32_bf16 v[82:85], v[228:231], v[50:53], v[82:85]
	s_waitcnt lgkmcnt(7)
	ds_read_b64_tr_b16 v[216:217], v165 offset:40960
	ds_read_b64_tr_b16 v[218:219], v165 offset:40960
	ds_read_b64_tr_b16 v[220:221], v165 offset:40992
	ds_read_b64_tr_b16 v[222:223], v165 offset:40992
	ds_read_b64_tr_b16 v[224:225], v165 offset:41024
	ds_read_b64_tr_b16 v[226:227], v165 offset:41024
	ds_read_b64_tr_b16 v[228:229], v165 offset:41056
	ds_read_b64_tr_b16 v[230:231], v165 offset:41056
	s_waitcnt lgkmcnt(8)
	v_mfma_f32_16x16x32_bf16 v[70:73], v[232:235], v[58:61], v[70:73]
	v_mfma_f32_16x16x32_bf16 v[74:77], v[236:239], v[58:61], v[74:77]
	v_mfma_f32_16x16x32_bf16 v[78:81], v[240:243], v[58:61], v[78:81]
	v_mfma_f32_16x16x32_bf16 v[82:85], v[244:247], v[58:61], v[82:85]
	s_waitcnt lgkmcnt(0)
	v_mfma_f32_16x16x32_bf16 v[70:73], v[216:219], v[66:69], v[70:73]
	v_mfma_f32_16x16x32_bf16 v[74:77], v[220:223], v[66:69], v[74:77]
	v_mfma_f32_16x16x32_bf16 v[78:81], v[224:227], v[66:69], v[78:81]
	v_mfma_f32_16x16x32_bf16 v[82:85], v[228:231], v[66:69], v[82:85]
	s_nop 7
	s_nop 1
	v_mul_f32_e32 v70, v70, v147
	v_mul_f32_e32 v71, v71, v147
	v_mul_f32_e32 v72, v72, v147
	v_mul_f32_e32 v73, v73, v147
	v_mul_f32_e32 v74, v74, v147
	v_mul_f32_e32 v75, v75, v147
	v_mul_f32_e32 v76, v76, v147
	v_mul_f32_e32 v77, v77, v147
	v_mul_f32_e32 v78, v78, v147
	v_mul_f32_e32 v79, v79, v147
	v_mul_f32_e32 v80, v80, v147
	v_mul_f32_e32 v81, v81, v147
	v_mul_f32_e32 v82, v82, v147
	v_mul_f32_e32 v83, v83, v147
	v_mul_f32_e32 v84, v84, v147
	v_mul_f32_e32 v85, v85, v147
	v_cvt_pk_bf16_f32 v70, v70, v71
	v_cvt_pk_bf16_f32 v71, v72, v73
	v_cvt_pk_bf16_f32 v74, v74, v75
	v_cvt_pk_bf16_f32 v75, v76, v77
	v_cvt_pk_bf16_f32 v78, v78, v79
	v_cvt_pk_bf16_f32 v79, v80, v81
	v_cvt_pk_bf16_f32 v82, v82, v83
	v_cvt_pk_bf16_f32 v83, v84, v85
	global_store_dwordx2 v[248:249], v[70:71], off offset:-64
	global_store_dwordx2 v[248:249], v[74:75], off offset:-32
	global_store_dwordx2 v[248:249], v[78:79], off
	global_store_dwordx2 v[248:249], v[82:83], off offset:32
	v_lshl_add_u64 v[248:249], v[248:249], 0, s[48:49]
	v_sub_f32_e32 v86, v94, v176
	v_sub_f32_e32 v87, v95, v176
	v_sub_f32_e32 v88, v96, v176
	v_sub_f32_e32 v89, v97, v176
	v_cmp_ge_i32_e32 vcc, 0, v108
	s_nop 1
	v_cndmask_b32_e32 v212, v252, v86, vcc
	v_cmp_ge_i32_e32 vcc, 0, v110
	s_nop 1
	v_cndmask_b32_e32 v213, v252, v87, vcc
	v_cmp_ge_i32_e32 vcc, 0, v111
	s_nop 1
	v_cndmask_b32_e32 v214, v252, v88, vcc
	v_cmp_ge_i32_e32 vcc, 0, v177
	s_nop 1
	v_cndmask_b32_e32 v215, v252, v89, vcc
	ds_read_b128 v[148:151], v164 offset:2048
	ds_read_b128 v[152:155], v164 offset:3072
	ds_read_b128 v[156:159], v164 offset:4096
	ds_read_b128 v[160:163], v164 offset:5120
	v_add_f32_e32 v90, v86, v174
	v_add_f32_e32 v91, v87, v174
	v_add_f32_e32 v92, v88, v174
	v_add_f32_e32 v93, v89, v174
	s_waitcnt lgkmcnt(2)
; __device__ __forceinline__ f32x4 mfma16(bf16x8 a, bf16x8 b, f32x4 c) { return __builtin_amdgcn_mfma_f32_16x16x32_bf16(a, b, c, 0, 0, 0); }
; __device__ void att_phase(int wv, const Params& p, unsigned char* lds) {
;     ...
;             for (int cb = 0; cb < 24; ++cb) { f32x4 a = {0, 0, 0, 0};
; #pragma unroll
;                 for (int kk = 0; kk < 2; ++kk) { const bf16x8 kf = *(const bf16x8*)(KL + (16 * cb + lr) * KP + 32 * kk + 8 * lq); a = mfma16(kf, qf[kk], a); }
;                 sc[cb] = a; }
	v_mfma_f32_16x16x32_bf16 v[2:5], v[148:151], v[188:191], v[212:215]
	v_mfma_f32_16x16x32_bf16 v[2:5], v[152:155], v[192:195], v[2:5]
	ds_read_b128 v[148:151], v164 offset:6144
	ds_read_b128 v[152:155], v164 offset:7168
	v_add_f32_e32 v86, v90, v174
	v_add_f32_e32 v87, v91, v174
	v_add_f32_e32 v88, v92, v174
	v_add_f32_e32 v89, v93, v174
	s_waitcnt lgkmcnt(2)
	v_mfma_f32_16x16x32_bf16 v[6:9], v[156:159], v[188:191], v[90:93]
	v_mfma_f32_16x16x32_bf16 v[6:9], v[160:163], v[192:195], v[6:9]
	ds_read_b128 v[156:159], v164 offset:8192
	ds_read_b128 v[160:163], v164 offset:9216
	v_add_f32_e32 v90, v86, v174
	v_add_f32_e32 v91, v87, v174
	v_add_f32_e32 v92, v88, v174
	v_add_f32_e32 v93, v89, v174
	s_waitcnt lgkmcnt(2)
	v_mfma_f32_16x16x32_bf16 v[10:13], v[148:151], v[188:191], v[86:89]
	v_mfma_f32_16x16x32_bf16 v[10:13], v[152:155], v[192:195], v[10:13]
	ds_read_b128 v[148:151], v164 offset:10240
	ds_read_b128 v[152:155], v164 offset:11264
	v_add_f32_e32 v86, v90, v174
	v_add_f32_e32 v87, v91, v174
	v_add_f32_e32 v88, v92, v174
	v_add_f32_e32 v89, v93, v174
	s_waitcnt lgkmcnt(2)
	v_mfma_f32_16x16x32_bf16 v[14:17], v[156:159], v[188:191], v[90:93]
	v_mfma_f32_16x16x32_bf16 v[14:17], v[160:163], v[192:195], v[14:17]
	ds_read_b128 v[156:159], v164 offset:12288
	ds_read_b128 v[160:163], v164 offset:13312
	v_add_f32_e32 v90, v86, v174
	v_add_f32_e32 v91, v87, v174
	v_add_f32_e32 v92, v88, v174
	v_add_f32_e32 v93, v89, v174
	s_waitcnt lgkmcnt(2)
	v_mfma_f32_16x16x32_bf16 v[18:21], v[148:151], v[188:191], v[86:89]
	v_mfma_f32_16x16x32_bf16 v[18:21], v[152:155], v[192:195], v[18:21]
	ds_read_b128 v[148:151], v164 offset:14336
	ds_read_b128 v[152:155], v164 offset:15360
	v_add_f32_e32 v86, v90, v174
	v_add_f32_e32 v87, v91, v174
	v_add_f32_e32 v88, v92, v174
	v_add_f32_e32 v89, v93, v174
	s_waitcnt lgkmcnt(2)
	v_mfma_f32_16x16x32_bf16 v[22:25], v[156:159], v[188:191], v[90:93]
	v_mfma_f32_16x16x32_bf16 v[22:25], v[160:163], v[192:195], v[22:25]
	ds_read_b128 v[156:159], v164 offset:16384
	ds_read_b128 v[160:163], v164 offset:17408
	v_add_f32_e32 v90, v86, v174
	v_add_f32_e32 v91, v87, v174
	v_add_f32_e32 v92, v88, v174
	v_add_f32_e32 v93, v89, v174
	s_waitcnt lgkmcnt(2)
	v_mfma_f32_16x16x32_bf16 v[26:29], v[148:151], v[188:191], v[86:89]
	v_mfma_f32_16x16x32_bf16 v[26:29], v[152:155], v[192:195], v[26:29]
	ds_read_b128 v[148:151], v164 offset:18432
	ds_read_b128 v[152:155], v164 offset:19456
	s_waitcnt lgkmcnt(2)
	v_mfma_f32_16x16x32_bf16 v[30:33], v[156:159], v[188:191], v[90:93]
	v_mfma_f32_16x16x32_bf16 v[30:33], v[160:163], v[192:195], v[30:33]
	ds_read_b128 v[156:159], v164 offset:20480
	ds_read_b128 v[160:163], v164 offset:21504
	v_sub_f32_e64 v86, -v94, v174
	v_sub_f32_e64 v87, -v95, v174
	v_sub_f32_e64 v88, -v96, v174
	v_sub_f32_e64 v89, -v97, v174
	s_waitcnt lgkmcnt(2)
	v_mfma_f32_16x16x32_bf16 v[34:37], v[148:151], v[188:191], v[98:101]
	v_mfma_f32_16x16x32_bf16 v[34:37], v[152:155], v[192:195], v[34:37]
	ds_read_b128 v[148:151], v164 offset:22528
	ds_read_b128 v[152:155], v164 offset:23552
	v_sub_f32_e32 v90, v86, v174
	v_sub_f32_e32 v91, v87, v174
	v_sub_f32_e32 v92, v88, v174
	v_sub_f32_e32 v93, v89, v174
	s_waitcnt lgkmcnt(2)
	v_mfma_f32_16x16x32_bf16 v[38:41], v[156:159], v[188:191], v[86:89]
	v_mfma_f32_16x16x32_bf16 v[38:41], v[160:163], v[192:195], v[38:41]
	ds_read_b128 v[156:159], v164 offset:24576
	ds_read_b128 v[160:163], v164 offset:25600
	v_sub_f32_e32 v86, v90, v174
	v_sub_f32_e32 v87, v91, v174
	v_sub_f32_e32 v88, v92, v174
	v_sub_f32_e32 v89, v93, v174
	s_waitcnt lgkmcnt(2)
	v_mfma_f32_16x16x32_bf16 v[42:45], v[148:151], v[188:191], v[90:93]
	v_mfma_f32_16x16x32_bf16 v[42:45], v[152:155], v[192:195], v[42:45]
	ds_read_b128 v[148:151], v164 offset:26624
	ds_read_b128 v[152:155], v164 offset:27648
	v_sub_f32_e32 v90, v86, v174
	v_sub_f32_e32 v91, v87, v174
	v_sub_f32_e32 v92, v88, v174
	v_sub_f32_e32 v93, v89, v174
	s_waitcnt lgkmcnt(2)
	v_mfma_f32_16x16x32_bf16 v[46:49], v[156:159], v[188:191], v[86:89]
	v_mfma_f32_16x16x32_bf16 v[46:49], v[160:163], v[192:195], v[46:49]
	ds_read_b128 v[156:159], v164 offset:28672
	ds_read_b128 v[160:163], v164 offset:29696
	v_sub_f32_e32 v86, v90, v174
	v_sub_f32_e32 v87, v91, v174
	v_sub_f32_e32 v88, v92, v174
	v_sub_f32_e32 v89, v93, v174
	s_waitcnt lgkmcnt(2)
	v_mfma_f32_16x16x32_bf16 v[50:53], v[148:151], v[188:191], v[90:93]
	v_mfma_f32_16x16x32_bf16 v[50:53], v[152:155], v[192:195], v[50:53]
	ds_read_b128 v[148:151], v164 offset:30720
	ds_read_b128 v[152:155], v164 offset:31744
	v_sub_f32_e32 v90, v86, v174
	v_sub_f32_e32 v91, v87, v174
	v_sub_f32_e32 v92, v88, v174
	v_sub_f32_e32 v93, v89, v174
	s_waitcnt lgkmcnt(2)
	v_mfma_f32_16x16x32_bf16 v[54:57], v[156:159], v[188:191], v[86:89]
	v_mfma_f32_16x16x32_bf16 v[54:57], v[160:163], v[192:195], v[54:57]
	ds_read_b128 v[156:159], v164 offset:32768
	ds_read_b128 v[160:163], v164 offset:33792
	v_sub_f32_e32 v86, v90, v174
	v_sub_f32_e32 v87, v91, v174
	v_sub_f32_e32 v88, v92, v174
	v_sub_f32_e32 v89, v93, v174
	s_waitcnt lgkmcnt(2)
	v_mfma_f32_16x16x32_bf16 v[58:61], v[148:151], v[188:191], v[90:93]
	v_mfma_f32_16x16x32_bf16 v[58:61], v[152:155], v[192:195], v[58:61]
	ds_read_b128 v[148:151], v164 offset:34816
	ds_read_b128 v[152:155], v164 offset:35840
	v_sub_f32_e32 v90, v86, v174
	v_sub_f32_e32 v91, v87, v174
	v_sub_f32_e32 v92, v88, v174
	v_sub_f32_e32 v93, v89, v174
	v_cmp_le_i32_e32 vcc, 0, v108
	s_nop 1
	v_cndmask_b32_e32 v212, v252, v90, vcc
	v_cmp_le_i32_e32 vcc, 0, v110
	s_nop 1
	v_cndmask_b32_e32 v213, v252, v91, vcc
	v_cmp_le_i32_e32 vcc, 0, v111
	s_nop 1
	v_cndmask_b32_e32 v214, v252, v92, vcc
	v_cmp_le_i32_e32 vcc, 0, v177
	s_nop 1
	v_cndmask_b32_e32 v215, v252, v93, vcc
	s_waitcnt lgkmcnt(2)
; __device__ void att_phase(int wv, const Params& p, unsigned char* lds) {
;     ...
;             float mx = sink;
; #pragma unroll
;             for (int cb = 0; cb < 24; ++cb) { const int kb = B - 1 + (cb >> 3); const bool bval = (kb >= sb && kb < se);
; #pragma unroll
;                 for (int j = 0; j < 4; ++j) { const int krel = 16 * cb + 4 * lq + j - 128;
;                     int dist = qrow - krel; dist = dist < 0 ? -dist : dist;
;                     const float v = (bval && dist <= 128) ? sc[cb][j] * 0.125f - slope * (float)dist : -1e30f;
;                     sc[cb][j] = v; mx = fmaxf(mx, v); } }
;             mx = fmaxf(mx, __shfl_xor(mx, 16)); mx = fmaxf(mx, __shfl_xor(mx, 32));
;             float sum = 0.f;
; #pragma unroll
;             for (int cb = 0; cb < 24; ++cb)
; #pragma unroll
;                 for (int j = 0; j < 4; ++j) { const float e = __expf(sc[cb][j] - mx); sc[cb][j] = e; sum += e; }
;             sum += __shfl_xor(sum, 16); sum += __shfl_xor(sum, 32);
	v_mfma_f32_16x16x32_bf16 v[62:65], v[156:159], v[188:191], v[86:89]
	v_mfma_f32_16x16x32_bf16 v[62:65], v[160:163], v[192:195], v[62:65]
	s_waitcnt lgkmcnt(0)
	v_mfma_f32_16x16x32_bf16 v[66:69], v[148:151], v[188:191], v[212:215]
	v_mfma_f32_16x16x32_bf16 v[66:69], v[152:155], v[192:195], v[66:69]
	s_waitcnt lgkmcnt(7)
	ds_read_b64_tr_b16 v[216:217], v165 offset:2560
	ds_read_b64_tr_b16 v[218:219], v165 offset:5120
	ds_read_b64_tr_b16 v[220:221], v165 offset:2592
	ds_read_b64_tr_b16 v[222:223], v165 offset:5152
	ds_read_b64_tr_b16 v[224:225], v165 offset:2624
	ds_read_b64_tr_b16 v[226:227], v165 offset:5184
	ds_read_b64_tr_b16 v[228:229], v165 offset:2656
	ds_read_b64_tr_b16 v[230:231], v165 offset:5216
	v_max3_f32 v169, v2, v3, v4
	v_max3_f32 v172, v5, v6, v7
	v_max3_f32 v169, v8, v9, v169
	v_max3_f32 v172, v10, v11, v172
	v_max3_f32 v169, v12, v13, v169
	v_max3_f32 v172, v14, v15, v172
	v_max3_f32 v169, v16, v17, v169
	v_max3_f32 v172, v18, v19, v172
	v_max3_f32 v169, v20, v21, v169
	v_max3_f32 v172, v22, v23, v172
	v_max3_f32 v169, v24, v25, v169
	v_max3_f32 v172, v26, v27, v172
	v_max3_f32 v169, v28, v29, v169
	v_max3_f32 v172, v30, v31, v172
	v_max3_f32 v169, v32, v33, v169
	v_max3_f32 v172, v34, v35, v172
	v_max3_f32 v169, v36, v37, v169
	v_max3_f32 v172, v38, v39, v172
	v_max3_f32 v169, v40, v41, v169
	v_max3_f32 v172, v42, v43, v172
	v_max3_f32 v169, v44, v45, v169
	v_max3_f32 v172, v46, v47, v172
	v_max3_f32 v169, v48, v49, v169
	v_max3_f32 v172, v50, v51, v172
	v_max3_f32 v169, v52, v53, v169
	v_max3_f32 v172, v54, v55, v172
	v_max3_f32 v169, v56, v57, v169
	v_max3_f32 v172, v58, v59, v172
	v_max3_f32 v169, v60, v61, v169
	v_max3_f32 v172, v62, v63, v172
	v_max3_f32 v169, v64, v65, v169
	v_max3_f32 v172, v66, v67, v172
	v_max3_f32 v169, v68, v69, v169
	v_max_f32_e32 v169, v169, v172
	v_mul_f32_e32 v169, 0x3e000000, v169
	v_max_f32_e32 v169, v169, v146
	ds_bpermute_b32 v172, v1, v169
	s_waitcnt lgkmcnt(0)
	v_max_f32_e32 v169, v169, v172
	ds_bpermute_b32 v172, v114, v169
	s_waitcnt lgkmcnt(0)
	v_max_f32_e32 v169, v169, v172
	v_mul_f32_e32 v175, 0xbfb8aa3b, v169
	v_mov_b32_e32 v170, 0
	v_mov_b32_e32 v171, 0
	v_fma_f32 v2, v2, s46, v175
	v_fma_f32 v3, v3, s46, v175
	v_fma_f32 v4, v4, s46, v175
	v_fma_f32 v5, v5, s46, v175
	v_exp_f32_e32 v2, v2
	v_exp_f32_e32 v3, v3
	v_exp_f32_e32 v4, v4
	v_exp_f32_e32 v5, v5
	v_fma_f32 v6, v6, s46, v175
	v_fma_f32 v7, v7, s46, v175
	v_fma_f32 v8, v8, s46, v175
	v_fma_f32 v9, v9, s46, v175
	v_exp_f32_e32 v6, v6
	v_exp_f32_e32 v7, v7
	v_exp_f32_e32 v8, v8
	v_exp_f32_e32 v9, v9
	v_add_f32_e32 v171, v171, v2
	v_add_f32_e32 v170, v170, v3
	v_add_f32_e32 v171, v171, v4
	v_add_f32_e32 v170, v170, v5
	v_fma_f32 v10, v10, s46, v175
	v_fma_f32 v11, v11, s46, v175
	v_fma_f32 v12, v12, s46, v175
	v_fma_f32 v13, v13, s46, v175
	v_exp_f32_e32 v10, v10
	v_exp_f32_e32 v11, v11
	v_exp_f32_e32 v12, v12
	v_exp_f32_e32 v13, v13
	v_add_f32_e32 v171, v171, v6
	v_add_f32_e32 v170, v170, v7
	v_add_f32_e32 v171, v171, v8
	v_add_f32_e32 v170, v170, v9
	v_fma_f32 v14, v14, s46, v175
	v_fma_f32 v15, v15, s46, v175
	v_fma_f32 v16, v16, s46, v175
	v_fma_f32 v17, v17, s46, v175
	v_exp_f32_e32 v14, v14
	v_exp_f32_e32 v15, v15
	v_exp_f32_e32 v16, v16
	v_exp_f32_e32 v17, v17
	v_add_f32_e32 v171, v171, v10
	v_add_f32_e32 v170, v170, v11
	v_add_f32_e32 v171, v171, v12
	v_add_f32_e32 v170, v170, v13
	v_fma_f32 v18, v18, s46, v175
	v_fma_f32 v19, v19, s46, v175
	v_fma_f32 v20, v20, s46, v175
	v_fma_f32 v21, v21, s46, v175
	v_exp_f32_e32 v18, v18
	v_exp_f32_e32 v19, v19
	v_exp_f32_e32 v20, v20
	v_exp_f32_e32 v21, v21
	v_add_f32_e32 v171, v171, v14
	v_add_f32_e32 v170, v170, v15
	v_add_f32_e32 v171, v171, v16
	v_add_f32_e32 v170, v170, v17
	v_fma_f32 v22, v22, s46, v175
	v_fma_f32 v23, v23, s46, v175
	v_fma_f32 v24, v24, s46, v175
	v_fma_f32 v25, v25, s46, v175
	v_exp_f32_e32 v22, v22
	v_exp_f32_e32 v23, v23
	v_exp_f32_e32 v24, v24
	v_exp_f32_e32 v25, v25
	v_add_f32_e32 v171, v171, v18
	v_add_f32_e32 v170, v170, v19
	v_add_f32_e32 v171, v171, v20
	v_add_f32_e32 v170, v170, v21
	v_fma_f32 v26, v26, s46, v175
	v_fma_f32 v27, v27, s46, v175
	v_fma_f32 v28, v28, s46, v175
	v_fma_f32 v29, v29, s46, v175
	v_exp_f32_e32 v26, v26
	v_exp_f32_e32 v27, v27
	v_exp_f32_e32 v28, v28
	v_exp_f32_e32 v29, v29
	v_add_f32_e32 v171, v171, v22
	v_add_f32_e32 v170, v170, v23
	v_add_f32_e32 v171, v171, v24
	v_add_f32_e32 v170, v170, v25
	v_fma_f32 v30, v30, s46, v175
	v_fma_f32 v31, v31, s46, v175
	v_fma_f32 v32, v32, s46, v175
	v_fma_f32 v33, v33, s46, v175
	v_exp_f32_e32 v30, v30
	v_exp_f32_e32 v31, v31
	v_exp_f32_e32 v32, v32
	v_exp_f32_e32 v33, v33
	v_add_f32_e32 v171, v171, v26
	v_add_f32_e32 v170, v170, v27
	v_add_f32_e32 v171, v171, v28
	v_add_f32_e32 v170, v170, v29
	v_fma_f32 v34, v34, s46, v175
	v_fma_f32 v35, v35, s46, v175
	v_fma_f32 v36, v36, s46, v175
	v_fma_f32 v37, v37, s46, v175
	v_exp_f32_e32 v34, v34
	v_exp_f32_e32 v35, v35
	v_exp_f32_e32 v36, v36
	v_exp_f32_e32 v37, v37
	v_add_f32_e32 v171, v171, v30
	v_add_f32_e32 v170, v170, v31
	v_add_f32_e32 v171, v171, v32
	v_add_f32_e32 v170, v170, v33
	v_fma_f32 v38, v38, s46, v175
	v_fma_f32 v39, v39, s46, v175
	v_fma_f32 v40, v40, s46, v175
	v_fma_f32 v41, v41, s46, v175
	v_exp_f32_e32 v38, v38
	v_exp_f32_e32 v39, v39
	v_exp_f32_e32 v40, v40
	v_exp_f32_e32 v41, v41
	v_add_f32_e32 v171, v171, v34
	v_add_f32_e32 v170, v170, v35
	v_add_f32_e32 v171, v171, v36
	v_add_f32_e32 v170, v170, v37
	v_fma_f32 v42, v42, s46, v175
	v_fma_f32 v43, v43, s46, v175
	v_fma_f32 v44, v44, s46, v175
	v_fma_f32 v45, v45, s46, v175
	v_exp_f32_e32 v42, v42
	v_exp_f32_e32 v43, v43
	v_exp_f32_e32 v44, v44
	v_exp_f32_e32 v45, v45
; __device__ __forceinline__ unsigned cvt_pk_bf16_asm(float lo, float hi) { unsigned r; asm volatile("v_cvt_pk_bf16_f32 %0, %1, %2" : "=v"(r) : "v"(lo), "v"(hi)); return r; }
; __device__ __forceinline__ f32x4 mfma16(bf16x8 a, bf16x8 b, f32x4 c) { return __builtin_amdgcn_mfma_f32_16x16x32_bf16(a, b, c, 0, 0, 0); }
; __device__ void att_phase(int wv, const Params& p, unsigned char* lds) {
;     ...
;             for (int cb = 0; cb < 24; ++cb)
; #pragma unroll
;                 for (int j = 0; j < 4; ++j) { const float e = __expf(sc[cb][j] - mx); sc[cb][j] = e; sum += e; }
;             sum += __shfl_xor(sum, 16); sum += __shfl_xor(sum, 32);
;             sum += __expf(sink - mx);
;             const float inv = 1.0f / sum;
;             f32x4 oa[4];
; #pragma unroll
;             for (int db = 0; db < 4; ++db) oa[db] = (f32x4){0, 0, 0, 0};
; #pragma unroll
;             for (int ks = 0; ks < 12; ++ks) {
;                 union { bf16x8 v; unsigned u[4]; } pf;
;                 pf.u[0] = cvt_pk_bf16_asm(sc[2 * ks][0], sc[2 * ks][1]); pf.u[1] = cvt_pk_bf16_asm(sc[2 * ks][2], sc[2 * ks][3]);
;                 pf.u[2] = cvt_pk_bf16_asm(sc[2 * ks + 1][0], sc[2 * ks + 1][1]); pf.u[3] = cvt_pk_bf16_asm(sc[2 * ks + 1][2], sc[2 * ks + 1][3]);
; #pragma unroll
;                 for (int db = 0; db < 4; ++db) {
;                     union { bf16x8 v; u32x2 h2[2]; } vf;
;                     const bf16_t* vp = VTL + (16 * db + lr) * VP + 32 * ks + 4 * lq;
;                     vf.h2[0] = *(const u32x2*)vp; vf.h2[1] = *(const u32x2*)(vp + 16);
;                     oa[db] = mfma16(vf.v, pf.v, oa[db]); } }
	v_add_f32_e32 v171, v171, v38
	v_add_f32_e32 v170, v170, v39
	v_add_f32_e32 v171, v171, v40
	v_add_f32_e32 v170, v170, v41
	v_fma_f32 v46, v46, s46, v175
	v_fma_f32 v47, v47, s46, v175
	v_fma_f32 v48, v48, s46, v175
	v_fma_f32 v49, v49, s46, v175
	v_exp_f32_e32 v46, v46
	v_exp_f32_e32 v47, v47
	v_exp_f32_e32 v48, v48
	v_exp_f32_e32 v49, v49
	v_add_f32_e32 v171, v171, v42
	v_add_f32_e32 v170, v170, v43
	v_add_f32_e32 v171, v171, v44
	v_add_f32_e32 v170, v170, v45
	v_fma_f32 v50, v50, s46, v175
	v_fma_f32 v51, v51, s46, v175
	v_fma_f32 v52, v52, s46, v175
	v_fma_f32 v53, v53, s46, v175
	v_exp_f32_e32 v50, v50
	v_exp_f32_e32 v51, v51
	v_exp_f32_e32 v52, v52
	v_exp_f32_e32 v53, v53
	v_add_f32_e32 v171, v171, v46
	v_add_f32_e32 v170, v170, v47
	v_add_f32_e32 v171, v171, v48
	v_add_f32_e32 v170, v170, v49
	v_fma_f32 v54, v54, s46, v175
	v_fma_f32 v55, v55, s46, v175
	v_fma_f32 v56, v56, s46, v175
	v_fma_f32 v57, v57, s46, v175
	v_exp_f32_e32 v54, v54
	v_exp_f32_e32 v55, v55
	v_exp_f32_e32 v56, v56
	v_exp_f32_e32 v57, v57
	v_add_f32_e32 v171, v171, v50
	v_add_f32_e32 v170, v170, v51
	v_add_f32_e32 v171, v171, v52
	v_add_f32_e32 v170, v170, v53
	v_fma_f32 v58, v58, s46, v175
	v_fma_f32 v59, v59, s46, v175
	v_fma_f32 v60, v60, s46, v175
	v_fma_f32 v61, v61, s46, v175
	v_exp_f32_e32 v58, v58
	v_exp_f32_e32 v59, v59
	v_exp_f32_e32 v60, v60
	v_exp_f32_e32 v61, v61
	v_add_f32_e32 v171, v171, v54
	v_add_f32_e32 v170, v170, v55
	v_add_f32_e32 v171, v171, v56
	v_add_f32_e32 v170, v170, v57
	v_fma_f32 v62, v62, s46, v175
	v_fma_f32 v63, v63, s46, v175
	v_fma_f32 v64, v64, s46, v175
	v_fma_f32 v65, v65, s46, v175
	v_exp_f32_e32 v62, v62
	v_exp_f32_e32 v63, v63
	v_exp_f32_e32 v64, v64
	v_exp_f32_e32 v65, v65
	v_add_f32_e32 v171, v171, v58
	v_add_f32_e32 v170, v170, v59
	v_add_f32_e32 v171, v171, v60
	v_add_f32_e32 v170, v170, v61
	v_fma_f32 v66, v66, s46, v175
	v_fma_f32 v67, v67, s46, v175
	v_fma_f32 v68, v68, s46, v175
	v_fma_f32 v69, v69, s46, v175
	v_exp_f32_e32 v66, v66
	v_exp_f32_e32 v67, v67
	v_exp_f32_e32 v68, v68
	v_exp_f32_e32 v69, v69
	v_add_f32_e32 v171, v171, v62
	v_add_f32_e32 v170, v170, v63
	v_add_f32_e32 v171, v171, v64
	v_add_f32_e32 v170, v170, v65
	v_add_f32_e32 v171, v171, v66
	v_add_f32_e32 v170, v170, v67
	v_add_f32_e32 v171, v171, v68
	v_add_f32_e32 v170, v170, v69
	v_add_f32_e32 v170, v170, v171
	v_cvt_pk_bf16_f32 v2, v2, v3
	v_cvt_pk_bf16_f32 v3, v4, v5
	v_cvt_pk_bf16_f32 v4, v6, v7
	v_cvt_pk_bf16_f32 v5, v8, v9
	v_cvt_pk_bf16_f32 v10, v10, v11
	v_cvt_pk_bf16_f32 v11, v12, v13
	v_cvt_pk_bf16_f32 v12, v14, v15
	v_cvt_pk_bf16_f32 v13, v16, v17
	v_cvt_pk_bf16_f32 v18, v18, v19
	v_cvt_pk_bf16_f32 v19, v20, v21
	v_cvt_pk_bf16_f32 v20, v22, v23
	v_cvt_pk_bf16_f32 v21, v24, v25
	v_cvt_pk_bf16_f32 v26, v26, v27
	v_cvt_pk_bf16_f32 v27, v28, v29
	v_cvt_pk_bf16_f32 v28, v30, v31
	v_cvt_pk_bf16_f32 v29, v32, v33
	v_cvt_pk_bf16_f32 v34, v34, v35
	v_cvt_pk_bf16_f32 v35, v36, v37
	v_cvt_pk_bf16_f32 v36, v38, v39
	v_cvt_pk_bf16_f32 v37, v40, v41
	v_cvt_pk_bf16_f32 v42, v42, v43
	v_cvt_pk_bf16_f32 v43, v44, v45
	v_cvt_pk_bf16_f32 v44, v46, v47
	v_cvt_pk_bf16_f32 v45, v48, v49
	v_cvt_pk_bf16_f32 v50, v50, v51
	v_cvt_pk_bf16_f32 v51, v52, v53
	v_cvt_pk_bf16_f32 v52, v54, v55
	v_cvt_pk_bf16_f32 v53, v56, v57
	v_cvt_pk_bf16_f32 v58, v58, v59
	v_cvt_pk_bf16_f32 v59, v60, v61
	v_cvt_pk_bf16_f32 v60, v62, v63
	v_cvt_pk_bf16_f32 v61, v64, v65
	v_cvt_pk_bf16_f32 v66, v66, v67
	v_cvt_pk_bf16_f32 v67, v68, v69
	v_mov_b32_e32 v68, 0
	v_mov_b32_e32 v69, 0
	ds_bpermute_b32 v172, v1, v170
	v_sub_f32_e32 v173, v146, v169
	v_mul_f32_e32 v173, 0x3fb8aa3b, v173
	v_exp_f32_e32 v173, v173
	s_waitcnt lgkmcnt(0)
	v_add_f32_e32 v170, v170, v172
	ds_bpermute_b32 v172, v114, v170
	s_waitcnt lgkmcnt(7)
	ds_read_b64_tr_b16 v[232:233], v165 offset:7680
	ds_read_b64_tr_b16 v[234:235], v165 offset:10240
	ds_read_b64_tr_b16 v[236:237], v165 offset:7712
	ds_read_b64_tr_b16 v[238:239], v165 offset:10272
	ds_read_b64_tr_b16 v[240:241], v165 offset:7744
	ds_read_b64_tr_b16 v[242:243], v165 offset:10304
	ds_read_b64_tr_b16 v[244:245], v165 offset:7776
	ds_read_b64_tr_b16 v[246:247], v165 offset:10336
	s_waitcnt lgkmcnt(8)
	v_mfma_f32_16x16x32_bf16 v[70:73], v[216:219], v[2:5], 0
	v_mfma_f32_16x16x32_bf16 v[74:77], v[220:223], v[2:5], 0
	v_mfma_f32_16x16x32_bf16 v[78:81], v[224:227], v[2:5], 0
	v_mfma_f32_16x16x32_bf16 v[82:85], v[228:231], v[2:5], 0
	v_add_f32_e32 v170, v170, v172
	v_add_f32_e32 v170, v170, v173
	v_rcp_f32_e32 v147, v170
	s_nop 0
	v_fma_f32 v179, -v170, v147, 1.0
	v_fmac_f32_e32 v147, v179, v147
	s_waitcnt lgkmcnt(7)
	ds_read_b64_tr_b16 v[216:217], v165 offset:12800
	ds_read_b64_tr_b16 v[218:219], v165 offset:15360
	ds_read_b64_tr_b16 v[220:221], v165 offset:12832
	ds_read_b64_tr_b16 v[222:223], v165 offset:15392
	ds_read_b64_tr_b16 v[224:225], v165 offset:12864
	ds_read_b64_tr_b16 v[226:227], v165 offset:15424
	ds_read_b64_tr_b16 v[228:229], v165 offset:12896
	ds_read_b64_tr_b16 v[230:231], v165 offset:15456
	s_waitcnt lgkmcnt(8)
	v_mfma_f32_16x16x32_bf16 v[70:73], v[232:235], v[10:13], v[70:73]
	v_mfma_f32_16x16x32_bf16 v[74:77], v[236:239], v[10:13], v[74:77]
	v_mfma_f32_16x16x32_bf16 v[78:81], v[240:243], v[10:13], v[78:81]
	v_mfma_f32_16x16x32_bf16 v[82:85], v[244:247], v[10:13], v[82:85]
	s_waitcnt lgkmcnt(7)
	ds_read_b64_tr_b16 v[232:233], v165 offset:17920
	ds_read_b64_tr_b16 v[234:235], v165 offset:20480
	ds_read_b64_tr_b16 v[236:237], v165 offset:17952
	ds_read_b64_tr_b16 v[238:239], v165 offset:20512
	ds_read_b64_tr_b16 v[240:241], v165 offset:17984
	ds_read_b64_tr_b16 v[242:243], v165 offset:20544
	ds_read_b64_tr_b16 v[244:245], v165 offset:18016
	ds_read_b64_tr_b16 v[246:247], v165 offset:20576
	s_waitcnt lgkmcnt(8)
; __device__ __forceinline__ unsigned cvt_pk_bf16_asm(float lo, float hi) { unsigned r; asm volatile("v_cvt_pk_bf16_f32 %0, %1, %2" : "=v"(r) : "v"(lo), "v"(hi)); return r; }
; __device__ __forceinline__ f32x4 mfma16(bf16x8 a, bf16x8 b, f32x4 c) { return __builtin_amdgcn_mfma_f32_16x16x32_bf16(a, b, c, 0, 0, 0); }
; __device__ void att_phase(int wv, const Params& p, unsigned char* lds) {
;     ...
;             for (int cb = 0; cb < 24; ++cb) { f32x4 a = {0, 0, 0, 0};
; #pragma unroll
;                 for (int kk = 0; kk < 2; ++kk) { const bf16x8 kf = *(const bf16x8*)(KL + (16 * cb + lr) * KP + 32 * kk + 8 * lq); a = mfma16(kf, qf[kk], a); }
;                 sc[cb] = a; }
;     ...
;             for (int ks = 0; ks < 12; ++ks) {
;                 union { bf16x8 v; unsigned u[4]; } pf;
;                 pf.u[0] = cvt_pk_bf16_asm(sc[2 * ks][0], sc[2 * ks][1]); pf.u[1] = cvt_pk_bf16_asm(sc[2 * ks][2], sc[2 * ks][3]);
;                 pf.u[2] = cvt_pk_bf16_asm(sc[2 * ks + 1][0], sc[2 * ks + 1][1]); pf.u[3] = cvt_pk_bf16_asm(sc[2 * ks + 1][2], sc[2 * ks + 1][3]);
; #pragma unroll
;                 for (int db = 0; db < 4; ++db) {
;                     union { bf16x8 v; u32x2 h2[2]; } vf;
;                     const bf16_t* vp = VTL + (16 * db + lr) * VP + 32 * ks + 4 * lq;
;                     vf.h2[0] = *(const u32x2*)vp; vf.h2[1] = *(const u32x2*)(vp + 16);
;                     oa[db] = mfma16(vf.v, pf.v, oa[db]); } }
; #pragma unroll
;             for (int db = 0; db < 4; ++db) { const f32x4 o = oa[db] * inv; u32x2 wv; wv.x = cvt_pk_bf16_asm(o[0], o[1]); wv.y = cvt_pk_bf16_asm(o[2], o[3]);
;                 *(u32x2*)(qkv + tokq * 1536 + 64 * h + 16 * db + 4 * lq) = wv; }
	v_mfma_f32_16x16x32_bf16 v[70:73], v[216:219], v[18:21], v[70:73]
	v_mfma_f32_16x16x32_bf16 v[74:77], v[220:223], v[18:21], v[74:77]
	v_mfma_f32_16x16x32_bf16 v[78:81], v[224:227], v[18:21], v[78:81]
	v_mfma_f32_16x16x32_bf16 v[82:85], v[228:231], v[18:21], v[82:85]
	s_waitcnt lgkmcnt(7)
	ds_read_b64_tr_b16 v[216:217], v165 offset:23040
	ds_read_b64_tr_b16 v[218:219], v165 offset:25600
	ds_read_b64_tr_b16 v[220:221], v165 offset:23072
	ds_read_b64_tr_b16 v[222:223], v165 offset:25632
	ds_read_b64_tr_b16 v[224:225], v165 offset:23104
	ds_read_b64_tr_b16 v[226:227], v165 offset:25664
	ds_read_b64_tr_b16 v[228:229], v165 offset:23136
	ds_read_b64_tr_b16 v[230:231], v165 offset:25696
	s_waitcnt lgkmcnt(8)
	v_mfma_f32_16x16x32_bf16 v[70:73], v[232:235], v[26:29], v[70:73]
	v_mfma_f32_16x16x32_bf16 v[74:77], v[236:239], v[26:29], v[74:77]
	v_mfma_f32_16x16x32_bf16 v[78:81], v[240:243], v[26:29], v[78:81]
	v_mfma_f32_16x16x32_bf16 v[82:85], v[244:247], v[26:29], v[82:85]
	s_waitcnt lgkmcnt(7)
	ds_read_b64_tr_b16 v[232:233], v165 offset:28160
	ds_read_b64_tr_b16 v[234:235], v165 offset:30720
	ds_read_b64_tr_b16 v[236:237], v165 offset:28192
	ds_read_b64_tr_b16 v[238:239], v165 offset:30752
	ds_read_b64_tr_b16 v[240:241], v165 offset:28224
	ds_read_b64_tr_b16 v[242:243], v165 offset:30784
	ds_read_b64_tr_b16 v[244:245], v165 offset:28256
	ds_read_b64_tr_b16 v[246:247], v165 offset:30816
	s_waitcnt lgkmcnt(8)
	v_mfma_f32_16x16x32_bf16 v[70:73], v[216:219], v[34:37], v[70:73]
	v_mfma_f32_16x16x32_bf16 v[74:77], v[220:223], v[34:37], v[74:77]
	v_mfma_f32_16x16x32_bf16 v[78:81], v[224:227], v[34:37], v[78:81]
	v_mfma_f32_16x16x32_bf16 v[82:85], v[228:231], v[34:37], v[82:85]
	s_waitcnt lgkmcnt(7)
	ds_read_b64_tr_b16 v[216:217], v165 offset:33280
	ds_read_b64_tr_b16 v[218:219], v165 offset:35840
	ds_read_b64_tr_b16 v[220:221], v165 offset:33312
	ds_read_b64_tr_b16 v[222:223], v165 offset:35872
	ds_read_b64_tr_b16 v[224:225], v165 offset:33344
	ds_read_b64_tr_b16 v[226:227], v165 offset:35904
	ds_read_b64_tr_b16 v[228:229], v165 offset:33376
	ds_read_b64_tr_b16 v[230:231], v165 offset:35936
	s_waitcnt lgkmcnt(8)
	v_mfma_f32_16x16x32_bf16 v[70:73], v[232:235], v[42:45], v[70:73]
	v_mfma_f32_16x16x32_bf16 v[74:77], v[236:239], v[42:45], v[74:77]
	v_mfma_f32_16x16x32_bf16 v[78:81], v[240:243], v[42:45], v[78:81]
	v_mfma_f32_16x16x32_bf16 v[82:85], v[244:247], v[42:45], v[82:85]
	s_waitcnt lgkmcnt(7)
	ds_read_b64_tr_b16 v[232:233], v165 offset:38400
	ds_read_b64_tr_b16 v[234:235], v165 offset:40960
	ds_read_b64_tr_b16 v[236:237], v165 offset:38432
	ds_read_b64_tr_b16 v[238:239], v165 offset:40992
	ds_read_b64_tr_b16 v[240:241], v165 offset:38464
	ds_read_b64_tr_b16 v[242:243], v165 offset:41024
	ds_read_b64_tr_b16 v[244:245], v165 offset:38496
	ds_read_b64_tr_b16 v[246:247], v165 offset:41056
	s_waitcnt lgkmcnt(8)
	v_mfma_f32_16x16x32_bf16 v[70:73], v[216:219], v[50:53], v[70:73]
	v_mfma_f32_16x16x32_bf16 v[74:77], v[220:223], v[50:53], v[74:77]
	v_mfma_f32_16x16x32_bf16 v[78:81], v[224:227], v[50:53], v[78:81]
	v_mfma_f32_16x16x32_bf16 v[82:85], v[228:231], v[50:53], v[82:85]
	s_waitcnt lgkmcnt(7)
	ds_read_b64_tr_b16 v[216:217], v165 offset:43520
	ds_read_b64_tr_b16 v[218:219], v165 offset:43520
	ds_read_b64_tr_b16 v[220:221], v165 offset:43552
	ds_read_b64_tr_b16 v[222:223], v165 offset:43552
	ds_read_b64_tr_b16 v[224:225], v165 offset:43584
	ds_read_b64_tr_b16 v[226:227], v165 offset:43584
	ds_read_b64_tr_b16 v[228:229], v165 offset:43616
	ds_read_b64_tr_b16 v[230:231], v165 offset:43616
	s_waitcnt lgkmcnt(8)
	v_mfma_f32_16x16x32_bf16 v[70:73], v[232:235], v[58:61], v[70:73]
	v_mfma_f32_16x16x32_bf16 v[74:77], v[236:239], v[58:61], v[74:77]
	v_mfma_f32_16x16x32_bf16 v[78:81], v[240:243], v[58:61], v[78:81]
	v_mfma_f32_16x16x32_bf16 v[82:85], v[244:247], v[58:61], v[82:85]
	s_waitcnt lgkmcnt(0)
	v_mfma_f32_16x16x32_bf16 v[70:73], v[216:219], v[66:69], v[70:73]
	v_mfma_f32_16x16x32_bf16 v[74:77], v[220:223], v[66:69], v[74:77]
	v_mfma_f32_16x16x32_bf16 v[78:81], v[224:227], v[66:69], v[78:81]
	v_mfma_f32_16x16x32_bf16 v[82:85], v[228:231], v[66:69], v[82:85]
	s_nop 7
	s_nop 1
	v_mul_f32_e32 v70, v70, v147
	v_mul_f32_e32 v71, v71, v147
	v_mul_f32_e32 v72, v72, v147
	v_mul_f32_e32 v73, v73, v147
	v_mul_f32_e32 v74, v74, v147
	v_mul_f32_e32 v75, v75, v147
	v_mul_f32_e32 v76, v76, v147
	v_mul_f32_e32 v77, v77, v147
	v_mul_f32_e32 v78, v78, v147
	v_mul_f32_e32 v79, v79, v147
	v_mul_f32_e32 v80, v80, v147
	v_mul_f32_e32 v81, v81, v147
	v_mul_f32_e32 v82, v82, v147
	v_mul_f32_e32 v83, v83, v147
	v_mul_f32_e32 v84, v84, v147
	v_mul_f32_e32 v85, v85, v147
	v_cvt_pk_bf16_f32 v70, v70, v71
	v_cvt_pk_bf16_f32 v71, v72, v73
	v_cvt_pk_bf16_f32 v74, v74, v75
	v_cvt_pk_bf16_f32 v75, v76, v77
	v_cvt_pk_bf16_f32 v78, v78, v79
	v_cvt_pk_bf16_f32 v79, v80, v81
	v_cvt_pk_bf16_f32 v82, v82, v83
	v_cvt_pk_bf16_f32 v83, v84, v85
	global_store_dwordx2 v[248:249], v[70:71], off offset:-64
	global_store_dwordx2 v[248:249], v[74:75], off offset:-32
	global_store_dwordx2 v[248:249], v[78:79], off
	global_store_dwordx2 v[248:249], v[82:83], off offset:32
	v_lshl_add_u64 v[248:249], v[248:249], 0, s[48:49]
	v_sub_f32_e32 v86, v94, v176
	v_sub_f32_e32 v87, v95, v176
	v_sub_f32_e32 v88, v96, v176
	v_sub_f32_e32 v89, v97, v176
	v_cmp_ge_i32_e32 vcc, 0, v108
	s_nop 1
	v_cndmask_b32_e32 v212, v252, v86, vcc
	v_cmp_ge_i32_e32 vcc, 0, v110
	s_nop 1
	v_cndmask_b32_e32 v213, v252, v87, vcc
	v_cmp_ge_i32_e32 vcc, 0, v111
	s_nop 1
	v_cndmask_b32_e32 v214, v252, v88, vcc
	v_cmp_ge_i32_e32 vcc, 0, v177
	s_nop 1
	v_cndmask_b32_e32 v215, v252, v89, vcc
	ds_read_b128 v[148:151], v164 offset:4096
	ds_read_b128 v[152:155], v164 offset:5120
	ds_read_b128 v[156:159], v164 offset:6144
	ds_read_b128 v[160:163], v164 offset:7168
	v_add_f32_e32 v90, v86, v174
	v_add_f32_e32 v91, v87, v174
	v_add_f32_e32 v92, v88, v174
	v_add_f32_e32 v93, v89, v174
	s_waitcnt lgkmcnt(2)
; __device__ __forceinline__ f32x4 mfma16(bf16x8 a, bf16x8 b, f32x4 c) { return __builtin_amdgcn_mfma_f32_16x16x32_bf16(a, b, c, 0, 0, 0); }
; __device__ void att_phase(int wv, const Params& p, unsigned char* lds) {
;     ...
;             for (int cb = 0; cb < 24; ++cb) { f32x4 a = {0, 0, 0, 0};
; #pragma unroll
;                 for (int kk = 0; kk < 2; ++kk) { const bf16x8 kf = *(const bf16x8*)(KL + (16 * cb + lr) * KP + 32 * kk + 8 * lq); a = mfma16(kf, qf[kk], a); }
;                 sc[cb] = a; }
	v_mfma_f32_16x16x32_bf16 v[2:5], v[148:151], v[196:199], v[212:215]
	v_mfma_f32_16x16x32_bf16 v[2:5], v[152:155], v[200:203], v[2:5]
	ds_read_b128 v[148:151], v164 offset:8192
	ds_read_b128 v[152:155], v164 offset:9216
	v_add_f32_e32 v86, v90, v174
	v_add_f32_e32 v87, v91, v174
	v_add_f32_e32 v88, v92, v174
	v_add_f32_e32 v89, v93, v174
	s_waitcnt lgkmcnt(2)
	v_mfma_f32_16x16x32_bf16 v[6:9], v[156:159], v[196:199], v[90:93]
	v_mfma_f32_16x16x32_bf16 v[6:9], v[160:163], v[200:203], v[6:9]
	ds_read_b128 v[156:159], v164 offset:10240
	ds_read_b128 v[160:163], v164 offset:11264
	v_add_f32_e32 v90, v86, v174
	v_add_f32_e32 v91, v87, v174
	v_add_f32_e32 v92, v88, v174
	v_add_f32_e32 v93, v89, v174
	s_waitcnt lgkmcnt(2)
	v_mfma_f32_16x16x32_bf16 v[10:13], v[148:151], v[196:199], v[86:89]
	v_mfma_f32_16x16x32_bf16 v[10:13], v[152:155], v[200:203], v[10:13]
	ds_read_b128 v[148:151], v164 offset:12288
	ds_read_b128 v[152:155], v164 offset:13312
	v_add_f32_e32 v86, v90, v174
	v_add_f32_e32 v87, v91, v174
	v_add_f32_e32 v88, v92, v174
	v_add_f32_e32 v89, v93, v174
	s_waitcnt lgkmcnt(2)
	v_mfma_f32_16x16x32_bf16 v[14:17], v[156:159], v[196:199], v[90:93]
	v_mfma_f32_16x16x32_bf16 v[14:17], v[160:163], v[200:203], v[14:17]
	ds_read_b128 v[156:159], v164 offset:14336
	ds_read_b128 v[160:163], v164 offset:15360
	v_add_f32_e32 v90, v86, v174
	v_add_f32_e32 v91, v87, v174
	v_add_f32_e32 v92, v88, v174
	v_add_f32_e32 v93, v89, v174
	s_waitcnt lgkmcnt(2)
	v_mfma_f32_16x16x32_bf16 v[18:21], v[148:151], v[196:199], v[86:89]
	v_mfma_f32_16x16x32_bf16 v[18:21], v[152:155], v[200:203], v[18:21]
	ds_read_b128 v[148:151], v164 offset:16384
	ds_read_b128 v[152:155], v164 offset:17408
	v_add_f32_e32 v86, v90, v174
	v_add_f32_e32 v87, v91, v174
	v_add_f32_e32 v88, v92, v174
	v_add_f32_e32 v89, v93, v174
	s_waitcnt lgkmcnt(2)
	v_mfma_f32_16x16x32_bf16 v[22:25], v[156:159], v[196:199], v[90:93]
	v_mfma_f32_16x16x32_bf16 v[22:25], v[160:163], v[200:203], v[22:25]
	ds_read_b128 v[156:159], v164 offset:18432
	ds_read_b128 v[160:163], v164 offset:19456
	v_add_f32_e32 v90, v86, v174
	v_add_f32_e32 v91, v87, v174
	v_add_f32_e32 v92, v88, v174
	v_add_f32_e32 v93, v89, v174
	s_waitcnt lgkmcnt(2)
	v_mfma_f32_16x16x32_bf16 v[26:29], v[148:151], v[196:199], v[86:89]
	v_mfma_f32_16x16x32_bf16 v[26:29], v[152:155], v[200:203], v[26:29]
	ds_read_b128 v[148:151], v164 offset:20480
	ds_read_b128 v[152:155], v164 offset:21504
	s_waitcnt lgkmcnt(2)
	v_mfma_f32_16x16x32_bf16 v[30:33], v[156:159], v[196:199], v[90:93]
	v_mfma_f32_16x16x32_bf16 v[30:33], v[160:163], v[200:203], v[30:33]
	ds_read_b128 v[156:159], v164 offset:22528
	ds_read_b128 v[160:163], v164 offset:23552
	v_sub_f32_e64 v86, -v94, v174
	v_sub_f32_e64 v87, -v95, v174
	v_sub_f32_e64 v88, -v96, v174
	v_sub_f32_e64 v89, -v97, v174
	s_waitcnt lgkmcnt(2)
	v_mfma_f32_16x16x32_bf16 v[34:37], v[148:151], v[196:199], v[98:101]
	v_mfma_f32_16x16x32_bf16 v[34:37], v[152:155], v[200:203], v[34:37]
	ds_read_b128 v[148:151], v164 offset:24576
	ds_read_b128 v[152:155], v164 offset:25600
	v_sub_f32_e32 v90, v86, v174
	v_sub_f32_e32 v91, v87, v174
	v_sub_f32_e32 v92, v88, v174
	v_sub_f32_e32 v93, v89, v174
	s_waitcnt lgkmcnt(2)
	v_mfma_f32_16x16x32_bf16 v[38:41], v[156:159], v[196:199], v[86:89]
	v_mfma_f32_16x16x32_bf16 v[38:41], v[160:163], v[200:203], v[38:41]
	ds_read_b128 v[156:159], v164 offset:26624
	ds_read_b128 v[160:163], v164 offset:27648
	v_sub_f32_e32 v86, v90, v174
	v_sub_f32_e32 v87, v91, v174
	v_sub_f32_e32 v88, v92, v174
	v_sub_f32_e32 v89, v93, v174
	s_waitcnt lgkmcnt(2)
	v_mfma_f32_16x16x32_bf16 v[42:45], v[148:151], v[196:199], v[90:93]
	v_mfma_f32_16x16x32_bf16 v[42:45], v[152:155], v[200:203], v[42:45]
	ds_read_b128 v[148:151], v164 offset:28672
	ds_read_b128 v[152:155], v164 offset:29696
	v_sub_f32_e32 v90, v86, v174
	v_sub_f32_e32 v91, v87, v174
	v_sub_f32_e32 v92, v88, v174
	v_sub_f32_e32 v93, v89, v174
	s_waitcnt lgkmcnt(2)
	v_mfma_f32_16x16x32_bf16 v[46:49], v[156:159], v[196:199], v[86:89]
	v_mfma_f32_16x16x32_bf16 v[46:49], v[160:163], v[200:203], v[46:49]
	ds_read_b128 v[156:159], v164 offset:30720
	ds_read_b128 v[160:163], v164 offset:31744
	v_sub_f32_e32 v86, v90, v174
	v_sub_f32_e32 v87, v91, v174
	v_sub_f32_e32 v88, v92, v174
	v_sub_f32_e32 v89, v93, v174
	s_waitcnt lgkmcnt(2)
	v_mfma_f32_16x16x32_bf16 v[50:53], v[148:151], v[196:199], v[90:93]
	v_mfma_f32_16x16x32_bf16 v[50:53], v[152:155], v[200:203], v[50:53]
	ds_read_b128 v[148:151], v164 offset:32768
	ds_read_b128 v[152:155], v164 offset:33792
	v_sub_f32_e32 v90, v86, v174
	v_sub_f32_e32 v91, v87, v174
	v_sub_f32_e32 v92, v88, v174
	v_sub_f32_e32 v93, v89, v174
	s_waitcnt lgkmcnt(2)
	v_mfma_f32_16x16x32_bf16 v[54:57], v[156:159], v[196:199], v[86:89]
	v_mfma_f32_16x16x32_bf16 v[54:57], v[160:163], v[200:203], v[54:57]
	ds_read_b128 v[156:159], v164 offset:34816
	ds_read_b128 v[160:163], v164 offset:35840
	v_sub_f32_e32 v86, v90, v174
	v_sub_f32_e32 v87, v91, v174
	v_sub_f32_e32 v88, v92, v174
	v_sub_f32_e32 v89, v93, v174
	s_waitcnt lgkmcnt(2)
	v_mfma_f32_16x16x32_bf16 v[58:61], v[148:151], v[196:199], v[90:93]
	v_mfma_f32_16x16x32_bf16 v[58:61], v[152:155], v[200:203], v[58:61]
	ds_read_b128 v[148:151], v164 offset:36864
	ds_read_b128 v[152:155], v164 offset:37888
	v_sub_f32_e32 v90, v86, v174
	v_sub_f32_e32 v91, v87, v174
	v_sub_f32_e32 v92, v88, v174
	v_sub_f32_e32 v93, v89, v174
	v_cmp_le_i32_e32 vcc, 0, v108
	s_nop 1
	v_cndmask_b32_e32 v212, v252, v90, vcc
	v_cmp_le_i32_e32 vcc, 0, v110
	s_nop 1
	v_cndmask_b32_e32 v213, v252, v91, vcc
	v_cmp_le_i32_e32 vcc, 0, v111
	s_nop 1
	v_cndmask_b32_e32 v214, v252, v92, vcc
	v_cmp_le_i32_e32 vcc, 0, v177
	s_nop 1
	v_cndmask_b32_e32 v215, v252, v93, vcc
	s_waitcnt lgkmcnt(2)
; __device__ void att_phase(int wv, const Params& p, unsigned char* lds) {
;     ...
;             float mx = sink;
; #pragma unroll
;             for (int cb = 0; cb < 24; ++cb) { const int kb = B - 1 + (cb >> 3); const bool bval = (kb >= sb && kb < se);
; #pragma unroll
;                 for (int j = 0; j < 4; ++j) { const int krel = 16 * cb + 4 * lq + j - 128;
;                     int dist = qrow - krel; dist = dist < 0 ? -dist : dist;
;                     const float v = (bval && dist <= 128) ? sc[cb][j] * 0.125f - slope * (float)dist : -1e30f;
;                     sc[cb][j] = v; mx = fmaxf(mx, v); } }
;             mx = fmaxf(mx, __shfl_xor(mx, 16)); mx = fmaxf(mx, __shfl_xor(mx, 32));
;             float sum = 0.f;
; #pragma unroll
;             for (int cb = 0; cb < 24; ++cb)
; #pragma unroll
;                 for (int j = 0; j < 4; ++j) { const float e = __expf(sc[cb][j] - mx); sc[cb][j] = e; sum += e; }
	v_mfma_f32_16x16x32_bf16 v[62:65], v[156:159], v[196:199], v[86:89]
	v_mfma_f32_16x16x32_bf16 v[62:65], v[160:163], v[200:203], v[62:65]
	s_waitcnt lgkmcnt(0)
	v_mfma_f32_16x16x32_bf16 v[66:69], v[148:151], v[196:199], v[212:215]
	v_mfma_f32_16x16x32_bf16 v[66:69], v[152:155], v[200:203], v[66:69]
	s_waitcnt lgkmcnt(7)
	ds_read_b64_tr_b16 v[216:217], v165 offset:5120
	ds_read_b64_tr_b16 v[218:219], v165 offset:7680
	ds_read_b64_tr_b16 v[220:221], v165 offset:5152
	ds_read_b64_tr_b16 v[222:223], v165 offset:7712
	ds_read_b64_tr_b16 v[224:225], v165 offset:5184
	ds_read_b64_tr_b16 v[226:227], v165 offset:7744
	ds_read_b64_tr_b16 v[228:229], v165 offset:5216
	ds_read_b64_tr_b16 v[230:231], v165 offset:7776
	v_max3_f32 v169, v2, v3, v4
	v_max3_f32 v172, v5, v6, v7
	v_max3_f32 v169, v8, v9, v169
	v_max3_f32 v172, v10, v11, v172
	v_max3_f32 v169, v12, v13, v169
	v_max3_f32 v172, v14, v15, v172
	v_max3_f32 v169, v16, v17, v169
	v_max3_f32 v172, v18, v19, v172
	v_max3_f32 v169, v20, v21, v169
	v_max3_f32 v172, v22, v23, v172
	v_max3_f32 v169, v24, v25, v169
	v_max3_f32 v172, v26, v27, v172
	v_max3_f32 v169, v28, v29, v169
	v_max3_f32 v172, v30, v31, v172
	v_max3_f32 v169, v32, v33, v169
	v_max3_f32 v172, v34, v35, v172
	v_max3_f32 v169, v36, v37, v169
	v_max3_f32 v172, v38, v39, v172
	v_max3_f32 v169, v40, v41, v169
	v_max3_f32 v172, v42, v43, v172
	v_max3_f32 v169, v44, v45, v169
	v_max3_f32 v172, v46, v47, v172
	v_max3_f32 v169, v48, v49, v169
	v_max3_f32 v172, v50, v51, v172
	v_max3_f32 v169, v52, v53, v169
	v_max3_f32 v172, v54, v55, v172
	v_max3_f32 v169, v56, v57, v169
	v_max3_f32 v172, v58, v59, v172
	v_max3_f32 v169, v60, v61, v169
	v_max3_f32 v172, v62, v63, v172
	v_max3_f32 v169, v64, v65, v169
	v_max3_f32 v172, v66, v67, v172
	v_max3_f32 v169, v68, v69, v169
	v_max_f32_e32 v169, v169, v172
	v_mul_f32_e32 v169, 0x3e000000, v169
	v_max_f32_e32 v169, v169, v146
	ds_bpermute_b32 v172, v1, v169
	s_waitcnt lgkmcnt(0)
	v_max_f32_e32 v169, v169, v172
	ds_bpermute_b32 v172, v114, v169
	s_waitcnt lgkmcnt(0)
	v_max_f32_e32 v169, v169, v172
	v_mul_f32_e32 v175, 0xbfb8aa3b, v169
	v_mov_b32_e32 v170, 0
	v_mov_b32_e32 v171, 0
	v_fma_f32 v2, v2, s46, v175
	v_fma_f32 v3, v3, s46, v175
	v_fma_f32 v4, v4, s46, v175
	v_fma_f32 v5, v5, s46, v175
	v_exp_f32_e32 v2, v2
	v_exp_f32_e32 v3, v3
	v_exp_f32_e32 v4, v4
	v_exp_f32_e32 v5, v5
	v_fma_f32 v6, v6, s46, v175
	v_fma_f32 v7, v7, s46, v175
	v_fma_f32 v8, v8, s46, v175
	v_fma_f32 v9, v9, s46, v175
	v_exp_f32_e32 v6, v6
	v_exp_f32_e32 v7, v7
	v_exp_f32_e32 v8, v8
	v_exp_f32_e32 v9, v9
	v_add_f32_e32 v171, v171, v2
	v_add_f32_e32 v170, v170, v3
	v_add_f32_e32 v171, v171, v4
	v_add_f32_e32 v170, v170, v5
	v_fma_f32 v10, v10, s46, v175
	v_fma_f32 v11, v11, s46, v175
	v_fma_f32 v12, v12, s46, v175
	v_fma_f32 v13, v13, s46, v175
	v_exp_f32_e32 v10, v10
	v_exp_f32_e32 v11, v11
	v_exp_f32_e32 v12, v12
	v_exp_f32_e32 v13, v13
	v_add_f32_e32 v171, v171, v6
	v_add_f32_e32 v170, v170, v7
	v_add_f32_e32 v171, v171, v8
	v_add_f32_e32 v170, v170, v9
	v_fma_f32 v14, v14, s46, v175
	v_fma_f32 v15, v15, s46, v175
	v_fma_f32 v16, v16, s46, v175
	v_fma_f32 v17, v17, s46, v175
	v_exp_f32_e32 v14, v14
	v_exp_f32_e32 v15, v15
	v_exp_f32_e32 v16, v16
	v_exp_f32_e32 v17, v17
	v_add_f32_e32 v171, v171, v10
	v_add_f32_e32 v170, v170, v11
	v_add_f32_e32 v171, v171, v12
	v_add_f32_e32 v170, v170, v13
	v_fma_f32 v18, v18, s46, v175
	v_fma_f32 v19, v19, s46, v175
	v_fma_f32 v20, v20, s46, v175
	v_fma_f32 v21, v21, s46, v175
	v_exp_f32_e32 v18, v18
	v_exp_f32_e32 v19, v19
	v_exp_f32_e32 v20, v20
	v_exp_f32_e32 v21, v21
	v_add_f32_e32 v171, v171, v14
	v_add_f32_e32 v170, v170, v15
	v_add_f32_e32 v171, v171, v16
	v_add_f32_e32 v170, v170, v17
	v_fma_f32 v22, v22, s46, v175
	v_fma_f32 v23, v23, s46, v175
	v_fma_f32 v24, v24, s46, v175
	v_fma_f32 v25, v25, s46, v175
	v_exp_f32_e32 v22, v22
	v_exp_f32_e32 v23, v23
	v_exp_f32_e32 v24, v24
	v_exp_f32_e32 v25, v25
	v_add_f32_e32 v171, v171, v18
	v_add_f32_e32 v170, v170, v19
	v_add_f32_e32 v171, v171, v20
	v_add_f32_e32 v170, v170, v21
	v_fma_f32 v26, v26, s46, v175
	v_fma_f32 v27, v27, s46, v175
	v_fma_f32 v28, v28, s46, v175
	v_fma_f32 v29, v29, s46, v175
	v_exp_f32_e32 v26, v26
	v_exp_f32_e32 v27, v27
	v_exp_f32_e32 v28, v28
	v_exp_f32_e32 v29, v29
	v_add_f32_e32 v171, v171, v22
	v_add_f32_e32 v170, v170, v23
	v_add_f32_e32 v171, v171, v24
	v_add_f32_e32 v170, v170, v25
	v_fma_f32 v30, v30, s46, v175
	v_fma_f32 v31, v31, s46, v175
	v_fma_f32 v32, v32, s46, v175
	v_fma_f32 v33, v33, s46, v175
	v_exp_f32_e32 v30, v30
	v_exp_f32_e32 v31, v31
	v_exp_f32_e32 v32, v32
	v_exp_f32_e32 v33, v33
	v_add_f32_e32 v171, v171, v26
	v_add_f32_e32 v170, v170, v27
	v_add_f32_e32 v171, v171, v28
	v_add_f32_e32 v170, v170, v29
	v_fma_f32 v34, v34, s46, v175
	v_fma_f32 v35, v35, s46, v175
	v_fma_f32 v36, v36, s46, v175
	v_fma_f32 v37, v37, s46, v175
	v_exp_f32_e32 v34, v34
	v_exp_f32_e32 v35, v35
	v_exp_f32_e32 v36, v36
	v_exp_f32_e32 v37, v37
	v_add_f32_e32 v171, v171, v30
	v_add_f32_e32 v170, v170, v31
	v_add_f32_e32 v171, v171, v32
	v_add_f32_e32 v170, v170, v33
	v_fma_f32 v38, v38, s46, v175
	v_fma_f32 v39, v39, s46, v175
	v_fma_f32 v40, v40, s46, v175
	v_fma_f32 v41, v41, s46, v175
	v_exp_f32_e32 v38, v38
	v_exp_f32_e32 v39, v39
	v_exp_f32_e32 v40, v40
	v_exp_f32_e32 v41, v41
	v_add_f32_e32 v171, v171, v34
	v_add_f32_e32 v170, v170, v35
	v_add_f32_e32 v171, v171, v36
	v_add_f32_e32 v170, v170, v37
	v_fma_f32 v42, v42, s46, v175
	v_fma_f32 v43, v43, s46, v175
	v_fma_f32 v44, v44, s46, v175
	v_fma_f32 v45, v45, s46, v175
	v_exp_f32_e32 v42, v42
	v_exp_f32_e32 v43, v43
	v_exp_f32_e32 v44, v44
	v_exp_f32_e32 v45, v45
; __device__ __forceinline__ unsigned cvt_pk_bf16_asm(float lo, float hi) { unsigned r; asm volatile("v_cvt_pk_bf16_f32 %0, %1, %2" : "=v"(r) : "v"(lo), "v"(hi)); return r; }
; __device__ __forceinline__ f32x4 mfma16(bf16x8 a, bf16x8 b, f32x4 c) { return __builtin_amdgcn_mfma_f32_16x16x32_bf16(a, b, c, 0, 0, 0); }
; __device__ void att_phase(int wv, const Params& p, unsigned char* lds) {
;     ...
;             for (int cb = 0; cb < 24; ++cb)
; #pragma unroll
;                 for (int j = 0; j < 4; ++j) { const float e = __expf(sc[cb][j] - mx); sc[cb][j] = e; sum += e; }
;             sum += __shfl_xor(sum, 16); sum += __shfl_xor(sum, 32);
;             sum += __expf(sink - mx);
;             const float inv = 1.0f / sum;
;             f32x4 oa[4];
; #pragma unroll
;             for (int db = 0; db < 4; ++db) oa[db] = (f32x4){0, 0, 0, 0};
; #pragma unroll
;             for (int ks = 0; ks < 12; ++ks) {
;                 union { bf16x8 v; unsigned u[4]; } pf;
;                 pf.u[0] = cvt_pk_bf16_asm(sc[2 * ks][0], sc[2 * ks][1]); pf.u[1] = cvt_pk_bf16_asm(sc[2 * ks][2], sc[2 * ks][3]);
;                 pf.u[2] = cvt_pk_bf16_asm(sc[2 * ks + 1][0], sc[2 * ks + 1][1]); pf.u[3] = cvt_pk_bf16_asm(sc[2 * ks + 1][2], sc[2 * ks + 1][3]);
; #pragma unroll
;                 for (int db = 0; db < 4; ++db) {
;                     union { bf16x8 v; u32x2 h2[2]; } vf;
;                     const bf16_t* vp = VTL + (16 * db + lr) * VP + 32 * ks + 4 * lq;
;                     vf.h2[0] = *(const u32x2*)vp; vf.h2[1] = *(const u32x2*)(vp + 16);
;                     oa[db] = mfma16(vf.v, pf.v, oa[db]); } }
	v_add_f32_e32 v171, v171, v38
	v_add_f32_e32 v170, v170, v39
	v_add_f32_e32 v171, v171, v40
	v_add_f32_e32 v170, v170, v41
	v_fma_f32 v46, v46, s46, v175
	v_fma_f32 v47, v47, s46, v175
	v_fma_f32 v48, v48, s46, v175
	v_fma_f32 v49, v49, s46, v175
	v_exp_f32_e32 v46, v46
	v_exp_f32_e32 v47, v47
	v_exp_f32_e32 v48, v48
	v_exp_f32_e32 v49, v49
	v_add_f32_e32 v171, v171, v42
	v_add_f32_e32 v170, v170, v43
	v_add_f32_e32 v171, v171, v44
	v_add_f32_e32 v170, v170, v45
	v_fma_f32 v50, v50, s46, v175
	v_fma_f32 v51, v51, s46, v175
	v_fma_f32 v52, v52, s46, v175
	v_fma_f32 v53, v53, s46, v175
	v_exp_f32_e32 v50, v50
	v_exp_f32_e32 v51, v51
	v_exp_f32_e32 v52, v52
	v_exp_f32_e32 v53, v53
	v_add_f32_e32 v171, v171, v46
	v_add_f32_e32 v170, v170, v47
	v_add_f32_e32 v171, v171, v48
	v_add_f32_e32 v170, v170, v49
	v_fma_f32 v54, v54, s46, v175
	v_fma_f32 v55, v55, s46, v175
	v_fma_f32 v56, v56, s46, v175
	v_fma_f32 v57, v57, s46, v175
	v_exp_f32_e32 v54, v54
	v_exp_f32_e32 v55, v55
	v_exp_f32_e32 v56, v56
	v_exp_f32_e32 v57, v57
	v_add_f32_e32 v171, v171, v50
	v_add_f32_e32 v170, v170, v51
	v_add_f32_e32 v171, v171, v52
	v_add_f32_e32 v170, v170, v53
	v_fma_f32 v58, v58, s46, v175
	v_fma_f32 v59, v59, s46, v175
	v_fma_f32 v60, v60, s46, v175
	v_fma_f32 v61, v61, s46, v175
	v_exp_f32_e32 v58, v58
	v_exp_f32_e32 v59, v59
	v_exp_f32_e32 v60, v60
	v_exp_f32_e32 v61, v61
	v_add_f32_e32 v171, v171, v54
	v_add_f32_e32 v170, v170, v55
	v_add_f32_e32 v171, v171, v56
	v_add_f32_e32 v170, v170, v57
	v_fma_f32 v62, v62, s46, v175
	v_fma_f32 v63, v63, s46, v175
	v_fma_f32 v64, v64, s46, v175
	v_fma_f32 v65, v65, s46, v175
	v_exp_f32_e32 v62, v62
	v_exp_f32_e32 v63, v63
	v_exp_f32_e32 v64, v64
	v_exp_f32_e32 v65, v65
	v_add_f32_e32 v171, v171, v58
	v_add_f32_e32 v170, v170, v59
	v_add_f32_e32 v171, v171, v60
	v_add_f32_e32 v170, v170, v61
	v_fma_f32 v66, v66, s46, v175
	v_fma_f32 v67, v67, s46, v175
	v_fma_f32 v68, v68, s46, v175
	v_fma_f32 v69, v69, s46, v175
	v_exp_f32_e32 v66, v66
	v_exp_f32_e32 v67, v67
	v_exp_f32_e32 v68, v68
	v_exp_f32_e32 v69, v69
	v_add_f32_e32 v171, v171, v62
	v_add_f32_e32 v170, v170, v63
	v_add_f32_e32 v171, v171, v64
	v_add_f32_e32 v170, v170, v65
	v_add_f32_e32 v171, v171, v66
	v_add_f32_e32 v170, v170, v67
	v_add_f32_e32 v171, v171, v68
	v_add_f32_e32 v170, v170, v69
	v_add_f32_e32 v170, v170, v171
	v_cvt_pk_bf16_f32 v2, v2, v3
	v_cvt_pk_bf16_f32 v3, v4, v5
	v_cvt_pk_bf16_f32 v4, v6, v7
	v_cvt_pk_bf16_f32 v5, v8, v9
	v_cvt_pk_bf16_f32 v10, v10, v11
	v_cvt_pk_bf16_f32 v11, v12, v13
	v_cvt_pk_bf16_f32 v12, v14, v15
	v_cvt_pk_bf16_f32 v13, v16, v17
	v_cvt_pk_bf16_f32 v18, v18, v19
	v_cvt_pk_bf16_f32 v19, v20, v21
	v_cvt_pk_bf16_f32 v20, v22, v23
	v_cvt_pk_bf16_f32 v21, v24, v25
	v_cvt_pk_bf16_f32 v26, v26, v27
	v_cvt_pk_bf16_f32 v27, v28, v29
	v_cvt_pk_bf16_f32 v28, v30, v31
	v_cvt_pk_bf16_f32 v29, v32, v33
	v_cvt_pk_bf16_f32 v34, v34, v35
	v_cvt_pk_bf16_f32 v35, v36, v37
	v_cvt_pk_bf16_f32 v36, v38, v39
	v_cvt_pk_bf16_f32 v37, v40, v41
	v_cvt_pk_bf16_f32 v42, v42, v43
	v_cvt_pk_bf16_f32 v43, v44, v45
	v_cvt_pk_bf16_f32 v44, v46, v47
	v_cvt_pk_bf16_f32 v45, v48, v49
	v_cvt_pk_bf16_f32 v50, v50, v51
	v_cvt_pk_bf16_f32 v51, v52, v53
	v_cvt_pk_bf16_f32 v52, v54, v55
	v_cvt_pk_bf16_f32 v53, v56, v57
	v_cvt_pk_bf16_f32 v58, v58, v59
	v_cvt_pk_bf16_f32 v59, v60, v61
	v_cvt_pk_bf16_f32 v60, v62, v63
	v_cvt_pk_bf16_f32 v61, v64, v65
	v_cvt_pk_bf16_f32 v66, v66, v67
	v_cvt_pk_bf16_f32 v67, v68, v69
	v_mov_b32_e32 v68, 0
	v_mov_b32_e32 v69, 0
	ds_bpermute_b32 v172, v1, v170
	v_sub_f32_e32 v173, v146, v169
	v_mul_f32_e32 v173, 0x3fb8aa3b, v173
	v_exp_f32_e32 v173, v173
	s_waitcnt lgkmcnt(0)
	v_add_f32_e32 v170, v170, v172
	ds_bpermute_b32 v172, v114, v170
	s_waitcnt lgkmcnt(7)
	ds_read_b64_tr_b16 v[232:233], v165 offset:10240
	ds_read_b64_tr_b16 v[234:235], v165 offset:12800
	ds_read_b64_tr_b16 v[236:237], v165 offset:10272
	ds_read_b64_tr_b16 v[238:239], v165 offset:12832
	ds_read_b64_tr_b16 v[240:241], v165 offset:10304
	ds_read_b64_tr_b16 v[242:243], v165 offset:12864
	ds_read_b64_tr_b16 v[244:245], v165 offset:10336
	ds_read_b64_tr_b16 v[246:247], v165 offset:12896
	s_waitcnt lgkmcnt(8)
	v_mfma_f32_16x16x32_bf16 v[70:73], v[216:219], v[2:5], 0
	v_mfma_f32_16x16x32_bf16 v[74:77], v[220:223], v[2:5], 0
	v_mfma_f32_16x16x32_bf16 v[78:81], v[224:227], v[2:5], 0
	v_mfma_f32_16x16x32_bf16 v[82:85], v[228:231], v[2:5], 0
	v_add_f32_e32 v170, v170, v172
	v_add_f32_e32 v170, v170, v173
	v_rcp_f32_e32 v147, v170
	s_nop 0
	v_fma_f32 v179, -v170, v147, 1.0
	v_fmac_f32_e32 v147, v179, v147
	s_waitcnt lgkmcnt(7)
	ds_read_b64_tr_b16 v[216:217], v165 offset:15360
	ds_read_b64_tr_b16 v[218:219], v165 offset:17920
	ds_read_b64_tr_b16 v[220:221], v165 offset:15392
	ds_read_b64_tr_b16 v[222:223], v165 offset:17952
	ds_read_b64_tr_b16 v[224:225], v165 offset:15424
	ds_read_b64_tr_b16 v[226:227], v165 offset:17984
	ds_read_b64_tr_b16 v[228:229], v165 offset:15456
	ds_read_b64_tr_b16 v[230:231], v165 offset:18016
	s_waitcnt lgkmcnt(8)
	v_mfma_f32_16x16x32_bf16 v[70:73], v[232:235], v[10:13], v[70:73]
	v_mfma_f32_16x16x32_bf16 v[74:77], v[236:239], v[10:13], v[74:77]
	v_mfma_f32_16x16x32_bf16 v[78:81], v[240:243], v[10:13], v[78:81]
	v_mfma_f32_16x16x32_bf16 v[82:85], v[244:247], v[10:13], v[82:85]
	s_waitcnt lgkmcnt(7)
	ds_read_b64_tr_b16 v[232:233], v165 offset:20480
	ds_read_b64_tr_b16 v[234:235], v165 offset:23040
	ds_read_b64_tr_b16 v[236:237], v165 offset:20512
	ds_read_b64_tr_b16 v[238:239], v165 offset:23072
	ds_read_b64_tr_b16 v[240:241], v165 offset:20544
	ds_read_b64_tr_b16 v[242:243], v165 offset:23104
	ds_read_b64_tr_b16 v[244:245], v165 offset:20576
	ds_read_b64_tr_b16 v[246:247], v165 offset:23136
	s_waitcnt lgkmcnt(8)
; __device__ __forceinline__ unsigned cvt_pk_bf16_asm(float lo, float hi) { unsigned r; asm volatile("v_cvt_pk_bf16_f32 %0, %1, %2" : "=v"(r) : "v"(lo), "v"(hi)); return r; }
; __device__ __forceinline__ f32x4 mfma16(bf16x8 a, bf16x8 b, f32x4 c) { return __builtin_amdgcn_mfma_f32_16x16x32_bf16(a, b, c, 0, 0, 0); }
; __device__ void att_phase(int wv, const Params& p, unsigned char* lds) {
;     ...
;             for (int cb = 0; cb < 24; ++cb) { f32x4 a = {0, 0, 0, 0};
; #pragma unroll
;                 for (int kk = 0; kk < 2; ++kk) { const bf16x8 kf = *(const bf16x8*)(KL + (16 * cb + lr) * KP + 32 * kk + 8 * lq); a = mfma16(kf, qf[kk], a); }
;                 sc[cb] = a; }
;             float mx = sink;
; #pragma unroll
;             for (int cb = 0; cb < 24; ++cb) { const int kb = B - 1 + (cb >> 3); const bool bval = (kb >= sb && kb < se);
; #pragma unroll
;                 for (int j = 0; j < 4; ++j) { const int krel = 16 * cb + 4 * lq + j - 128;
;                     int dist = qrow - krel; dist = dist < 0 ? -dist : dist;
;                     const float v = (bval && dist <= 128) ? sc[cb][j] * 0.125f - slope * (float)dist : -1e30f;
;     ...
; #pragma unroll
;                 for (int db = 0; db < 4; ++db) {
;                     union { bf16x8 v; u32x2 h2[2]; } vf;
;                     const bf16_t* vp = VTL + (16 * db + lr) * VP + 32 * ks + 4 * lq;
;                     vf.h2[0] = *(const u32x2*)vp; vf.h2[1] = *(const u32x2*)(vp + 16);
;                     oa[db] = mfma16(vf.v, pf.v, oa[db]); } }
; #pragma unroll
;             for (int db = 0; db < 4; ++db) { const f32x4 o = oa[db] * inv; u32x2 wv; wv.x = cvt_pk_bf16_asm(o[0], o[1]); wv.y = cvt_pk_bf16_asm(o[2], o[3]);
;                 *(u32x2*)(qkv + tokq * 1536 + 64 * h + 16 * db + 4 * lq) = wv; }
	v_mfma_f32_16x16x32_bf16 v[70:73], v[216:219], v[18:21], v[70:73]
	v_mfma_f32_16x16x32_bf16 v[74:77], v[220:223], v[18:21], v[74:77]
	v_mfma_f32_16x16x32_bf16 v[78:81], v[224:227], v[18:21], v[78:81]
	v_mfma_f32_16x16x32_bf16 v[82:85], v[228:231], v[18:21], v[82:85]
	s_waitcnt lgkmcnt(7)
	ds_read_b64_tr_b16 v[216:217], v165 offset:25600
	ds_read_b64_tr_b16 v[218:219], v165 offset:28160
	ds_read_b64_tr_b16 v[220:221], v165 offset:25632
	ds_read_b64_tr_b16 v[222:223], v165 offset:28192
	ds_read_b64_tr_b16 v[224:225], v165 offset:25664
	ds_read_b64_tr_b16 v[226:227], v165 offset:28224
	ds_read_b64_tr_b16 v[228:229], v165 offset:25696
	ds_read_b64_tr_b16 v[230:231], v165 offset:28256
	s_waitcnt lgkmcnt(8)
	v_mfma_f32_16x16x32_bf16 v[70:73], v[232:235], v[26:29], v[70:73]
	v_mfma_f32_16x16x32_bf16 v[74:77], v[236:239], v[26:29], v[74:77]
	v_mfma_f32_16x16x32_bf16 v[78:81], v[240:243], v[26:29], v[78:81]
	v_mfma_f32_16x16x32_bf16 v[82:85], v[244:247], v[26:29], v[82:85]
	s_waitcnt lgkmcnt(7)
	ds_read_b64_tr_b16 v[232:233], v165 offset:30720
	ds_read_b64_tr_b16 v[234:235], v165 offset:33280
	ds_read_b64_tr_b16 v[236:237], v165 offset:30752
	ds_read_b64_tr_b16 v[238:239], v165 offset:33312
	ds_read_b64_tr_b16 v[240:241], v165 offset:30784
	ds_read_b64_tr_b16 v[242:243], v165 offset:33344
	ds_read_b64_tr_b16 v[244:245], v165 offset:30816
	ds_read_b64_tr_b16 v[246:247], v165 offset:33376
	s_waitcnt lgkmcnt(8)
	v_mfma_f32_16x16x32_bf16 v[70:73], v[216:219], v[34:37], v[70:73]
	v_mfma_f32_16x16x32_bf16 v[74:77], v[220:223], v[34:37], v[74:77]
	v_mfma_f32_16x16x32_bf16 v[78:81], v[224:227], v[34:37], v[78:81]
	v_mfma_f32_16x16x32_bf16 v[82:85], v[228:231], v[34:37], v[82:85]
	s_waitcnt lgkmcnt(7)
	ds_read_b64_tr_b16 v[216:217], v165 offset:35840
	ds_read_b64_tr_b16 v[218:219], v165 offset:38400
	ds_read_b64_tr_b16 v[220:221], v165 offset:35872
	ds_read_b64_tr_b16 v[222:223], v165 offset:38432
	ds_read_b64_tr_b16 v[224:225], v165 offset:35904
	ds_read_b64_tr_b16 v[226:227], v165 offset:38464
	ds_read_b64_tr_b16 v[228:229], v165 offset:35936
	ds_read_b64_tr_b16 v[230:231], v165 offset:38496
	s_waitcnt lgkmcnt(8)
	v_mfma_f32_16x16x32_bf16 v[70:73], v[232:235], v[42:45], v[70:73]
	v_mfma_f32_16x16x32_bf16 v[74:77], v[236:239], v[42:45], v[74:77]
	v_mfma_f32_16x16x32_bf16 v[78:81], v[240:243], v[42:45], v[78:81]
	v_mfma_f32_16x16x32_bf16 v[82:85], v[244:247], v[42:45], v[82:85]
	s_waitcnt lgkmcnt(7)
	ds_read_b64_tr_b16 v[232:233], v165 offset:40960
	ds_read_b64_tr_b16 v[234:235], v165 offset:43520
	ds_read_b64_tr_b16 v[236:237], v165 offset:40992
	ds_read_b64_tr_b16 v[238:239], v165 offset:43552
	ds_read_b64_tr_b16 v[240:241], v165 offset:41024
	ds_read_b64_tr_b16 v[242:243], v165 offset:43584
	ds_read_b64_tr_b16 v[244:245], v165 offset:41056
	ds_read_b64_tr_b16 v[246:247], v165 offset:43616
	s_waitcnt lgkmcnt(8)
	v_mfma_f32_16x16x32_bf16 v[70:73], v[216:219], v[50:53], v[70:73]
	v_mfma_f32_16x16x32_bf16 v[74:77], v[220:223], v[50:53], v[74:77]
	v_mfma_f32_16x16x32_bf16 v[78:81], v[224:227], v[50:53], v[78:81]
	v_mfma_f32_16x16x32_bf16 v[82:85], v[228:231], v[50:53], v[82:85]
	s_waitcnt lgkmcnt(7)
	ds_read_b64_tr_b16 v[216:217], v165 offset:46080
	ds_read_b64_tr_b16 v[218:219], v165 offset:46080
	ds_read_b64_tr_b16 v[220:221], v165 offset:46112
	ds_read_b64_tr_b16 v[222:223], v165 offset:46112
	ds_read_b64_tr_b16 v[224:225], v165 offset:46144
	ds_read_b64_tr_b16 v[226:227], v165 offset:46144
	ds_read_b64_tr_b16 v[228:229], v165 offset:46176
	ds_read_b64_tr_b16 v[230:231], v165 offset:46176
	s_waitcnt lgkmcnt(8)
	v_mfma_f32_16x16x32_bf16 v[70:73], v[232:235], v[58:61], v[70:73]
	v_mfma_f32_16x16x32_bf16 v[74:77], v[236:239], v[58:61], v[74:77]
	v_mfma_f32_16x16x32_bf16 v[78:81], v[240:243], v[58:61], v[78:81]
	v_mfma_f32_16x16x32_bf16 v[82:85], v[244:247], v[58:61], v[82:85]
	s_waitcnt lgkmcnt(0)
	v_mfma_f32_16x16x32_bf16 v[70:73], v[216:219], v[66:69], v[70:73]
	v_mfma_f32_16x16x32_bf16 v[74:77], v[220:223], v[66:69], v[74:77]
	v_mfma_f32_16x16x32_bf16 v[78:81], v[224:227], v[66:69], v[78:81]
	v_mfma_f32_16x16x32_bf16 v[82:85], v[228:231], v[66:69], v[82:85]
	s_nop 7
	s_nop 1
	v_mul_f32_e32 v70, v70, v147
	v_mul_f32_e32 v71, v71, v147
	v_mul_f32_e32 v72, v72, v147
	v_mul_f32_e32 v73, v73, v147
	v_mul_f32_e32 v74, v74, v147
	v_mul_f32_e32 v75, v75, v147
	v_mul_f32_e32 v76, v76, v147
	v_mul_f32_e32 v77, v77, v147
	v_mul_f32_e32 v78, v78, v147
	v_mul_f32_e32 v79, v79, v147
	v_mul_f32_e32 v80, v80, v147
	v_mul_f32_e32 v81, v81, v147
	v_mul_f32_e32 v82, v82, v147
	v_mul_f32_e32 v83, v83, v147
	v_mul_f32_e32 v84, v84, v147
	v_mul_f32_e32 v85, v85, v147
	v_cvt_pk_bf16_f32 v70, v70, v71
	v_cvt_pk_bf16_f32 v71, v72, v73
	v_cvt_pk_bf16_f32 v74, v74, v75
	v_cvt_pk_bf16_f32 v75, v76, v77
	v_cvt_pk_bf16_f32 v78, v78, v79
	v_cvt_pk_bf16_f32 v79, v80, v81
	v_cvt_pk_bf16_f32 v82, v82, v83
	v_cvt_pk_bf16_f32 v83, v84, v85
	global_store_dwordx2 v[248:249], v[70:71], off offset:-64
	global_store_dwordx2 v[248:249], v[74:75], off offset:-32
	global_store_dwordx2 v[248:249], v[78:79], off
	global_store_dwordx2 v[248:249], v[82:83], off offset:32
	v_lshl_add_u64 v[248:249], v[248:249], 0, s[48:49]
	v_sub_f32_e32 v86, v94, v176
	v_sub_f32_e32 v87, v95, v176
	v_sub_f32_e32 v88, v96, v176
	v_sub_f32_e32 v89, v97, v176
	v_cmp_ge_i32_e32 vcc, 0, v108
	s_nop 1
	v_cndmask_b32_e32 v212, v252, v86, vcc
	v_cmp_ge_i32_e32 vcc, 0, v110
	s_nop 1
	v_cndmask_b32_e32 v213, v252, v87, vcc
	v_cmp_ge_i32_e32 vcc, 0, v111
	s_nop 1
	v_cndmask_b32_e32 v214, v252, v88, vcc
	v_cmp_ge_i32_e32 vcc, 0, v177
	s_nop 1
	v_cndmask_b32_e32 v215, v252, v89, vcc
	ds_read_b128 v[148:151], v164 offset:6144
	ds_read_b128 v[152:155], v164 offset:7168
	ds_read_b128 v[156:159], v164 offset:8192
	ds_read_b128 v[160:163], v164 offset:9216
	v_add_f32_e32 v90, v86, v174
	v_add_f32_e32 v91, v87, v174
	v_add_f32_e32 v92, v88, v174
	v_add_f32_e32 v93, v89, v174
	s_waitcnt lgkmcnt(2)
; __device__ __forceinline__ f32x4 mfma16(bf16x8 a, bf16x8 b, f32x4 c) { return __builtin_amdgcn_mfma_f32_16x16x32_bf16(a, b, c, 0, 0, 0); }
; __device__ void att_phase(int wv, const Params& p, unsigned char* lds) {
;     ...
;             for (int cb = 0; cb < 24; ++cb) { f32x4 a = {0, 0, 0, 0};
; #pragma unroll
;                 for (int kk = 0; kk < 2; ++kk) { const bf16x8 kf = *(const bf16x8*)(KL + (16 * cb + lr) * KP + 32 * kk + 8 * lq); a = mfma16(kf, qf[kk], a); }
;                 sc[cb] = a; }
;             float mx = sink;
; #pragma unroll
;             for (int cb = 0; cb < 24; ++cb) { const int kb = B - 1 + (cb >> 3); const bool bval = (kb >= sb && kb < se);
; #pragma unroll
;                 for (int j = 0; j < 4; ++j) { const int krel = 16 * cb + 4 * lq + j - 128;
;                     int dist = qrow - krel; dist = dist < 0 ? -dist : dist;
;                     const float v = (bval && dist <= 128) ? sc[cb][j] * 0.125f - slope * (float)dist : -1e30f;
	v_mfma_f32_16x16x32_bf16 v[2:5], v[148:151], v[204:207], v[212:215]
	v_mfma_f32_16x16x32_bf16 v[2:5], v[152:155], v[208:211], v[2:5]
	ds_read_b128 v[148:151], v164 offset:10240
	ds_read_b128 v[152:155], v164 offset:11264
	v_add_f32_e32 v86, v90, v174
	v_add_f32_e32 v87, v91, v174
	v_add_f32_e32 v88, v92, v174
	v_add_f32_e32 v89, v93, v174
	s_waitcnt lgkmcnt(2)
	v_mfma_f32_16x16x32_bf16 v[6:9], v[156:159], v[204:207], v[90:93]
	v_mfma_f32_16x16x32_bf16 v[6:9], v[160:163], v[208:211], v[6:9]
	ds_read_b128 v[156:159], v164 offset:12288
	ds_read_b128 v[160:163], v164 offset:13312
	v_add_f32_e32 v90, v86, v174
	v_add_f32_e32 v91, v87, v174
	v_add_f32_e32 v92, v88, v174
	v_add_f32_e32 v93, v89, v174
	s_waitcnt lgkmcnt(2)
	v_mfma_f32_16x16x32_bf16 v[10:13], v[148:151], v[204:207], v[86:89]
	v_mfma_f32_16x16x32_bf16 v[10:13], v[152:155], v[208:211], v[10:13]
	ds_read_b128 v[148:151], v164 offset:14336
	ds_read_b128 v[152:155], v164 offset:15360
	v_add_f32_e32 v86, v90, v174
	v_add_f32_e32 v87, v91, v174
	v_add_f32_e32 v88, v92, v174
	v_add_f32_e32 v89, v93, v174
	s_waitcnt lgkmcnt(2)
	v_mfma_f32_16x16x32_bf16 v[14:17], v[156:159], v[204:207], v[90:93]
	v_mfma_f32_16x16x32_bf16 v[14:17], v[160:163], v[208:211], v[14:17]
	ds_read_b128 v[156:159], v164 offset:16384
	ds_read_b128 v[160:163], v164 offset:17408
	v_add_f32_e32 v90, v86, v174
	v_add_f32_e32 v91, v87, v174
	v_add_f32_e32 v92, v88, v174
	v_add_f32_e32 v93, v89, v174
	s_waitcnt lgkmcnt(2)
	v_mfma_f32_16x16x32_bf16 v[18:21], v[148:151], v[204:207], v[86:89]
	v_mfma_f32_16x16x32_bf16 v[18:21], v[152:155], v[208:211], v[18:21]
	ds_read_b128 v[148:151], v164 offset:18432
	ds_read_b128 v[152:155], v164 offset:19456
	v_add_f32_e32 v86, v90, v174
	v_add_f32_e32 v87, v91, v174
	v_add_f32_e32 v88, v92, v174
	v_add_f32_e32 v89, v93, v174
	s_waitcnt lgkmcnt(2)
	v_mfma_f32_16x16x32_bf16 v[22:25], v[156:159], v[204:207], v[90:93]
	v_mfma_f32_16x16x32_bf16 v[22:25], v[160:163], v[208:211], v[22:25]
	ds_read_b128 v[156:159], v164 offset:20480
	ds_read_b128 v[160:163], v164 offset:21504
	v_add_f32_e32 v90, v86, v174
	v_add_f32_e32 v91, v87, v174
	v_add_f32_e32 v92, v88, v174
	v_add_f32_e32 v93, v89, v174
	s_waitcnt lgkmcnt(2)
	v_mfma_f32_16x16x32_bf16 v[26:29], v[148:151], v[204:207], v[86:89]
	v_mfma_f32_16x16x32_bf16 v[26:29], v[152:155], v[208:211], v[26:29]
	ds_read_b128 v[148:151], v164 offset:22528
	ds_read_b128 v[152:155], v164 offset:23552
	s_waitcnt lgkmcnt(2)
	v_mfma_f32_16x16x32_bf16 v[30:33], v[156:159], v[204:207], v[90:93]
	v_mfma_f32_16x16x32_bf16 v[30:33], v[160:163], v[208:211], v[30:33]
	ds_read_b128 v[156:159], v164 offset:24576
	ds_read_b128 v[160:163], v164 offset:25600
	v_sub_f32_e64 v86, -v94, v174
	v_sub_f32_e64 v87, -v95, v174
	v_sub_f32_e64 v88, -v96, v174
	v_sub_f32_e64 v89, -v97, v174
	s_waitcnt lgkmcnt(2)
	v_mfma_f32_16x16x32_bf16 v[34:37], v[148:151], v[204:207], v[98:101]
	v_mfma_f32_16x16x32_bf16 v[34:37], v[152:155], v[208:211], v[34:37]
	ds_read_b128 v[148:151], v164 offset:26624
	ds_read_b128 v[152:155], v164 offset:27648
	v_sub_f32_e32 v90, v86, v174
	v_sub_f32_e32 v91, v87, v174
	v_sub_f32_e32 v92, v88, v174
	v_sub_f32_e32 v93, v89, v174
	s_waitcnt lgkmcnt(2)
	v_mfma_f32_16x16x32_bf16 v[38:41], v[156:159], v[204:207], v[86:89]
	v_mfma_f32_16x16x32_bf16 v[38:41], v[160:163], v[208:211], v[38:41]
	ds_read_b128 v[156:159], v164 offset:28672
	ds_read_b128 v[160:163], v164 offset:29696
	v_sub_f32_e32 v86, v90, v174
	v_sub_f32_e32 v87, v91, v174
	v_sub_f32_e32 v88, v92, v174
	v_sub_f32_e32 v89, v93, v174
	s_waitcnt lgkmcnt(2)
	v_mfma_f32_16x16x32_bf16 v[42:45], v[148:151], v[204:207], v[90:93]
	v_mfma_f32_16x16x32_bf16 v[42:45], v[152:155], v[208:211], v[42:45]
	ds_read_b128 v[148:151], v164 offset:30720
	ds_read_b128 v[152:155], v164 offset:31744
	v_sub_f32_e32 v90, v86, v174
	v_sub_f32_e32 v91, v87, v174
	v_sub_f32_e32 v92, v88, v174
	v_sub_f32_e32 v93, v89, v174
	s_waitcnt lgkmcnt(2)
	v_mfma_f32_16x16x32_bf16 v[46:49], v[156:159], v[204:207], v[86:89]
	v_mfma_f32_16x16x32_bf16 v[46:49], v[160:163], v[208:211], v[46:49]
	ds_read_b128 v[156:159], v164 offset:32768
	ds_read_b128 v[160:163], v164 offset:33792
	v_sub_f32_e32 v86, v90, v174
	v_sub_f32_e32 v87, v91, v174
	v_sub_f32_e32 v88, v92, v174
	v_sub_f32_e32 v89, v93, v174
	s_waitcnt lgkmcnt(2)
	v_mfma_f32_16x16x32_bf16 v[50:53], v[148:151], v[204:207], v[90:93]
	v_mfma_f32_16x16x32_bf16 v[50:53], v[152:155], v[208:211], v[50:53]
	ds_read_b128 v[148:151], v164 offset:34816
	ds_read_b128 v[152:155], v164 offset:35840
	v_sub_f32_e32 v90, v86, v174
	v_sub_f32_e32 v91, v87, v174
	v_sub_f32_e32 v92, v88, v174
	v_sub_f32_e32 v93, v89, v174
	s_waitcnt lgkmcnt(2)
	v_mfma_f32_16x16x32_bf16 v[54:57], v[156:159], v[204:207], v[86:89]
	v_mfma_f32_16x16x32_bf16 v[54:57], v[160:163], v[208:211], v[54:57]
	ds_read_b128 v[156:159], v164 offset:36864
	ds_read_b128 v[160:163], v164 offset:37888
	v_sub_f32_e32 v86, v90, v174
	v_sub_f32_e32 v87, v91, v174
	v_sub_f32_e32 v88, v92, v174
	v_sub_f32_e32 v89, v93, v174
	s_waitcnt lgkmcnt(2)
	v_mfma_f32_16x16x32_bf16 v[58:61], v[148:151], v[204:207], v[90:93]
	v_mfma_f32_16x16x32_bf16 v[58:61], v[152:155], v[208:211], v[58:61]
	ds_read_b128 v[148:151], v164 offset:38912
	ds_read_b128 v[152:155], v164 offset:39936
	v_sub_f32_e32 v90, v86, v174
	v_sub_f32_e32 v91, v87, v174
	v_sub_f32_e32 v92, v88, v174
	v_sub_f32_e32 v93, v89, v174
	v_cmp_le_i32_e32 vcc, 0, v108
	s_nop 1
	v_cndmask_b32_e32 v212, v252, v90, vcc
	v_cmp_le_i32_e32 vcc, 0, v110
	s_nop 1
	v_cndmask_b32_e32 v213, v252, v91, vcc
	v_cmp_le_i32_e32 vcc, 0, v111
	s_nop 1
	v_cndmask_b32_e32 v214, v252, v92, vcc
	v_cmp_le_i32_e32 vcc, 0, v177
	s_nop 1
	v_cndmask_b32_e32 v215, v252, v93, vcc
	s_waitcnt lgkmcnt(2)
; __device__ __forceinline__ f32x4 mfma16(bf16x8 a, bf16x8 b, f32x4 c) { return __builtin_amdgcn_mfma_f32_16x16x32_bf16(a, b, c, 0, 0, 0); }
; __device__ void att_phase(int wv, const Params& p, unsigned char* lds) {
;     ...
;             for (int cb = 0; cb < 24; ++cb) { f32x4 a = {0, 0, 0, 0};
; #pragma unroll
;                 for (int kk = 0; kk < 2; ++kk) { const bf16x8 kf = *(const bf16x8*)(KL + (16 * cb + lr) * KP + 32 * kk + 8 * lq); a = mfma16(kf, qf[kk], a); }
;                 sc[cb] = a; }
;             float mx = sink;
; #pragma unroll
;             for (int cb = 0; cb < 24; ++cb) { const int kb = B - 1 + (cb >> 3); const bool bval = (kb >= sb && kb < se);
; #pragma unroll
;                 for (int j = 0; j < 4; ++j) { const int krel = 16 * cb + 4 * lq + j - 128;
;                     int dist = qrow - krel; dist = dist < 0 ? -dist : dist;
;                     const float v = (bval && dist <= 128) ? sc[cb][j] * 0.125f - slope * (float)dist : -1e30f;
;                     sc[cb][j] = v; mx = fmaxf(mx, v); } }
;             mx = fmaxf(mx, __shfl_xor(mx, 16)); mx = fmaxf(mx, __shfl_xor(mx, 32));
;             float sum = 0.f;
; #pragma unroll
;             for (int cb = 0; cb < 24; ++cb)
; #pragma unroll
;                 for (int j = 0; j < 4; ++j) { const float e = __expf(sc[cb][j] - mx); sc[cb][j] = e; sum += e; }
	v_mfma_f32_16x16x32_bf16 v[62:65], v[156:159], v[204:207], v[86:89]
	v_mfma_f32_16x16x32_bf16 v[62:65], v[160:163], v[208:211], v[62:65]
	s_waitcnt lgkmcnt(0)
	v_mfma_f32_16x16x32_bf16 v[66:69], v[148:151], v[204:207], v[212:215]
	v_mfma_f32_16x16x32_bf16 v[66:69], v[152:155], v[208:211], v[66:69]
	s_waitcnt lgkmcnt(7)
	ds_read_b64_tr_b16 v[216:217], v165 offset:7680
	ds_read_b64_tr_b16 v[218:219], v165 offset:10240
	ds_read_b64_tr_b16 v[220:221], v165 offset:7712
	ds_read_b64_tr_b16 v[222:223], v165 offset:10272
	ds_read_b64_tr_b16 v[224:225], v165 offset:7744
	ds_read_b64_tr_b16 v[226:227], v165 offset:10304
	ds_read_b64_tr_b16 v[228:229], v165 offset:7776
	ds_read_b64_tr_b16 v[230:231], v165 offset:10336
	v_max3_f32 v169, v2, v3, v4
	v_max3_f32 v172, v5, v6, v7
	v_max3_f32 v169, v8, v9, v169
	v_max3_f32 v172, v10, v11, v172
	v_max3_f32 v169, v12, v13, v169
	v_max3_f32 v172, v14, v15, v172
	v_max3_f32 v169, v16, v17, v169
	v_max3_f32 v172, v18, v19, v172
	v_max3_f32 v169, v20, v21, v169
	v_max3_f32 v172, v22, v23, v172
	v_max3_f32 v169, v24, v25, v169
	v_max3_f32 v172, v26, v27, v172
	v_max3_f32 v169, v28, v29, v169
	v_max3_f32 v172, v30, v31, v172
	v_max3_f32 v169, v32, v33, v169
	v_max3_f32 v172, v34, v35, v172
	v_max3_f32 v169, v36, v37, v169
	v_max3_f32 v172, v38, v39, v172
	v_max3_f32 v169, v40, v41, v169
	v_max3_f32 v172, v42, v43, v172
	v_max3_f32 v169, v44, v45, v169
	v_max3_f32 v172, v46, v47, v172
	v_max3_f32 v169, v48, v49, v169
	v_max3_f32 v172, v50, v51, v172
	v_max3_f32 v169, v52, v53, v169
	v_max3_f32 v172, v54, v55, v172
	v_max3_f32 v169, v56, v57, v169
	v_max3_f32 v172, v58, v59, v172
	v_max3_f32 v169, v60, v61, v169
	v_max3_f32 v172, v62, v63, v172
	v_max3_f32 v169, v64, v65, v169
	v_max3_f32 v172, v66, v67, v172
	v_max3_f32 v169, v68, v69, v169
	v_max_f32_e32 v169, v169, v172
	v_mul_f32_e32 v169, 0x3e000000, v169
	v_max_f32_e32 v169, v169, v146
	ds_bpermute_b32 v172, v1, v169
	s_waitcnt lgkmcnt(0)
	v_max_f32_e32 v169, v169, v172
	ds_bpermute_b32 v172, v114, v169
	s_waitcnt lgkmcnt(0)
	v_max_f32_e32 v169, v169, v172
	v_mul_f32_e32 v175, 0xbfb8aa3b, v169
	v_mov_b32_e32 v170, 0
	v_mov_b32_e32 v171, 0
	v_fma_f32 v2, v2, s46, v175
	v_fma_f32 v3, v3, s46, v175
	v_fma_f32 v4, v4, s46, v175
	v_fma_f32 v5, v5, s46, v175
	v_exp_f32_e32 v2, v2
	v_exp_f32_e32 v3, v3
	v_exp_f32_e32 v4, v4
	v_exp_f32_e32 v5, v5
	v_fma_f32 v6, v6, s46, v175
	v_fma_f32 v7, v7, s46, v175
	v_fma_f32 v8, v8, s46, v175
	v_fma_f32 v9, v9, s46, v175
	v_exp_f32_e32 v6, v6
	v_exp_f32_e32 v7, v7
	v_exp_f32_e32 v8, v8
	v_exp_f32_e32 v9, v9
	v_add_f32_e32 v171, v171, v2
	v_add_f32_e32 v170, v170, v3
	v_add_f32_e32 v171, v171, v4
	v_add_f32_e32 v170, v170, v5
	v_fma_f32 v10, v10, s46, v175
	v_fma_f32 v11, v11, s46, v175
	v_fma_f32 v12, v12, s46, v175
	v_fma_f32 v13, v13, s46, v175
	v_exp_f32_e32 v10, v10
	v_exp_f32_e32 v11, v11
	v_exp_f32_e32 v12, v12
	v_exp_f32_e32 v13, v13
	v_add_f32_e32 v171, v171, v6
	v_add_f32_e32 v170, v170, v7
	v_add_f32_e32 v171, v171, v8
	v_add_f32_e32 v170, v170, v9
	v_fma_f32 v14, v14, s46, v175
	v_fma_f32 v15, v15, s46, v175
	v_fma_f32 v16, v16, s46, v175
	v_fma_f32 v17, v17, s46, v175
	v_exp_f32_e32 v14, v14
	v_exp_f32_e32 v15, v15
	v_exp_f32_e32 v16, v16
	v_exp_f32_e32 v17, v17
	v_add_f32_e32 v171, v171, v10
	v_add_f32_e32 v170, v170, v11
	v_add_f32_e32 v171, v171, v12
	v_add_f32_e32 v170, v170, v13
	v_fma_f32 v18, v18, s46, v175
	v_fma_f32 v19, v19, s46, v175
	v_fma_f32 v20, v20, s46, v175
	v_fma_f32 v21, v21, s46, v175
	v_exp_f32_e32 v18, v18
	v_exp_f32_e32 v19, v19
	v_exp_f32_e32 v20, v20
	v_exp_f32_e32 v21, v21
	v_add_f32_e32 v171, v171, v14
	v_add_f32_e32 v170, v170, v15
	v_add_f32_e32 v171, v171, v16
	v_add_f32_e32 v170, v170, v17
	v_fma_f32 v22, v22, s46, v175
	v_fma_f32 v23, v23, s46, v175
	v_fma_f32 v24, v24, s46, v175
	v_fma_f32 v25, v25, s46, v175
	v_exp_f32_e32 v22, v22
	v_exp_f32_e32 v23, v23
	v_exp_f32_e32 v24, v24
	v_exp_f32_e32 v25, v25
	v_add_f32_e32 v171, v171, v18
	v_add_f32_e32 v170, v170, v19
	v_add_f32_e32 v171, v171, v20
	v_add_f32_e32 v170, v170, v21
	v_fma_f32 v26, v26, s46, v175
	v_fma_f32 v27, v27, s46, v175
	v_fma_f32 v28, v28, s46, v175
	v_fma_f32 v29, v29, s46, v175
	v_exp_f32_e32 v26, v26
	v_exp_f32_e32 v27, v27
	v_exp_f32_e32 v28, v28
	v_exp_f32_e32 v29, v29
	v_add_f32_e32 v171, v171, v22
	v_add_f32_e32 v170, v170, v23
	v_add_f32_e32 v171, v171, v24
	v_add_f32_e32 v170, v170, v25
	v_fma_f32 v30, v30, s46, v175
	v_fma_f32 v31, v31, s46, v175
	v_fma_f32 v32, v32, s46, v175
	v_fma_f32 v33, v33, s46, v175
	v_exp_f32_e32 v30, v30
	v_exp_f32_e32 v31, v31
	v_exp_f32_e32 v32, v32
	v_exp_f32_e32 v33, v33
	v_add_f32_e32 v171, v171, v26
	v_add_f32_e32 v170, v170, v27
	v_add_f32_e32 v171, v171, v28
	v_add_f32_e32 v170, v170, v29
	v_fma_f32 v34, v34, s46, v175
	v_fma_f32 v35, v35, s46, v175
	v_fma_f32 v36, v36, s46, v175
	v_fma_f32 v37, v37, s46, v175
	v_exp_f32_e32 v34, v34
	v_exp_f32_e32 v35, v35
	v_exp_f32_e32 v36, v36
	v_exp_f32_e32 v37, v37
	v_add_f32_e32 v171, v171, v30
	v_add_f32_e32 v170, v170, v31
	v_add_f32_e32 v171, v171, v32
	v_add_f32_e32 v170, v170, v33
	v_fma_f32 v38, v38, s46, v175
	v_fma_f32 v39, v39, s46, v175
	v_fma_f32 v40, v40, s46, v175
	v_fma_f32 v41, v41, s46, v175
	v_exp_f32_e32 v38, v38
	v_exp_f32_e32 v39, v39
	v_exp_f32_e32 v40, v40
	v_exp_f32_e32 v41, v41
	v_add_f32_e32 v171, v171, v34
	v_add_f32_e32 v170, v170, v35
	v_add_f32_e32 v171, v171, v36
	v_add_f32_e32 v170, v170, v37
	v_fma_f32 v42, v42, s46, v175
	v_fma_f32 v43, v43, s46, v175
	v_fma_f32 v44, v44, s46, v175
	v_fma_f32 v45, v45, s46, v175
	v_exp_f32_e32 v42, v42
	v_exp_f32_e32 v43, v43
	v_exp_f32_e32 v44, v44
; __device__ __forceinline__ unsigned cvt_pk_bf16_asm(float lo, float hi) { unsigned r; asm volatile("v_cvt_pk_bf16_f32 %0, %1, %2" : "=v"(r) : "v"(lo), "v"(hi)); return r; }
; __device__ __forceinline__ f32x4 mfma16(bf16x8 a, bf16x8 b, f32x4 c) { return __builtin_amdgcn_mfma_f32_16x16x32_bf16(a, b, c, 0, 0, 0); }
; __device__ void att_phase(int wv, const Params& p, unsigned char* lds) {
;     ...
;             for (int cb = 0; cb < 24; ++cb)
; #pragma unroll
;                 for (int j = 0; j < 4; ++j) { const float e = __expf(sc[cb][j] - mx); sc[cb][j] = e; sum += e; }
;             sum += __shfl_xor(sum, 16); sum += __shfl_xor(sum, 32);
;             sum += __expf(sink - mx);
;             const float inv = 1.0f / sum;
;             f32x4 oa[4];
; #pragma unroll
;             for (int db = 0; db < 4; ++db) oa[db] = (f32x4){0, 0, 0, 0};
; #pragma unroll
;             for (int ks = 0; ks < 12; ++ks) {
;                 union { bf16x8 v; unsigned u[4]; } pf;
;                 pf.u[0] = cvt_pk_bf16_asm(sc[2 * ks][0], sc[2 * ks][1]); pf.u[1] = cvt_pk_bf16_asm(sc[2 * ks][2], sc[2 * ks][3]);
;                 pf.u[2] = cvt_pk_bf16_asm(sc[2 * ks + 1][0], sc[2 * ks + 1][1]); pf.u[3] = cvt_pk_bf16_asm(sc[2 * ks + 1][2], sc[2 * ks + 1][3]);
; #pragma unroll
;                 for (int db = 0; db < 4; ++db) {
;                     union { bf16x8 v; u32x2 h2[2]; } vf;
;                     const bf16_t* vp = VTL + (16 * db + lr) * VP + 32 * ks + 4 * lq;
;                     vf.h2[0] = *(const u32x2*)vp; vf.h2[1] = *(const u32x2*)(vp + 16);
;                     oa[db] = mfma16(vf.v, pf.v, oa[db]); } }
	v_exp_f32_e32 v45, v45
	v_add_f32_e32 v171, v171, v38
	v_add_f32_e32 v170, v170, v39
	v_add_f32_e32 v171, v171, v40
	v_add_f32_e32 v170, v170, v41
	v_fma_f32 v46, v46, s46, v175
	v_fma_f32 v47, v47, s46, v175
	v_fma_f32 v48, v48, s46, v175
	v_fma_f32 v49, v49, s46, v175
	v_exp_f32_e32 v46, v46
	v_exp_f32_e32 v47, v47
	v_exp_f32_e32 v48, v48
	v_exp_f32_e32 v49, v49
	v_add_f32_e32 v171, v171, v42
	v_add_f32_e32 v170, v170, v43
	v_add_f32_e32 v171, v171, v44
	v_add_f32_e32 v170, v170, v45
	v_fma_f32 v50, v50, s46, v175
	v_fma_f32 v51, v51, s46, v175
	v_fma_f32 v52, v52, s46, v175
	v_fma_f32 v53, v53, s46, v175
	v_exp_f32_e32 v50, v50
	v_exp_f32_e32 v51, v51
	v_exp_f32_e32 v52, v52
	v_exp_f32_e32 v53, v53
	v_add_f32_e32 v171, v171, v46
	v_add_f32_e32 v170, v170, v47
	v_add_f32_e32 v171, v171, v48
	v_add_f32_e32 v170, v170, v49
	v_fma_f32 v54, v54, s46, v175
	v_fma_f32 v55, v55, s46, v175
	v_fma_f32 v56, v56, s46, v175
	v_fma_f32 v57, v57, s46, v175
	v_exp_f32_e32 v54, v54
	v_exp_f32_e32 v55, v55
	v_exp_f32_e32 v56, v56
	v_exp_f32_e32 v57, v57
	v_add_f32_e32 v171, v171, v50
	v_add_f32_e32 v170, v170, v51
	v_add_f32_e32 v171, v171, v52
	v_add_f32_e32 v170, v170, v53
	v_fma_f32 v58, v58, s46, v175
	v_fma_f32 v59, v59, s46, v175
	v_fma_f32 v60, v60, s46, v175
	v_fma_f32 v61, v61, s46, v175
	v_exp_f32_e32 v58, v58
	v_exp_f32_e32 v59, v59
	v_exp_f32_e32 v60, v60
	v_exp_f32_e32 v61, v61
	v_add_f32_e32 v171, v171, v54
	v_add_f32_e32 v170, v170, v55
	v_add_f32_e32 v171, v171, v56
	v_add_f32_e32 v170, v170, v57
	v_fma_f32 v62, v62, s46, v175
	v_fma_f32 v63, v63, s46, v175
	v_fma_f32 v64, v64, s46, v175
	v_fma_f32 v65, v65, s46, v175
	v_exp_f32_e32 v62, v62
	v_exp_f32_e32 v63, v63
	v_exp_f32_e32 v64, v64
	v_exp_f32_e32 v65, v65
	v_add_f32_e32 v171, v171, v58
	v_add_f32_e32 v170, v170, v59
	v_add_f32_e32 v171, v171, v60
	v_add_f32_e32 v170, v170, v61
	v_fma_f32 v66, v66, s46, v175
	v_fma_f32 v67, v67, s46, v175
	v_fma_f32 v68, v68, s46, v175
	v_fma_f32 v69, v69, s46, v175
	v_exp_f32_e32 v66, v66
	v_exp_f32_e32 v67, v67
	v_exp_f32_e32 v68, v68
	v_exp_f32_e32 v69, v69
	v_add_f32_e32 v171, v171, v62
	v_add_f32_e32 v170, v170, v63
	v_add_f32_e32 v171, v171, v64
	v_add_f32_e32 v170, v170, v65
	v_add_f32_e32 v171, v171, v66
	v_add_f32_e32 v170, v170, v67
	v_add_f32_e32 v171, v171, v68
	v_add_f32_e32 v170, v170, v69
	v_add_f32_e32 v170, v170, v171
	v_cvt_pk_bf16_f32 v2, v2, v3
	v_cvt_pk_bf16_f32 v3, v4, v5
	v_cvt_pk_bf16_f32 v4, v6, v7
	v_cvt_pk_bf16_f32 v5, v8, v9
	v_cvt_pk_bf16_f32 v10, v10, v11
	v_cvt_pk_bf16_f32 v11, v12, v13
	v_cvt_pk_bf16_f32 v12, v14, v15
	v_cvt_pk_bf16_f32 v13, v16, v17
	v_cvt_pk_bf16_f32 v18, v18, v19
	v_cvt_pk_bf16_f32 v19, v20, v21
	v_cvt_pk_bf16_f32 v20, v22, v23
	v_cvt_pk_bf16_f32 v21, v24, v25
	v_cvt_pk_bf16_f32 v26, v26, v27
	v_cvt_pk_bf16_f32 v27, v28, v29
	v_cvt_pk_bf16_f32 v28, v30, v31
	v_cvt_pk_bf16_f32 v29, v32, v33
	v_cvt_pk_bf16_f32 v34, v34, v35
	v_cvt_pk_bf16_f32 v35, v36, v37
	v_cvt_pk_bf16_f32 v36, v38, v39
	v_cvt_pk_bf16_f32 v37, v40, v41
	v_cvt_pk_bf16_f32 v42, v42, v43
	v_cvt_pk_bf16_f32 v43, v44, v45
	v_cvt_pk_bf16_f32 v44, v46, v47
	v_cvt_pk_bf16_f32 v45, v48, v49
	v_cvt_pk_bf16_f32 v50, v50, v51
	v_cvt_pk_bf16_f32 v51, v52, v53
	v_cvt_pk_bf16_f32 v52, v54, v55
	v_cvt_pk_bf16_f32 v53, v56, v57
	v_cvt_pk_bf16_f32 v58, v58, v59
	v_cvt_pk_bf16_f32 v59, v60, v61
	v_cvt_pk_bf16_f32 v60, v62, v63
	v_cvt_pk_bf16_f32 v61, v64, v65
	v_cvt_pk_bf16_f32 v66, v66, v67
	v_cvt_pk_bf16_f32 v67, v68, v69
	v_mov_b32_e32 v68, 0
	v_mov_b32_e32 v69, 0
	ds_bpermute_b32 v172, v1, v170
	v_sub_f32_e32 v173, v146, v169
	v_mul_f32_e32 v173, 0x3fb8aa3b, v173
	v_exp_f32_e32 v173, v173
	s_waitcnt lgkmcnt(0)
	v_add_f32_e32 v170, v170, v172
	ds_bpermute_b32 v172, v114, v170
	s_waitcnt lgkmcnt(7)
	ds_read_b64_tr_b16 v[232:233], v165 offset:12800
	ds_read_b64_tr_b16 v[234:235], v165 offset:15360
	ds_read_b64_tr_b16 v[236:237], v165 offset:12832
	ds_read_b64_tr_b16 v[238:239], v165 offset:15392
	ds_read_b64_tr_b16 v[240:241], v165 offset:12864
	ds_read_b64_tr_b16 v[242:243], v165 offset:15424
	ds_read_b64_tr_b16 v[244:245], v165 offset:12896
	ds_read_b64_tr_b16 v[246:247], v165 offset:15456
	s_waitcnt lgkmcnt(8)
	v_mfma_f32_16x16x32_bf16 v[70:73], v[216:219], v[2:5], 0
	v_mfma_f32_16x16x32_bf16 v[74:77], v[220:223], v[2:5], 0
	v_mfma_f32_16x16x32_bf16 v[78:81], v[224:227], v[2:5], 0
	v_mfma_f32_16x16x32_bf16 v[82:85], v[228:231], v[2:5], 0
	v_add_f32_e32 v170, v170, v172
	v_add_f32_e32 v170, v170, v173
	v_rcp_f32_e32 v147, v170
	s_nop 0
	v_fma_f32 v179, -v170, v147, 1.0
	v_fmac_f32_e32 v147, v179, v147
	s_waitcnt lgkmcnt(7)
	ds_read_b64_tr_b16 v[216:217], v165 offset:17920
	ds_read_b64_tr_b16 v[218:219], v165 offset:20480
	ds_read_b64_tr_b16 v[220:221], v165 offset:17952
	ds_read_b64_tr_b16 v[222:223], v165 offset:20512
	ds_read_b64_tr_b16 v[224:225], v165 offset:17984
	ds_read_b64_tr_b16 v[226:227], v165 offset:20544
	ds_read_b64_tr_b16 v[228:229], v165 offset:18016
	ds_read_b64_tr_b16 v[230:231], v165 offset:20576
	s_waitcnt lgkmcnt(8)
	v_mfma_f32_16x16x32_bf16 v[70:73], v[232:235], v[10:13], v[70:73]
	v_mfma_f32_16x16x32_bf16 v[74:77], v[236:239], v[10:13], v[74:77]
	v_mfma_f32_16x16x32_bf16 v[78:81], v[240:243], v[10:13], v[78:81]
	v_mfma_f32_16x16x32_bf16 v[82:85], v[244:247], v[10:13], v[82:85]
	s_waitcnt lgkmcnt(7)
	ds_read_b64_tr_b16 v[232:233], v165 offset:23040
	ds_read_b64_tr_b16 v[234:235], v165 offset:25600
	ds_read_b64_tr_b16 v[236:237], v165 offset:23072
	ds_read_b64_tr_b16 v[238:239], v165 offset:25632
	ds_read_b64_tr_b16 v[240:241], v165 offset:23104
	ds_read_b64_tr_b16 v[242:243], v165 offset:25664
	ds_read_b64_tr_b16 v[244:245], v165 offset:23136
	ds_read_b64_tr_b16 v[246:247], v165 offset:25696
	s_waitcnt lgkmcnt(8)
; __device__ __forceinline__ unsigned cvt_pk_bf16_asm(float lo, float hi) { unsigned r; asm volatile("v_cvt_pk_bf16_f32 %0, %1, %2" : "=v"(r) : "v"(lo), "v"(hi)); return r; }
; __device__ __forceinline__ f32x4 mfma16(bf16x8 a, bf16x8 b, f32x4 c) { return __builtin_amdgcn_mfma_f32_16x16x32_bf16(a, b, c, 0, 0, 0); }
; __device__ void att_phase(int wv, const Params& p, unsigned char* lds) {
;     ...
;             for (int ks = 0; ks < 12; ++ks) {
;                 union { bf16x8 v; unsigned u[4]; } pf;
;                 pf.u[0] = cvt_pk_bf16_asm(sc[2 * ks][0], sc[2 * ks][1]); pf.u[1] = cvt_pk_bf16_asm(sc[2 * ks][2], sc[2 * ks][3]);
;                 pf.u[2] = cvt_pk_bf16_asm(sc[2 * ks + 1][0], sc[2 * ks + 1][1]); pf.u[3] = cvt_pk_bf16_asm(sc[2 * ks + 1][2], sc[2 * ks + 1][3]);
; #pragma unroll
;                 for (int db = 0; db < 4; ++db) {
;                     union { bf16x8 v; u32x2 h2[2]; } vf;
;                     const bf16_t* vp = VTL + (16 * db + lr) * VP + 32 * ks + 4 * lq;
;                     vf.h2[0] = *(const u32x2*)vp; vf.h2[1] = *(const u32x2*)(vp + 16);
;                     oa[db] = mfma16(vf.v, pf.v, oa[db]); } }
; #pragma unroll
;             for (int db = 0; db < 4; ++db) { const f32x4 o = oa[db] * inv; u32x2 wv; wv.x = cvt_pk_bf16_asm(o[0], o[1]); wv.y = cvt_pk_bf16_asm(o[2], o[3]);
;                 *(u32x2*)(qkv + tokq * 1536 + 64 * h + 16 * db + 4 * lq) = wv; }
	v_mfma_f32_16x16x32_bf16 v[70:73], v[216:219], v[18:21], v[70:73]
	v_mfma_f32_16x16x32_bf16 v[74:77], v[220:223], v[18:21], v[74:77]
	v_mfma_f32_16x16x32_bf16 v[78:81], v[224:227], v[18:21], v[78:81]
	v_mfma_f32_16x16x32_bf16 v[82:85], v[228:231], v[18:21], v[82:85]
	s_waitcnt lgkmcnt(7)
	ds_read_b64_tr_b16 v[216:217], v165 offset:28160
	ds_read_b64_tr_b16 v[218:219], v165 offset:30720
	ds_read_b64_tr_b16 v[220:221], v165 offset:28192
	ds_read_b64_tr_b16 v[222:223], v165 offset:30752
	ds_read_b64_tr_b16 v[224:225], v165 offset:28224
	ds_read_b64_tr_b16 v[226:227], v165 offset:30784
	ds_read_b64_tr_b16 v[228:229], v165 offset:28256
	ds_read_b64_tr_b16 v[230:231], v165 offset:30816
	s_waitcnt lgkmcnt(8)
	v_mfma_f32_16x16x32_bf16 v[70:73], v[232:235], v[26:29], v[70:73]
	v_mfma_f32_16x16x32_bf16 v[74:77], v[236:239], v[26:29], v[74:77]
	v_mfma_f32_16x16x32_bf16 v[78:81], v[240:243], v[26:29], v[78:81]
	v_mfma_f32_16x16x32_bf16 v[82:85], v[244:247], v[26:29], v[82:85]
	s_waitcnt lgkmcnt(7)
	ds_read_b64_tr_b16 v[232:233], v165 offset:33280
	ds_read_b64_tr_b16 v[234:235], v165 offset:35840
	ds_read_b64_tr_b16 v[236:237], v165 offset:33312
	ds_read_b64_tr_b16 v[238:239], v165 offset:35872
	ds_read_b64_tr_b16 v[240:241], v165 offset:33344
	ds_read_b64_tr_b16 v[242:243], v165 offset:35904
	ds_read_b64_tr_b16 v[244:245], v165 offset:33376
	ds_read_b64_tr_b16 v[246:247], v165 offset:35936
	s_waitcnt lgkmcnt(8)
	v_mfma_f32_16x16x32_bf16 v[70:73], v[216:219], v[34:37], v[70:73]
	v_mfma_f32_16x16x32_bf16 v[74:77], v[220:223], v[34:37], v[74:77]
	v_mfma_f32_16x16x32_bf16 v[78:81], v[224:227], v[34:37], v[78:81]
	v_mfma_f32_16x16x32_bf16 v[82:85], v[228:231], v[34:37], v[82:85]
	s_waitcnt lgkmcnt(7)
	ds_read_b64_tr_b16 v[216:217], v165 offset:38400
	ds_read_b64_tr_b16 v[218:219], v165 offset:40960
	ds_read_b64_tr_b16 v[220:221], v165 offset:38432
	ds_read_b64_tr_b16 v[222:223], v165 offset:40992
	ds_read_b64_tr_b16 v[224:225], v165 offset:38464
	ds_read_b64_tr_b16 v[226:227], v165 offset:41024
	ds_read_b64_tr_b16 v[228:229], v165 offset:38496
	ds_read_b64_tr_b16 v[230:231], v165 offset:41056
	s_waitcnt lgkmcnt(8)
	v_mfma_f32_16x16x32_bf16 v[70:73], v[232:235], v[42:45], v[70:73]
	v_mfma_f32_16x16x32_bf16 v[74:77], v[236:239], v[42:45], v[74:77]
	v_mfma_f32_16x16x32_bf16 v[78:81], v[240:243], v[42:45], v[78:81]
	v_mfma_f32_16x16x32_bf16 v[82:85], v[244:247], v[42:45], v[82:85]
	s_waitcnt lgkmcnt(7)
	ds_read_b64_tr_b16 v[232:233], v165 offset:43520
	ds_read_b64_tr_b16 v[234:235], v165 offset:46080
	ds_read_b64_tr_b16 v[236:237], v165 offset:43552
	ds_read_b64_tr_b16 v[238:239], v165 offset:46112
	ds_read_b64_tr_b16 v[240:241], v165 offset:43584
	ds_read_b64_tr_b16 v[242:243], v165 offset:46144
	ds_read_b64_tr_b16 v[244:245], v165 offset:43616
	ds_read_b64_tr_b16 v[246:247], v165 offset:46176
	s_waitcnt lgkmcnt(8)
	v_mfma_f32_16x16x32_bf16 v[70:73], v[216:219], v[50:53], v[70:73]
	v_mfma_f32_16x16x32_bf16 v[74:77], v[220:223], v[50:53], v[74:77]
	v_mfma_f32_16x16x32_bf16 v[78:81], v[224:227], v[50:53], v[78:81]
	v_mfma_f32_16x16x32_bf16 v[82:85], v[228:231], v[50:53], v[82:85]
	s_waitcnt lgkmcnt(7)
	ds_read_b64_tr_b16 v[216:217], v165 offset:48640
	ds_read_b64_tr_b16 v[218:219], v165 offset:48640
	ds_read_b64_tr_b16 v[220:221], v165 offset:48672
	ds_read_b64_tr_b16 v[222:223], v165 offset:48672
	ds_read_b64_tr_b16 v[224:225], v165 offset:48704
	ds_read_b64_tr_b16 v[226:227], v165 offset:48704
	ds_read_b64_tr_b16 v[228:229], v165 offset:48736
	ds_read_b64_tr_b16 v[230:231], v165 offset:48736
	s_waitcnt lgkmcnt(8)
	v_mfma_f32_16x16x32_bf16 v[70:73], v[232:235], v[58:61], v[70:73]
	v_mfma_f32_16x16x32_bf16 v[74:77], v[236:239], v[58:61], v[74:77]
	v_mfma_f32_16x16x32_bf16 v[78:81], v[240:243], v[58:61], v[78:81]
	v_mfma_f32_16x16x32_bf16 v[82:85], v[244:247], v[58:61], v[82:85]
	s_waitcnt lgkmcnt(0)
	v_mfma_f32_16x16x32_bf16 v[70:73], v[216:219], v[66:69], v[70:73]
	v_mfma_f32_16x16x32_bf16 v[74:77], v[220:223], v[66:69], v[74:77]
	v_mfma_f32_16x16x32_bf16 v[78:81], v[224:227], v[66:69], v[78:81]
	v_mfma_f32_16x16x32_bf16 v[82:85], v[228:231], v[66:69], v[82:85]
	s_nop 7
	s_nop 1
	v_mul_f32_e32 v70, v70, v147
	v_mul_f32_e32 v71, v71, v147
	v_mul_f32_e32 v72, v72, v147
	v_mul_f32_e32 v73, v73, v147
	v_mul_f32_e32 v74, v74, v147
	v_mul_f32_e32 v75, v75, v147
	v_mul_f32_e32 v76, v76, v147
	v_mul_f32_e32 v77, v77, v147
	v_mul_f32_e32 v78, v78, v147
	v_mul_f32_e32 v79, v79, v147
	v_mul_f32_e32 v80, v80, v147
	v_mul_f32_e32 v81, v81, v147
	v_mul_f32_e32 v82, v82, v147
	v_mul_f32_e32 v83, v83, v147
	v_mul_f32_e32 v84, v84, v147
	v_mul_f32_e32 v85, v85, v147
	v_cvt_pk_bf16_f32 v70, v70, v71
	v_cvt_pk_bf16_f32 v71, v72, v73
	v_cvt_pk_bf16_f32 v74, v74, v75
	v_cvt_pk_bf16_f32 v75, v76, v77
	v_cvt_pk_bf16_f32 v78, v78, v79
	v_cvt_pk_bf16_f32 v79, v80, v81
	v_cvt_pk_bf16_f32 v82, v82, v83
	v_cvt_pk_bf16_f32 v83, v84, v85
	global_store_dwordx2 v[248:249], v[70:71], off offset:-64
	global_store_dwordx2 v[248:249], v[74:75], off offset:-32
	global_store_dwordx2 v[248:249], v[78:79], off
	global_store_dwordx2 v[248:249], v[82:83], off offset:32
	s_branch .Latt_done
; __device__ __forceinline__ f32x4 mfma16(bf16x8 a, bf16x8 b, f32x4 c) { return __builtin_amdgcn_mfma_f32_16x16x32_bf16(a, b, c, 0, 0, 0); }
; __device__ void att_phase(int wv, const Params& p, unsigned char* lds) {
;     ...
;         const int gq = w >> 1, h = 4 * kh + gq;
;         const float slope = exp2f(-0.5f * (float)(h + 1)), sink = p.b_sinks[h];
;         for (int rb = 0; rb < 4; ++rb) {
;             const int qrow = 64 * (w & 1) + 16 * rb + lr;
;             const size_t tokq = (size_t)B * 128 + qrow;
;             bf16x8 qf[2];
; #pragma unroll
;             for (int kk = 0; kk < 2; ++kk) qf[kk] = *(const bf16x8*)(qkv + tokq * 1536 + 64 * h + 32 * kk + 8 * lq);
;             f32x4 sc[24];
; #pragma unroll
;             for (int cb = 0; cb < 24; ++cb) { f32x4 a = {0, 0, 0, 0};
; #pragma unroll
;                 for (int kk = 0; kk < 2; ++kk) { const bf16x8 kf = *(const bf16x8*)(KL + (16 * cb + lr) * KP + 32 * kk + 8 * lq); a = mfma16(kf, qf[kk], a); }
;                 sc[cb] = a; }
;             float mx = sink;
; #pragma unroll
;             for (int cb = 0; cb < 24; ++cb) { const int kb = B - 1 + (cb >> 3); const bool bval = (kb >= sb && kb < se);
; #pragma unroll
;                 for (int j = 0; j < 4; ++j) { const int krel = 16 * cb + 4 * lq + j - 128;
;                     int dist = qrow - krel; dist = dist < 0 ? -dist : dist;
;                     const float v = (bval && dist <= 128) ? sc[cb][j] * 0.125f - slope * (float)dist : -1e30f;
.Latt_general:
	s_mov_b32 s46, 0x3e38aa3b
	s_and_b32 s47, s33, 1
	s_mul_i32 s22, s47, 0x2000
	v_add_u32_e32 v164, s22, v141
	s_mul_i32 s22, s47, 0x2800
	s_add_i32 s22, s22, 0xd800
	v_bfe_u32 v165, v250, 2, 4
	v_mul_u32_u24_e32 v165, 0xa0, v165
	v_and_b32_e32 v166, 3, v250
	v_lshl_add_u32 v165, v166, 3, v165
	v_add_u32_e32 v165, s22, v165
	s_lshl_b32 s47, s47, 2
	v_and_b32_e32 v172, 15, v250
	v_lshrrev_b32_e32 v173, 4, v250
	v_lshlrev_b32_e32 v173, 2, v173
	v_sub_u32_e32 v108, v172, v173
	v_subrev_u32_e32 v110, 1, v108
	v_subrev_u32_e32 v111, 2, v108
	v_subrev_u32_e32 v177, 3, v108
	v_mul_f32_e32 v147, 0xc1000000, v109
	v_mul_f32_e32 v174, 0x43000000, v109
	v_mul_f32_e32 v176, 0x44800000, v109
	v_cvt_f32_i32_e32 v179, v108
	v_mul_f32_e32 v94, v147, v179
	v_mul_f32_e64 v98, v147, |v179|
	v_cvt_f32_i32_e32 v179, v110
	v_mul_f32_e32 v95, v147, v179
	v_mul_f32_e64 v99, v147, |v179|
	v_cvt_f32_i32_e32 v179, v111
	v_mul_f32_e32 v96, v147, v179
	v_mul_f32_e64 v100, v147, |v179|
	v_cvt_f32_i32_e32 v179, v177
	v_mul_f32_e32 v97, v147, v179
	v_mul_f32_e64 v101, v147, |v179|
	v_lshl_add_u64 v[248:249], v[112:113], 0, s[0:1]
	v_sub_f32_e32 v86, v94, v176
	v_sub_f32_e32 v87, v95, v176
	v_sub_f32_e32 v88, v96, v176
	v_sub_f32_e32 v89, v97, v176
	v_cmp_ge_i32_e32 vcc, 0, v108
	s_nop 1
	v_cndmask_b32_e32 v212, v252, v86, vcc
	v_cmp_ge_i32_e32 vcc, 0, v110
	s_nop 1
	v_cndmask_b32_e32 v213, v252, v87, vcc
	v_cmp_ge_i32_e32 vcc, 0, v111
	s_nop 1
	v_cndmask_b32_e32 v214, v252, v88, vcc
	v_cmp_ge_i32_e32 vcc, 0, v177
	s_nop 1
	v_cndmask_b32_e32 v215, v252, v89, vcc
	ds_read_b128 v[148:151], v164
	ds_read_b128 v[152:155], v164 offset:1024
	ds_read_b128 v[156:159], v164 offset:2048
	ds_read_b128 v[160:163], v164 offset:3072
	v_add_f32_e32 v90, v86, v174
	v_add_f32_e32 v91, v87, v174
	v_add_f32_e32 v92, v88, v174
	v_add_f32_e32 v93, v89, v174
	s_cmp_lt_i32 s47, 16
	s_cselect_b64 vcc, -1, s[10:11]
	s_cmp_lt_i32 s47, 8
	s_cselect_b64 vcc, s[6:7], vcc
	v_cndmask_b32_e32 v232, v252, v212, vcc
	v_cndmask_b32_e32 v233, v252, v213, vcc
	v_cndmask_b32_e32 v234, v252, v214, vcc
	v_cndmask_b32_e32 v235, v252, v215, vcc
	s_waitcnt lgkmcnt(2)
	v_mfma_f32_16x16x32_bf16 v[2:5], v[148:151], v[180:183], v[232:235]
	v_mfma_f32_16x16x32_bf16 v[2:5], v[152:155], v[184:187], v[2:5]
	ds_read_b128 v[148:151], v164 offset:4096
	ds_read_b128 v[152:155], v164 offset:5120
	v_add_f32_e32 v86, v90, v174
	v_add_f32_e32 v87, v91, v174
	v_add_f32_e32 v88, v92, v174
	v_add_f32_e32 v89, v93, v174
	s_cmp_lt_i32 s47, 15
	s_cselect_b64 vcc, -1, s[10:11]
	s_cmp_lt_i32 s47, 7
	s_cselect_b64 vcc, s[6:7], vcc
	v_cndmask_b32_e32 v236, v252, v90, vcc
	v_cndmask_b32_e32 v237, v252, v91, vcc
	v_cndmask_b32_e32 v238, v252, v92, vcc
	v_cndmask_b32_e32 v239, v252, v93, vcc
	s_waitcnt lgkmcnt(2)
	v_mfma_f32_16x16x32_bf16 v[6:9], v[156:159], v[180:183], v[236:239]
	v_mfma_f32_16x16x32_bf16 v[6:9], v[160:163], v[184:187], v[6:9]
	ds_read_b128 v[156:159], v164 offset:6144
	ds_read_b128 v[160:163], v164 offset:7168
	v_add_f32_e32 v90, v86, v174
	v_add_f32_e32 v91, v87, v174
	v_add_f32_e32 v92, v88, v174
	v_add_f32_e32 v93, v89, v174
	s_cmp_lt_i32 s47, 14
	s_cselect_b64 vcc, -1, s[10:11]
	s_cmp_lt_i32 s47, 6
	s_cselect_b64 vcc, s[6:7], vcc
	v_cndmask_b32_e32 v232, v252, v86, vcc
	v_cndmask_b32_e32 v233, v252, v87, vcc
	v_cndmask_b32_e32 v234, v252, v88, vcc
	v_cndmask_b32_e32 v235, v252, v89, vcc
	s_waitcnt lgkmcnt(2)
	v_mfma_f32_16x16x32_bf16 v[10:13], v[148:151], v[180:183], v[232:235]
	v_mfma_f32_16x16x32_bf16 v[10:13], v[152:155], v[184:187], v[10:13]
	ds_read_b128 v[148:151], v164 offset:8192
	ds_read_b128 v[152:155], v164 offset:9216
	v_add_f32_e32 v86, v90, v174
	v_add_f32_e32 v87, v91, v174
	v_add_f32_e32 v88, v92, v174
	v_add_f32_e32 v89, v93, v174
	s_cmp_lt_i32 s47, 13
	s_cselect_b64 vcc, -1, s[10:11]
	s_cmp_lt_i32 s47, 5
	s_cselect_b64 vcc, s[6:7], vcc
	v_cndmask_b32_e32 v236, v252, v90, vcc
	v_cndmask_b32_e32 v237, v252, v91, vcc
	v_cndmask_b32_e32 v238, v252, v92, vcc
	v_cndmask_b32_e32 v239, v252, v93, vcc
	s_waitcnt lgkmcnt(2)
	v_mfma_f32_16x16x32_bf16 v[14:17], v[156:159], v[180:183], v[236:239]
	v_mfma_f32_16x16x32_bf16 v[14:17], v[160:163], v[184:187], v[14:17]
	ds_read_b128 v[156:159], v164 offset:10240
	ds_read_b128 v[160:163], v164 offset:11264
	v_add_f32_e32 v90, v86, v174
	v_add_f32_e32 v91, v87, v174
	v_add_f32_e32 v92, v88, v174
	v_add_f32_e32 v93, v89, v174
	s_cmp_lt_i32 s47, 12
	s_cselect_b64 vcc, -1, s[10:11]
	s_cmp_lt_i32 s47, 4
	s_cselect_b64 vcc, s[6:7], vcc
	v_cndmask_b32_e32 v232, v252, v86, vcc
	v_cndmask_b32_e32 v233, v252, v87, vcc
	v_cndmask_b32_e32 v234, v252, v88, vcc
	v_cndmask_b32_e32 v235, v252, v89, vcc
	s_waitcnt lgkmcnt(2)
	v_mfma_f32_16x16x32_bf16 v[18:21], v[148:151], v[180:183], v[232:235]
	v_mfma_f32_16x16x32_bf16 v[18:21], v[152:155], v[184:187], v[18:21]
	ds_read_b128 v[148:151], v164 offset:12288
	ds_read_b128 v[152:155], v164 offset:13312
	v_add_f32_e32 v86, v90, v174
	v_add_f32_e32 v87, v91, v174
	v_add_f32_e32 v88, v92, v174
	v_add_f32_e32 v89, v93, v174
	s_cmp_lt_i32 s47, 11
	s_cselect_b64 vcc, -1, s[10:11]
	s_cmp_lt_i32 s47, 3
	s_cselect_b64 vcc, s[6:7], vcc
	v_cndmask_b32_e32 v236, v252, v90, vcc
	v_cndmask_b32_e32 v237, v252, v91, vcc
	v_cndmask_b32_e32 v238, v252, v92, vcc
	v_cndmask_b32_e32 v239, v252, v93, vcc
	s_waitcnt lgkmcnt(2)
	v_mfma_f32_16x16x32_bf16 v[22:25], v[156:159], v[180:183], v[236:239]
	v_mfma_f32_16x16x32_bf16 v[22:25], v[160:163], v[184:187], v[22:25]
	ds_read_b128 v[156:159], v164 offset:14336
	ds_read_b128 v[160:163], v164 offset:15360
	v_add_f32_e32 v90, v86, v174
	v_add_f32_e32 v91, v87, v174
	v_add_f32_e32 v92, v88, v174
	v_add_f32_e32 v93, v89, v174
	s_cmp_lt_i32 s47, 10
	s_cselect_b64 vcc, -1, s[10:11]
	s_cmp_lt_i32 s47, 2
	s_cselect_b64 vcc, s[6:7], vcc
	v_cndmask_b32_e32 v232, v252, v86, vcc
	v_cndmask_b32_e32 v233, v252, v87, vcc
	v_cndmask_b32_e32 v234, v252, v88, vcc
	v_cndmask_b32_e32 v235, v252, v89, vcc
	s_waitcnt lgkmcnt(2)
; __device__ __forceinline__ f32x4 mfma16(bf16x8 a, bf16x8 b, f32x4 c) { return __builtin_amdgcn_mfma_f32_16x16x32_bf16(a, b, c, 0, 0, 0); }
; __device__ void att_phase(int wv, const Params& p, unsigned char* lds) {
;     ...
;             for (int cb = 0; cb < 24; ++cb) { f32x4 a = {0, 0, 0, 0};
; #pragma unroll
;                 for (int kk = 0; kk < 2; ++kk) { const bf16x8 kf = *(const bf16x8*)(KL + (16 * cb + lr) * KP + 32 * kk + 8 * lq); a = mfma16(kf, qf[kk], a); }
;                 sc[cb] = a; }
;             float mx = sink;
; #pragma unroll
;             for (int cb = 0; cb < 24; ++cb) { const int kb = B - 1 + (cb >> 3); const bool bval = (kb >= sb && kb < se);
; #pragma unroll
;                 for (int j = 0; j < 4; ++j) { const int krel = 16 * cb + 4 * lq + j - 128;
;                     int dist = qrow - krel; dist = dist < 0 ? -dist : dist;
;                     const float v = (bval && dist <= 128) ? sc[cb][j] * 0.125f - slope * (float)dist : -1e30f;
	v_mfma_f32_16x16x32_bf16 v[26:29], v[148:151], v[180:183], v[232:235]
	v_mfma_f32_16x16x32_bf16 v[26:29], v[152:155], v[184:187], v[26:29]
	ds_read_b128 v[148:151], v164 offset:16384
	ds_read_b128 v[152:155], v164 offset:17408
	s_cmp_lt_i32 s47, 9
	s_cselect_b64 vcc, -1, s[10:11]
	s_cmp_lt_i32 s47, 1
	s_cselect_b64 vcc, s[6:7], vcc
	v_cndmask_b32_e32 v236, v252, v90, vcc
	v_cndmask_b32_e32 v237, v252, v91, vcc
	v_cndmask_b32_e32 v238, v252, v92, vcc
	v_cndmask_b32_e32 v239, v252, v93, vcc
	s_waitcnt lgkmcnt(2)
	v_mfma_f32_16x16x32_bf16 v[30:33], v[156:159], v[180:183], v[236:239]
	v_mfma_f32_16x16x32_bf16 v[30:33], v[160:163], v[184:187], v[30:33]
	ds_read_b128 v[156:159], v164 offset:18432
	ds_read_b128 v[160:163], v164 offset:19456
	v_sub_f32_e64 v86, -v94, v174
	v_sub_f32_e64 v87, -v95, v174
	v_sub_f32_e64 v88, -v96, v174
	v_sub_f32_e64 v89, -v97, v174
	s_waitcnt lgkmcnt(2)
	v_mfma_f32_16x16x32_bf16 v[34:37], v[148:151], v[180:183], v[98:101]
	v_mfma_f32_16x16x32_bf16 v[34:37], v[152:155], v[184:187], v[34:37]
	ds_read_b128 v[148:151], v164 offset:20480
	ds_read_b128 v[152:155], v164 offset:21504
	v_sub_f32_e32 v90, v86, v174
	v_sub_f32_e32 v91, v87, v174
	v_sub_f32_e32 v92, v88, v174
	v_sub_f32_e32 v93, v89, v174
	s_waitcnt lgkmcnt(2)
	v_mfma_f32_16x16x32_bf16 v[38:41], v[156:159], v[180:183], v[86:89]
	v_mfma_f32_16x16x32_bf16 v[38:41], v[160:163], v[184:187], v[38:41]
	ds_read_b128 v[156:159], v164 offset:22528
	ds_read_b128 v[160:163], v164 offset:23552
	v_sub_f32_e32 v86, v90, v174
	v_sub_f32_e32 v87, v91, v174
	v_sub_f32_e32 v88, v92, v174
	v_sub_f32_e32 v89, v93, v174
	s_waitcnt lgkmcnt(2)
	v_mfma_f32_16x16x32_bf16 v[42:45], v[148:151], v[180:183], v[90:93]
	v_mfma_f32_16x16x32_bf16 v[42:45], v[152:155], v[184:187], v[42:45]
	ds_read_b128 v[148:151], v164 offset:24576
	ds_read_b128 v[152:155], v164 offset:25600
	v_sub_f32_e32 v90, v86, v174
	v_sub_f32_e32 v91, v87, v174
	v_sub_f32_e32 v92, v88, v174
	v_sub_f32_e32 v93, v89, v174
	s_waitcnt lgkmcnt(2)
	v_mfma_f32_16x16x32_bf16 v[46:49], v[156:159], v[180:183], v[86:89]
	v_mfma_f32_16x16x32_bf16 v[46:49], v[160:163], v[184:187], v[46:49]
	ds_read_b128 v[156:159], v164 offset:26624
	ds_read_b128 v[160:163], v164 offset:27648
	v_sub_f32_e32 v86, v90, v174
	v_sub_f32_e32 v87, v91, v174
	v_sub_f32_e32 v88, v92, v174
	v_sub_f32_e32 v89, v93, v174
	s_cmp_lt_i32 s47, 4
	s_cselect_b64 vcc, -1, s[10:11]
	s_cmp_lt_i32 s47, -4
	s_cselect_b64 vcc, s[6:7], vcc
	v_cndmask_b32_e32 v232, v252, v90, vcc
	v_cndmask_b32_e32 v233, v252, v91, vcc
	v_cndmask_b32_e32 v234, v252, v92, vcc
	v_cndmask_b32_e32 v235, v252, v93, vcc
	s_waitcnt lgkmcnt(2)
	v_mfma_f32_16x16x32_bf16 v[50:53], v[148:151], v[180:183], v[232:235]
	v_mfma_f32_16x16x32_bf16 v[50:53], v[152:155], v[184:187], v[50:53]
	ds_read_b128 v[148:151], v164 offset:28672
	ds_read_b128 v[152:155], v164 offset:29696
	v_sub_f32_e32 v90, v86, v174
	v_sub_f32_e32 v91, v87, v174
	v_sub_f32_e32 v92, v88, v174
	v_sub_f32_e32 v93, v89, v174
	s_cmp_lt_i32 s47, 3
	s_cselect_b64 vcc, -1, s[10:11]
	s_cmp_lt_i32 s47, -5
	s_cselect_b64 vcc, s[6:7], vcc
	v_cndmask_b32_e32 v236, v252, v86, vcc
	v_cndmask_b32_e32 v237, v252, v87, vcc
	v_cndmask_b32_e32 v238, v252, v88, vcc
	v_cndmask_b32_e32 v239, v252, v89, vcc
	s_waitcnt lgkmcnt(2)
	v_mfma_f32_16x16x32_bf16 v[54:57], v[156:159], v[180:183], v[236:239]
	v_mfma_f32_16x16x32_bf16 v[54:57], v[160:163], v[184:187], v[54:57]
	ds_read_b128 v[156:159], v164 offset:30720
	ds_read_b128 v[160:163], v164 offset:31744
	v_sub_f32_e32 v86, v90, v174
	v_sub_f32_e32 v87, v91, v174
	v_sub_f32_e32 v88, v92, v174
	v_sub_f32_e32 v89, v93, v174
	s_cmp_lt_i32 s47, 2
	s_cselect_b64 vcc, -1, s[10:11]
	s_cmp_lt_i32 s47, -6
	s_cselect_b64 vcc, s[6:7], vcc
	v_cndmask_b32_e32 v232, v252, v90, vcc
	v_cndmask_b32_e32 v233, v252, v91, vcc
	v_cndmask_b32_e32 v234, v252, v92, vcc
	v_cndmask_b32_e32 v235, v252, v93, vcc
	s_waitcnt lgkmcnt(2)
	v_mfma_f32_16x16x32_bf16 v[58:61], v[148:151], v[180:183], v[232:235]
	v_mfma_f32_16x16x32_bf16 v[58:61], v[152:155], v[184:187], v[58:61]
	ds_read_b128 v[148:151], v164 offset:32768
	ds_read_b128 v[152:155], v164 offset:33792
	v_sub_f32_e32 v90, v86, v174
	v_sub_f32_e32 v91, v87, v174
	v_sub_f32_e32 v92, v88, v174
	v_sub_f32_e32 v93, v89, v174
	v_cmp_le_i32_e32 vcc, 0, v108
	s_nop 1
	v_cndmask_b32_e32 v212, v252, v90, vcc
	v_cmp_le_i32_e32 vcc, 0, v110
	s_nop 1
	v_cndmask_b32_e32 v213, v252, v91, vcc
	v_cmp_le_i32_e32 vcc, 0, v111
	s_nop 1
	v_cndmask_b32_e32 v214, v252, v92, vcc
	v_cmp_le_i32_e32 vcc, 0, v177
	s_nop 1
	v_cndmask_b32_e32 v215, v252, v93, vcc
	s_cmp_lt_i32 s47, 1
	s_cselect_b64 vcc, -1, s[10:11]
	s_cmp_lt_i32 s47, -7
	s_cselect_b64 vcc, s[6:7], vcc
	v_cndmask_b32_e32 v236, v252, v86, vcc
	v_cndmask_b32_e32 v237, v252, v87, vcc
	v_cndmask_b32_e32 v238, v252, v88, vcc
	v_cndmask_b32_e32 v239, v252, v89, vcc
	s_waitcnt lgkmcnt(2)
	v_mfma_f32_16x16x32_bf16 v[62:65], v[156:159], v[180:183], v[236:239]
	v_mfma_f32_16x16x32_bf16 v[62:65], v[160:163], v[184:187], v[62:65]
	s_cmp_lt_i32 s47, 0
	s_cselect_b64 vcc, -1, s[10:11]
	s_cmp_lt_i32 s47, -8
	s_cselect_b64 vcc, s[6:7], vcc
	v_cndmask_b32_e32 v232, v252, v212, vcc
	v_cndmask_b32_e32 v233, v252, v213, vcc
	v_cndmask_b32_e32 v234, v252, v214, vcc
	v_cndmask_b32_e32 v235, v252, v215, vcc
	s_waitcnt lgkmcnt(0)
	v_mfma_f32_16x16x32_bf16 v[66:69], v[148:151], v[180:183], v[232:235]
	v_mfma_f32_16x16x32_bf16 v[66:69], v[152:155], v[184:187], v[66:69]
	s_waitcnt lgkmcnt(7)
; __device__ void att_phase(int wv, const Params& p, unsigned char* lds) {
;     ...
;             float mx = sink;
; #pragma unroll
;             for (int cb = 0; cb < 24; ++cb) { const int kb = B - 1 + (cb >> 3); const bool bval = (kb >= sb && kb < se);
; #pragma unroll
;                 for (int j = 0; j < 4; ++j) { const int krel = 16 * cb + 4 * lq + j - 128;
;                     int dist = qrow - krel; dist = dist < 0 ? -dist : dist;
;                     const float v = (bval && dist <= 128) ? sc[cb][j] * 0.125f - slope * (float)dist : -1e30f;
;                     sc[cb][j] = v; mx = fmaxf(mx, v); } }
;             mx = fmaxf(mx, __shfl_xor(mx, 16)); mx = fmaxf(mx, __shfl_xor(mx, 32));
;             float sum = 0.f;
; #pragma unroll
;             for (int cb = 0; cb < 24; ++cb)
; #pragma unroll
;                 for (int j = 0; j < 4; ++j) { const float e = __expf(sc[cb][j] - mx); sc[cb][j] = e; sum += e; }
	ds_read_b64_tr_b16 v[216:217], v165
	ds_read_b64_tr_b16 v[218:219], v165 offset:2560
	ds_read_b64_tr_b16 v[220:221], v165 offset:32
	ds_read_b64_tr_b16 v[222:223], v165 offset:2592
	ds_read_b64_tr_b16 v[224:225], v165 offset:64
	ds_read_b64_tr_b16 v[226:227], v165 offset:2624
	ds_read_b64_tr_b16 v[228:229], v165 offset:96
	ds_read_b64_tr_b16 v[230:231], v165 offset:2656
	v_max3_f32 v169, v2, v3, v4
	v_max3_f32 v172, v5, v6, v7
	v_max3_f32 v169, v8, v9, v169
	v_max3_f32 v172, v10, v11, v172
	v_max3_f32 v169, v12, v13, v169
	v_max3_f32 v172, v14, v15, v172
	v_max3_f32 v169, v16, v17, v169
	v_max3_f32 v172, v18, v19, v172
	v_max3_f32 v169, v20, v21, v169
	v_max3_f32 v172, v22, v23, v172
	v_max3_f32 v169, v24, v25, v169
	v_max3_f32 v172, v26, v27, v172
	v_max3_f32 v169, v28, v29, v169
	v_max3_f32 v172, v30, v31, v172
	v_max3_f32 v169, v32, v33, v169
	v_max3_f32 v172, v34, v35, v172
	v_max3_f32 v169, v36, v37, v169
	v_max3_f32 v172, v38, v39, v172
	v_max3_f32 v169, v40, v41, v169
	v_max3_f32 v172, v42, v43, v172
	v_max3_f32 v169, v44, v45, v169
	v_max3_f32 v172, v46, v47, v172
	v_max3_f32 v169, v48, v49, v169
	v_max3_f32 v172, v50, v51, v172
	v_max3_f32 v169, v52, v53, v169
	v_max3_f32 v172, v54, v55, v172
	v_max3_f32 v169, v56, v57, v169
	v_max3_f32 v172, v58, v59, v172
	v_max3_f32 v169, v60, v61, v169
	v_max3_f32 v172, v62, v63, v172
	v_max3_f32 v169, v64, v65, v169
	v_max3_f32 v172, v66, v67, v172
	v_max3_f32 v169, v68, v69, v169
	v_max_f32_e32 v169, v169, v172
	v_mul_f32_e32 v169, 0x3e000000, v169
	s_waitcnt vmcnt(0)
	v_max_f32_e32 v169, v169, v146
	ds_bpermute_b32 v172, v1, v169
	s_waitcnt lgkmcnt(0)
	v_max_f32_e32 v169, v169, v172
	ds_bpermute_b32 v172, v114, v169
	s_waitcnt lgkmcnt(0)
	v_max_f32_e32 v169, v169, v172
	v_mul_f32_e32 v175, 0xbfb8aa3b, v169
	v_mov_b32_e32 v170, 0
	v_mov_b32_e32 v171, 0
	v_fma_f32 v2, v2, s46, v175
	v_fma_f32 v3, v3, s46, v175
	v_fma_f32 v4, v4, s46, v175
	v_fma_f32 v5, v5, s46, v175
	v_exp_f32_e32 v2, v2
	v_exp_f32_e32 v3, v3
	v_exp_f32_e32 v4, v4
	v_exp_f32_e32 v5, v5
	v_fma_f32 v6, v6, s46, v175
	v_fma_f32 v7, v7, s46, v175
	v_fma_f32 v8, v8, s46, v175
	v_fma_f32 v9, v9, s46, v175
	v_exp_f32_e32 v6, v6
	v_exp_f32_e32 v7, v7
	v_exp_f32_e32 v8, v8
	v_exp_f32_e32 v9, v9
	v_add_f32_e32 v171, v171, v2
	v_add_f32_e32 v170, v170, v3
	v_add_f32_e32 v171, v171, v4
	v_add_f32_e32 v170, v170, v5
	v_fma_f32 v10, v10, s46, v175
	v_fma_f32 v11, v11, s46, v175
	v_fma_f32 v12, v12, s46, v175
	v_fma_f32 v13, v13, s46, v175
	v_exp_f32_e32 v10, v10
	v_exp_f32_e32 v11, v11
	v_exp_f32_e32 v12, v12
	v_exp_f32_e32 v13, v13
	v_add_f32_e32 v171, v171, v6
	v_add_f32_e32 v170, v170, v7
	v_add_f32_e32 v171, v171, v8
	v_add_f32_e32 v170, v170, v9
	v_fma_f32 v14, v14, s46, v175
	v_fma_f32 v15, v15, s46, v175
	v_fma_f32 v16, v16, s46, v175
	v_fma_f32 v17, v17, s46, v175
	v_exp_f32_e32 v14, v14
	v_exp_f32_e32 v15, v15
	v_exp_f32_e32 v16, v16
	v_exp_f32_e32 v17, v17
	v_add_f32_e32 v171, v171, v10
	v_add_f32_e32 v170, v170, v11
	v_add_f32_e32 v171, v171, v12
	v_add_f32_e32 v170, v170, v13
	v_fma_f32 v18, v18, s46, v175
	v_fma_f32 v19, v19, s46, v175
	v_fma_f32 v20, v20, s46, v175
	v_fma_f32 v21, v21, s46, v175
	v_exp_f32_e32 v18, v18
	v_exp_f32_e32 v19, v19
	v_exp_f32_e32 v20, v20
	v_exp_f32_e32 v21, v21
	v_add_f32_e32 v171, v171, v14
	v_add_f32_e32 v170, v170, v15
	v_add_f32_e32 v171, v171, v16
	v_add_f32_e32 v170, v170, v17
	v_fma_f32 v22, v22, s46, v175
	v_fma_f32 v23, v23, s46, v175
	v_fma_f32 v24, v24, s46, v175
	v_fma_f32 v25, v25, s46, v175
	v_exp_f32_e32 v22, v22
	v_exp_f32_e32 v23, v23
	v_exp_f32_e32 v24, v24
	v_exp_f32_e32 v25, v25
	v_add_f32_e32 v171, v171, v18
	v_add_f32_e32 v170, v170, v19
	v_add_f32_e32 v171, v171, v20
	v_add_f32_e32 v170, v170, v21
	v_fma_f32 v26, v26, s46, v175
	v_fma_f32 v27, v27, s46, v175
	v_fma_f32 v28, v28, s46, v175
	v_fma_f32 v29, v29, s46, v175
	v_exp_f32_e32 v26, v26
	v_exp_f32_e32 v27, v27
	v_exp_f32_e32 v28, v28
	v_exp_f32_e32 v29, v29
	v_add_f32_e32 v171, v171, v22
	v_add_f32_e32 v170, v170, v23
	v_add_f32_e32 v171, v171, v24
	v_add_f32_e32 v170, v170, v25
	v_fma_f32 v30, v30, s46, v175
	v_fma_f32 v31, v31, s46, v175
	v_fma_f32 v32, v32, s46, v175
	v_fma_f32 v33, v33, s46, v175
	v_exp_f32_e32 v30, v30
	v_exp_f32_e32 v31, v31
	v_exp_f32_e32 v32, v32
	v_exp_f32_e32 v33, v33
	v_add_f32_e32 v171, v171, v26
	v_add_f32_e32 v170, v170, v27
	v_add_f32_e32 v171, v171, v28
	v_add_f32_e32 v170, v170, v29
	v_fma_f32 v34, v34, s46, v175
	v_fma_f32 v35, v35, s46, v175
	v_fma_f32 v36, v36, s46, v175
	v_fma_f32 v37, v37, s46, v175
	v_exp_f32_e32 v34, v34
	v_exp_f32_e32 v35, v35
	v_exp_f32_e32 v36, v36
	v_exp_f32_e32 v37, v37
	v_add_f32_e32 v171, v171, v30
	v_add_f32_e32 v170, v170, v31
	v_add_f32_e32 v171, v171, v32
	v_add_f32_e32 v170, v170, v33
	v_fma_f32 v38, v38, s46, v175
	v_fma_f32 v39, v39, s46, v175
	v_fma_f32 v40, v40, s46, v175
	v_fma_f32 v41, v41, s46, v175
	v_exp_f32_e32 v38, v38
	v_exp_f32_e32 v39, v39
	v_exp_f32_e32 v40, v40
	v_exp_f32_e32 v41, v41
	v_add_f32_e32 v171, v171, v34
	v_add_f32_e32 v170, v170, v35
	v_add_f32_e32 v171, v171, v36
	v_add_f32_e32 v170, v170, v37
	v_fma_f32 v42, v42, s46, v175
	v_fma_f32 v43, v43, s46, v175
	v_fma_f32 v44, v44, s46, v175
	v_fma_f32 v45, v45, s46, v175
	v_exp_f32_e32 v42, v42
	v_exp_f32_e32 v43, v43
	v_exp_f32_e32 v44, v44
	v_exp_f32_e32 v45, v45
	v_add_f32_e32 v171, v171, v38
	v_add_f32_e32 v170, v170, v39
	v_add_f32_e32 v171, v171, v40
	v_add_f32_e32 v170, v170, v41
	v_fma_f32 v46, v46, s46, v175
	v_fma_f32 v47, v47, s46, v175
	v_fma_f32 v48, v48, s46, v175
	v_fma_f32 v49, v49, s46, v175
	v_exp_f32_e32 v46, v46
	v_exp_f32_e32 v47, v47
	v_exp_f32_e32 v48, v48
; __device__ __forceinline__ unsigned cvt_pk_bf16_asm(float lo, float hi) { unsigned r; asm volatile("v_cvt_pk_bf16_f32 %0, %1, %2" : "=v"(r) : "v"(lo), "v"(hi)); return r; }
; __device__ __forceinline__ f32x4 mfma16(bf16x8 a, bf16x8 b, f32x4 c) { return __builtin_amdgcn_mfma_f32_16x16x32_bf16(a, b, c, 0, 0, 0); }
; __device__ void att_phase(int wv, const Params& p, unsigned char* lds) {
;     ...
;             for (int cb = 0; cb < 24; ++cb)
; #pragma unroll
;                 for (int j = 0; j < 4; ++j) { const float e = __expf(sc[cb][j] - mx); sc[cb][j] = e; sum += e; }
;             sum += __shfl_xor(sum, 16); sum += __shfl_xor(sum, 32);
;             sum += __expf(sink - mx);
;             const float inv = 1.0f / sum;
;             f32x4 oa[4];
; #pragma unroll
;             for (int db = 0; db < 4; ++db) oa[db] = (f32x4){0, 0, 0, 0};
; #pragma unroll
;             for (int ks = 0; ks < 12; ++ks) {
;                 union { bf16x8 v; unsigned u[4]; } pf;
;                 pf.u[0] = cvt_pk_bf16_asm(sc[2 * ks][0], sc[2 * ks][1]); pf.u[1] = cvt_pk_bf16_asm(sc[2 * ks][2], sc[2 * ks][3]);
;                 pf.u[2] = cvt_pk_bf16_asm(sc[2 * ks + 1][0], sc[2 * ks + 1][1]); pf.u[3] = cvt_pk_bf16_asm(sc[2 * ks + 1][2], sc[2 * ks + 1][3]);
; #pragma unroll
;                 for (int db = 0; db < 4; ++db) {
;                     union { bf16x8 v; u32x2 h2[2]; } vf;
;                     const bf16_t* vp = VTL + (16 * db + lr) * VP + 32 * ks + 4 * lq;
;                     vf.h2[0] = *(const u32x2*)vp; vf.h2[1] = *(const u32x2*)(vp + 16);
;                     oa[db] = mfma16(vf.v, pf.v, oa[db]); } }
	v_exp_f32_e32 v49, v49
	v_add_f32_e32 v171, v171, v42
	v_add_f32_e32 v170, v170, v43
	v_add_f32_e32 v171, v171, v44
	v_add_f32_e32 v170, v170, v45
	v_fma_f32 v50, v50, s46, v175
	v_fma_f32 v51, v51, s46, v175
	v_fma_f32 v52, v52, s46, v175
	v_fma_f32 v53, v53, s46, v175
	v_exp_f32_e32 v50, v50
	v_exp_f32_e32 v51, v51
	v_exp_f32_e32 v52, v52
	v_exp_f32_e32 v53, v53
	v_add_f32_e32 v171, v171, v46
	v_add_f32_e32 v170, v170, v47
	v_add_f32_e32 v171, v171, v48
	v_add_f32_e32 v170, v170, v49
	v_fma_f32 v54, v54, s46, v175
	v_fma_f32 v55, v55, s46, v175
	v_fma_f32 v56, v56, s46, v175
	v_fma_f32 v57, v57, s46, v175
	v_exp_f32_e32 v54, v54
	v_exp_f32_e32 v55, v55
	v_exp_f32_e32 v56, v56
	v_exp_f32_e32 v57, v57
	v_add_f32_e32 v171, v171, v50
	v_add_f32_e32 v170, v170, v51
	v_add_f32_e32 v171, v171, v52
	v_add_f32_e32 v170, v170, v53
	v_fma_f32 v58, v58, s46, v175
	v_fma_f32 v59, v59, s46, v175
	v_fma_f32 v60, v60, s46, v175
	v_fma_f32 v61, v61, s46, v175
	v_exp_f32_e32 v58, v58
	v_exp_f32_e32 v59, v59
	v_exp_f32_e32 v60, v60
	v_exp_f32_e32 v61, v61
	v_add_f32_e32 v171, v171, v54
	v_add_f32_e32 v170, v170, v55
	v_add_f32_e32 v171, v171, v56
	v_add_f32_e32 v170, v170, v57
	v_fma_f32 v62, v62, s46, v175
	v_fma_f32 v63, v63, s46, v175
	v_fma_f32 v64, v64, s46, v175
	v_fma_f32 v65, v65, s46, v175
	v_exp_f32_e32 v62, v62
	v_exp_f32_e32 v63, v63
	v_exp_f32_e32 v64, v64
	v_exp_f32_e32 v65, v65
	v_add_f32_e32 v171, v171, v58
	v_add_f32_e32 v170, v170, v59
	v_add_f32_e32 v171, v171, v60
	v_add_f32_e32 v170, v170, v61
	v_fma_f32 v66, v66, s46, v175
	v_fma_f32 v67, v67, s46, v175
	v_fma_f32 v68, v68, s46, v175
	v_fma_f32 v69, v69, s46, v175
	v_exp_f32_e32 v66, v66
	v_exp_f32_e32 v67, v67
	v_exp_f32_e32 v68, v68
	v_exp_f32_e32 v69, v69
	v_add_f32_e32 v171, v171, v62
	v_add_f32_e32 v170, v170, v63
	v_add_f32_e32 v171, v171, v64
	v_add_f32_e32 v170, v170, v65
	v_add_f32_e32 v171, v171, v66
	v_add_f32_e32 v170, v170, v67
	v_add_f32_e32 v171, v171, v68
	v_add_f32_e32 v170, v170, v69
	v_add_f32_e32 v170, v170, v171
	v_cvt_pk_bf16_f32 v2, v2, v3
	v_cvt_pk_bf16_f32 v3, v4, v5
	v_cvt_pk_bf16_f32 v4, v6, v7
	v_cvt_pk_bf16_f32 v5, v8, v9
	v_cvt_pk_bf16_f32 v10, v10, v11
	v_cvt_pk_bf16_f32 v11, v12, v13
	v_cvt_pk_bf16_f32 v12, v14, v15
	v_cvt_pk_bf16_f32 v13, v16, v17
	v_cvt_pk_bf16_f32 v18, v18, v19
	v_cvt_pk_bf16_f32 v19, v20, v21
	v_cvt_pk_bf16_f32 v20, v22, v23
	v_cvt_pk_bf16_f32 v21, v24, v25
	v_cvt_pk_bf16_f32 v26, v26, v27
	v_cvt_pk_bf16_f32 v27, v28, v29
	v_cvt_pk_bf16_f32 v28, v30, v31
	v_cvt_pk_bf16_f32 v29, v32, v33
	v_cvt_pk_bf16_f32 v34, v34, v35
	v_cvt_pk_bf16_f32 v35, v36, v37
	v_cvt_pk_bf16_f32 v36, v38, v39
	v_cvt_pk_bf16_f32 v37, v40, v41
	v_cvt_pk_bf16_f32 v42, v42, v43
	v_cvt_pk_bf16_f32 v43, v44, v45
	v_cvt_pk_bf16_f32 v44, v46, v47
	v_cvt_pk_bf16_f32 v45, v48, v49
	v_cvt_pk_bf16_f32 v50, v50, v51
	v_cvt_pk_bf16_f32 v51, v52, v53
	v_cvt_pk_bf16_f32 v52, v54, v55
	v_cvt_pk_bf16_f32 v53, v56, v57
	v_cvt_pk_bf16_f32 v58, v58, v59
	v_cvt_pk_bf16_f32 v59, v60, v61
	v_cvt_pk_bf16_f32 v60, v62, v63
	v_cvt_pk_bf16_f32 v61, v64, v65
	v_cvt_pk_bf16_f32 v66, v66, v67
	v_cvt_pk_bf16_f32 v67, v68, v69
	v_mov_b32_e32 v68, 0
	v_mov_b32_e32 v69, 0
	ds_bpermute_b32 v172, v1, v170
	v_sub_f32_e32 v173, v146, v169
	v_mul_f32_e32 v173, 0x3fb8aa3b, v173
	v_exp_f32_e32 v173, v173
	s_waitcnt lgkmcnt(0)
	v_add_f32_e32 v170, v170, v172
	ds_bpermute_b32 v172, v114, v170
	s_waitcnt lgkmcnt(7)
	ds_read_b64_tr_b16 v[232:233], v165 offset:5120
	ds_read_b64_tr_b16 v[234:235], v165 offset:7680
	ds_read_b64_tr_b16 v[236:237], v165 offset:5152
	ds_read_b64_tr_b16 v[238:239], v165 offset:7712
	ds_read_b64_tr_b16 v[240:241], v165 offset:5184
	ds_read_b64_tr_b16 v[242:243], v165 offset:7744
	ds_read_b64_tr_b16 v[244:245], v165 offset:5216
	ds_read_b64_tr_b16 v[246:247], v165 offset:7776
	s_waitcnt lgkmcnt(8)
	v_mfma_f32_16x16x32_bf16 v[70:73], v[216:219], v[2:5], 0
	v_mfma_f32_16x16x32_bf16 v[74:77], v[220:223], v[2:5], 0
	v_mfma_f32_16x16x32_bf16 v[78:81], v[224:227], v[2:5], 0
	v_mfma_f32_16x16x32_bf16 v[82:85], v[228:231], v[2:5], 0
	v_add_f32_e32 v170, v170, v172
	v_add_f32_e32 v170, v170, v173
	v_rcp_f32_e32 v147, v170
	s_nop 0
	v_fma_f32 v179, -v170, v147, 1.0
	v_fmac_f32_e32 v147, v179, v147
	s_waitcnt lgkmcnt(7)
	ds_read_b64_tr_b16 v[216:217], v165 offset:10240
	ds_read_b64_tr_b16 v[218:219], v165 offset:12800
	ds_read_b64_tr_b16 v[220:221], v165 offset:10272
	ds_read_b64_tr_b16 v[222:223], v165 offset:12832
	ds_read_b64_tr_b16 v[224:225], v165 offset:10304
	ds_read_b64_tr_b16 v[226:227], v165 offset:12864
	ds_read_b64_tr_b16 v[228:229], v165 offset:10336
	ds_read_b64_tr_b16 v[230:231], v165 offset:12896
	s_waitcnt lgkmcnt(8)
	v_mfma_f32_16x16x32_bf16 v[70:73], v[232:235], v[10:13], v[70:73]
	v_mfma_f32_16x16x32_bf16 v[74:77], v[236:239], v[10:13], v[74:77]
	v_mfma_f32_16x16x32_bf16 v[78:81], v[240:243], v[10:13], v[78:81]
	v_mfma_f32_16x16x32_bf16 v[82:85], v[244:247], v[10:13], v[82:85]
	s_waitcnt lgkmcnt(7)
	ds_read_b64_tr_b16 v[232:233], v165 offset:15360
	ds_read_b64_tr_b16 v[234:235], v165 offset:17920
	ds_read_b64_tr_b16 v[236:237], v165 offset:15392
	ds_read_b64_tr_b16 v[238:239], v165 offset:17952
	ds_read_b64_tr_b16 v[240:241], v165 offset:15424
	ds_read_b64_tr_b16 v[242:243], v165 offset:17984
	ds_read_b64_tr_b16 v[244:245], v165 offset:15456
	ds_read_b64_tr_b16 v[246:247], v165 offset:18016
	s_waitcnt lgkmcnt(8)
	v_mfma_f32_16x16x32_bf16 v[70:73], v[216:219], v[18:21], v[70:73]
	v_mfma_f32_16x16x32_bf16 v[74:77], v[220:223], v[18:21], v[74:77]
	v_mfma_f32_16x16x32_bf16 v[78:81], v[224:227], v[18:21], v[78:81]
	v_mfma_f32_16x16x32_bf16 v[82:85], v[228:231], v[18:21], v[82:85]
	s_waitcnt lgkmcnt(7)
; __device__ __forceinline__ unsigned cvt_pk_bf16_asm(float lo, float hi) { unsigned r; asm volatile("v_cvt_pk_bf16_f32 %0, %1, %2" : "=v"(r) : "v"(lo), "v"(hi)); return r; }
; __device__ __forceinline__ f32x4 mfma16(bf16x8 a, bf16x8 b, f32x4 c) { return __builtin_amdgcn_mfma_f32_16x16x32_bf16(a, b, c, 0, 0, 0); }
; __device__ void att_phase(int wv, const Params& p, unsigned char* lds) {
;     ...
;             for (int cb = 0; cb < 24; ++cb) { f32x4 a = {0, 0, 0, 0};
; #pragma unroll
;                 for (int kk = 0; kk < 2; ++kk) { const bf16x8 kf = *(const bf16x8*)(KL + (16 * cb + lr) * KP + 32 * kk + 8 * lq); a = mfma16(kf, qf[kk], a); }
;                 sc[cb] = a; }
;             float mx = sink;
; #pragma unroll
;             for (int cb = 0; cb < 24; ++cb) { const int kb = B - 1 + (cb >> 3); const bool bval = (kb >= sb && kb < se);
; #pragma unroll
;                 for (int j = 0; j < 4; ++j) { const int krel = 16 * cb + 4 * lq + j - 128;
;                     int dist = qrow - krel; dist = dist < 0 ? -dist : dist;
;                     const float v = (bval && dist <= 128) ? sc[cb][j] * 0.125f - slope * (float)dist : -1e30f;
;     ...
;             for (int ks = 0; ks < 12; ++ks) {
;                 union { bf16x8 v; unsigned u[4]; } pf;
;                 pf.u[0] = cvt_pk_bf16_asm(sc[2 * ks][0], sc[2 * ks][1]); pf.u[1] = cvt_pk_bf16_asm(sc[2 * ks][2], sc[2 * ks][3]);
;                 pf.u[2] = cvt_pk_bf16_asm(sc[2 * ks + 1][0], sc[2 * ks + 1][1]); pf.u[3] = cvt_pk_bf16_asm(sc[2 * ks + 1][2], sc[2 * ks + 1][3]);
; #pragma unroll
;                 for (int db = 0; db < 4; ++db) {
;                     union { bf16x8 v; u32x2 h2[2]; } vf;
;                     const bf16_t* vp = VTL + (16 * db + lr) * VP + 32 * ks + 4 * lq;
;                     vf.h2[0] = *(const u32x2*)vp; vf.h2[1] = *(const u32x2*)(vp + 16);
;                     oa[db] = mfma16(vf.v, pf.v, oa[db]); } }
; #pragma unroll
;             for (int db = 0; db < 4; ++db) { const f32x4 o = oa[db] * inv; u32x2 wv; wv.x = cvt_pk_bf16_asm(o[0], o[1]); wv.y = cvt_pk_bf16_asm(o[2], o[3]);
;                 *(u32x2*)(qkv + tokq * 1536 + 64 * h + 16 * db + 4 * lq) = wv; }
	ds_read_b64_tr_b16 v[216:217], v165 offset:20480
	ds_read_b64_tr_b16 v[218:219], v165 offset:23040
	ds_read_b64_tr_b16 v[220:221], v165 offset:20512
	ds_read_b64_tr_b16 v[222:223], v165 offset:23072
	ds_read_b64_tr_b16 v[224:225], v165 offset:20544
	ds_read_b64_tr_b16 v[226:227], v165 offset:23104
	ds_read_b64_tr_b16 v[228:229], v165 offset:20576
	ds_read_b64_tr_b16 v[230:231], v165 offset:23136
	s_waitcnt lgkmcnt(8)
	v_mfma_f32_16x16x32_bf16 v[70:73], v[232:235], v[26:29], v[70:73]
	v_mfma_f32_16x16x32_bf16 v[74:77], v[236:239], v[26:29], v[74:77]
	v_mfma_f32_16x16x32_bf16 v[78:81], v[240:243], v[26:29], v[78:81]
	v_mfma_f32_16x16x32_bf16 v[82:85], v[244:247], v[26:29], v[82:85]
	s_waitcnt lgkmcnt(7)
	ds_read_b64_tr_b16 v[232:233], v165 offset:25600
	ds_read_b64_tr_b16 v[234:235], v165 offset:28160
	ds_read_b64_tr_b16 v[236:237], v165 offset:25632
	ds_read_b64_tr_b16 v[238:239], v165 offset:28192
	ds_read_b64_tr_b16 v[240:241], v165 offset:25664
	ds_read_b64_tr_b16 v[242:243], v165 offset:28224
	ds_read_b64_tr_b16 v[244:245], v165 offset:25696
	ds_read_b64_tr_b16 v[246:247], v165 offset:28256
	s_waitcnt lgkmcnt(8)
	v_mfma_f32_16x16x32_bf16 v[70:73], v[216:219], v[34:37], v[70:73]
	v_mfma_f32_16x16x32_bf16 v[74:77], v[220:223], v[34:37], v[74:77]
	v_mfma_f32_16x16x32_bf16 v[78:81], v[224:227], v[34:37], v[78:81]
	v_mfma_f32_16x16x32_bf16 v[82:85], v[228:231], v[34:37], v[82:85]
	s_waitcnt lgkmcnt(7)
	ds_read_b64_tr_b16 v[216:217], v165 offset:30720
	ds_read_b64_tr_b16 v[218:219], v165 offset:33280
	ds_read_b64_tr_b16 v[220:221], v165 offset:30752
	ds_read_b64_tr_b16 v[222:223], v165 offset:33312
	ds_read_b64_tr_b16 v[224:225], v165 offset:30784
	ds_read_b64_tr_b16 v[226:227], v165 offset:33344
	ds_read_b64_tr_b16 v[228:229], v165 offset:30816
	ds_read_b64_tr_b16 v[230:231], v165 offset:33376
	s_waitcnt lgkmcnt(8)
	v_mfma_f32_16x16x32_bf16 v[70:73], v[232:235], v[42:45], v[70:73]
	v_mfma_f32_16x16x32_bf16 v[74:77], v[236:239], v[42:45], v[74:77]
	v_mfma_f32_16x16x32_bf16 v[78:81], v[240:243], v[42:45], v[78:81]
	v_mfma_f32_16x16x32_bf16 v[82:85], v[244:247], v[42:45], v[82:85]
	s_waitcnt lgkmcnt(7)
	ds_read_b64_tr_b16 v[232:233], v165 offset:35840
	ds_read_b64_tr_b16 v[234:235], v165 offset:38400
	ds_read_b64_tr_b16 v[236:237], v165 offset:35872
	ds_read_b64_tr_b16 v[238:239], v165 offset:38432
	ds_read_b64_tr_b16 v[240:241], v165 offset:35904
	ds_read_b64_tr_b16 v[242:243], v165 offset:38464
	ds_read_b64_tr_b16 v[244:245], v165 offset:35936
	ds_read_b64_tr_b16 v[246:247], v165 offset:38496
	s_waitcnt lgkmcnt(8)
	v_mfma_f32_16x16x32_bf16 v[70:73], v[216:219], v[50:53], v[70:73]
	v_mfma_f32_16x16x32_bf16 v[74:77], v[220:223], v[50:53], v[74:77]
	v_mfma_f32_16x16x32_bf16 v[78:81], v[224:227], v[50:53], v[78:81]
	v_mfma_f32_16x16x32_bf16 v[82:85], v[228:231], v[50:53], v[82:85]
	s_waitcnt lgkmcnt(7)
	ds_read_b64_tr_b16 v[216:217], v165 offset:40960
	ds_read_b64_tr_b16 v[218:219], v165 offset:40960
	ds_read_b64_tr_b16 v[220:221], v165 offset:40992
	ds_read_b64_tr_b16 v[222:223], v165 offset:40992
	ds_read_b64_tr_b16 v[224:225], v165 offset:41024
	ds_read_b64_tr_b16 v[226:227], v165 offset:41024
	ds_read_b64_tr_b16 v[228:229], v165 offset:41056
	ds_read_b64_tr_b16 v[230:231], v165 offset:41056
	s_waitcnt lgkmcnt(8)
	v_mfma_f32_16x16x32_bf16 v[70:73], v[232:235], v[58:61], v[70:73]
	v_mfma_f32_16x16x32_bf16 v[74:77], v[236:239], v[58:61], v[74:77]
	v_mfma_f32_16x16x32_bf16 v[78:81], v[240:243], v[58:61], v[78:81]
	v_mfma_f32_16x16x32_bf16 v[82:85], v[244:247], v[58:61], v[82:85]
	s_waitcnt lgkmcnt(0)
	v_mfma_f32_16x16x32_bf16 v[70:73], v[216:219], v[66:69], v[70:73]
	v_mfma_f32_16x16x32_bf16 v[74:77], v[220:223], v[66:69], v[74:77]
	v_mfma_f32_16x16x32_bf16 v[78:81], v[224:227], v[66:69], v[78:81]
	v_mfma_f32_16x16x32_bf16 v[82:85], v[228:231], v[66:69], v[82:85]
	s_nop 7
	s_nop 1
	v_mul_f32_e32 v70, v70, v147
	v_mul_f32_e32 v71, v71, v147
	v_mul_f32_e32 v72, v72, v147
	v_mul_f32_e32 v73, v73, v147
	v_mul_f32_e32 v74, v74, v147
	v_mul_f32_e32 v75, v75, v147
	v_mul_f32_e32 v76, v76, v147
	v_mul_f32_e32 v77, v77, v147
	v_mul_f32_e32 v78, v78, v147
	v_mul_f32_e32 v79, v79, v147
	v_mul_f32_e32 v80, v80, v147
	v_mul_f32_e32 v81, v81, v147
	v_mul_f32_e32 v82, v82, v147
	v_mul_f32_e32 v83, v83, v147
	v_mul_f32_e32 v84, v84, v147
	v_mul_f32_e32 v85, v85, v147
	v_cvt_pk_bf16_f32 v70, v70, v71
	v_cvt_pk_bf16_f32 v71, v72, v73
	v_cvt_pk_bf16_f32 v74, v74, v75
	v_cvt_pk_bf16_f32 v75, v76, v77
	v_cvt_pk_bf16_f32 v78, v78, v79
	v_cvt_pk_bf16_f32 v79, v80, v81
	v_cvt_pk_bf16_f32 v82, v82, v83
	v_cvt_pk_bf16_f32 v83, v84, v85
	global_store_dwordx2 v[248:249], v[70:71], off offset:-64
	global_store_dwordx2 v[248:249], v[74:75], off offset:-32
	global_store_dwordx2 v[248:249], v[78:79], off
	global_store_dwordx2 v[248:249], v[82:83], off offset:32
	v_lshl_add_u64 v[248:249], v[248:249], 0, s[48:49]
	v_sub_f32_e32 v86, v94, v176
	v_sub_f32_e32 v87, v95, v176
	v_sub_f32_e32 v88, v96, v176
	v_sub_f32_e32 v89, v97, v176
	v_cmp_ge_i32_e32 vcc, 0, v108
	s_nop 1
	v_cndmask_b32_e32 v212, v252, v86, vcc
	v_cmp_ge_i32_e32 vcc, 0, v110
	s_nop 1
	v_cndmask_b32_e32 v213, v252, v87, vcc
	v_cmp_ge_i32_e32 vcc, 0, v111
	s_nop 1
	v_cndmask_b32_e32 v214, v252, v88, vcc
	v_cmp_ge_i32_e32 vcc, 0, v177
	s_nop 1
	v_cndmask_b32_e32 v215, v252, v89, vcc
	ds_read_b128 v[148:151], v164 offset:2048
	ds_read_b128 v[152:155], v164 offset:3072
	ds_read_b128 v[156:159], v164 offset:4096
	ds_read_b128 v[160:163], v164 offset:5120
	v_add_f32_e32 v90, v86, v174
	v_add_f32_e32 v91, v87, v174
	v_add_f32_e32 v92, v88, v174
	v_add_f32_e32 v93, v89, v174
	s_cmp_lt_i32 s47, 15
	s_cselect_b64 vcc, -1, s[10:11]
	s_cmp_lt_i32 s47, 7
	s_cselect_b64 vcc, s[6:7], vcc
	v_cndmask_b32_e32 v232, v252, v212, vcc
	v_cndmask_b32_e32 v233, v252, v213, vcc
	v_cndmask_b32_e32 v234, v252, v214, vcc
	v_cndmask_b32_e32 v235, v252, v215, vcc
	s_waitcnt lgkmcnt(2)
; __device__ __forceinline__ f32x4 mfma16(bf16x8 a, bf16x8 b, f32x4 c) { return __builtin_amdgcn_mfma_f32_16x16x32_bf16(a, b, c, 0, 0, 0); }
; __device__ void att_phase(int wv, const Params& p, unsigned char* lds) {
;     ...
;             for (int cb = 0; cb < 24; ++cb) { f32x4 a = {0, 0, 0, 0};
; #pragma unroll
;                 for (int kk = 0; kk < 2; ++kk) { const bf16x8 kf = *(const bf16x8*)(KL + (16 * cb + lr) * KP + 32 * kk + 8 * lq); a = mfma16(kf, qf[kk], a); }
;                 sc[cb] = a; }
;             float mx = sink;
; #pragma unroll
;             for (int cb = 0; cb < 24; ++cb) { const int kb = B - 1 + (cb >> 3); const bool bval = (kb >= sb && kb < se);
; #pragma unroll
;                 for (int j = 0; j < 4; ++j) { const int krel = 16 * cb + 4 * lq + j - 128;
;                     int dist = qrow - krel; dist = dist < 0 ? -dist : dist;
;                     const float v = (bval && dist <= 128) ? sc[cb][j] * 0.125f - slope * (float)dist : -1e30f;
	v_mfma_f32_16x16x32_bf16 v[2:5], v[148:151], v[188:191], v[232:235]
	v_mfma_f32_16x16x32_bf16 v[2:5], v[152:155], v[192:195], v[2:5]
	ds_read_b128 v[148:151], v164 offset:6144
	ds_read_b128 v[152:155], v164 offset:7168
	v_add_f32_e32 v86, v90, v174
	v_add_f32_e32 v87, v91, v174
	v_add_f32_e32 v88, v92, v174
	v_add_f32_e32 v89, v93, v174
	s_cmp_lt_i32 s47, 14
	s_cselect_b64 vcc, -1, s[10:11]
	s_cmp_lt_i32 s47, 6
	s_cselect_b64 vcc, s[6:7], vcc
	v_cndmask_b32_e32 v236, v252, v90, vcc
	v_cndmask_b32_e32 v237, v252, v91, vcc
	v_cndmask_b32_e32 v238, v252, v92, vcc
	v_cndmask_b32_e32 v239, v252, v93, vcc
	s_waitcnt lgkmcnt(2)
	v_mfma_f32_16x16x32_bf16 v[6:9], v[156:159], v[188:191], v[236:239]
	v_mfma_f32_16x16x32_bf16 v[6:9], v[160:163], v[192:195], v[6:9]
	ds_read_b128 v[156:159], v164 offset:8192
	ds_read_b128 v[160:163], v164 offset:9216
	v_add_f32_e32 v90, v86, v174
	v_add_f32_e32 v91, v87, v174
	v_add_f32_e32 v92, v88, v174
	v_add_f32_e32 v93, v89, v174
	s_cmp_lt_i32 s47, 13
	s_cselect_b64 vcc, -1, s[10:11]
	s_cmp_lt_i32 s47, 5
	s_cselect_b64 vcc, s[6:7], vcc
	v_cndmask_b32_e32 v232, v252, v86, vcc
	v_cndmask_b32_e32 v233, v252, v87, vcc
	v_cndmask_b32_e32 v234, v252, v88, vcc
	v_cndmask_b32_e32 v235, v252, v89, vcc
	s_waitcnt lgkmcnt(2)
	v_mfma_f32_16x16x32_bf16 v[10:13], v[148:151], v[188:191], v[232:235]
	v_mfma_f32_16x16x32_bf16 v[10:13], v[152:155], v[192:195], v[10:13]
	ds_read_b128 v[148:151], v164 offset:10240
	ds_read_b128 v[152:155], v164 offset:11264
	v_add_f32_e32 v86, v90, v174
	v_add_f32_e32 v87, v91, v174
	v_add_f32_e32 v88, v92, v174
	v_add_f32_e32 v89, v93, v174
	s_cmp_lt_i32 s47, 12
	s_cselect_b64 vcc, -1, s[10:11]
	s_cmp_lt_i32 s47, 4
	s_cselect_b64 vcc, s[6:7], vcc
	v_cndmask_b32_e32 v236, v252, v90, vcc
	v_cndmask_b32_e32 v237, v252, v91, vcc
	v_cndmask_b32_e32 v238, v252, v92, vcc
	v_cndmask_b32_e32 v239, v252, v93, vcc
	s_waitcnt lgkmcnt(2)
	v_mfma_f32_16x16x32_bf16 v[14:17], v[156:159], v[188:191], v[236:239]
	v_mfma_f32_16x16x32_bf16 v[14:17], v[160:163], v[192:195], v[14:17]
	ds_read_b128 v[156:159], v164 offset:12288
	ds_read_b128 v[160:163], v164 offset:13312
	v_add_f32_e32 v90, v86, v174
	v_add_f32_e32 v91, v87, v174
	v_add_f32_e32 v92, v88, v174
	v_add_f32_e32 v93, v89, v174
	s_cmp_lt_i32 s47, 11
	s_cselect_b64 vcc, -1, s[10:11]
	s_cmp_lt_i32 s47, 3
	s_cselect_b64 vcc, s[6:7], vcc
	v_cndmask_b32_e32 v232, v252, v86, vcc
	v_cndmask_b32_e32 v233, v252, v87, vcc
	v_cndmask_b32_e32 v234, v252, v88, vcc
	v_cndmask_b32_e32 v235, v252, v89, vcc
	s_waitcnt lgkmcnt(2)
	v_mfma_f32_16x16x32_bf16 v[18:21], v[148:151], v[188:191], v[232:235]
	v_mfma_f32_16x16x32_bf16 v[18:21], v[152:155], v[192:195], v[18:21]
	ds_read_b128 v[148:151], v164 offset:14336
	ds_read_b128 v[152:155], v164 offset:15360
	v_add_f32_e32 v86, v90, v174
	v_add_f32_e32 v87, v91, v174
	v_add_f32_e32 v88, v92, v174
	v_add_f32_e32 v89, v93, v174
	s_cmp_lt_i32 s47, 10
	s_cselect_b64 vcc, -1, s[10:11]
	s_cmp_lt_i32 s47, 2
	s_cselect_b64 vcc, s[6:7], vcc
	v_cndmask_b32_e32 v236, v252, v90, vcc
	v_cndmask_b32_e32 v237, v252, v91, vcc
	v_cndmask_b32_e32 v238, v252, v92, vcc
	v_cndmask_b32_e32 v239, v252, v93, vcc
	s_waitcnt lgkmcnt(2)
	v_mfma_f32_16x16x32_bf16 v[22:25], v[156:159], v[188:191], v[236:239]
	v_mfma_f32_16x16x32_bf16 v[22:25], v[160:163], v[192:195], v[22:25]
	ds_read_b128 v[156:159], v164 offset:16384
	ds_read_b128 v[160:163], v164 offset:17408
	v_add_f32_e32 v90, v86, v174
	v_add_f32_e32 v91, v87, v174
	v_add_f32_e32 v92, v88, v174
	v_add_f32_e32 v93, v89, v174
	s_cmp_lt_i32 s47, 9
	s_cselect_b64 vcc, -1, s[10:11]
	s_cmp_lt_i32 s47, 1
	s_cselect_b64 vcc, s[6:7], vcc
	v_cndmask_b32_e32 v232, v252, v86, vcc
	v_cndmask_b32_e32 v233, v252, v87, vcc
	v_cndmask_b32_e32 v234, v252, v88, vcc
	v_cndmask_b32_e32 v235, v252, v89, vcc
	s_waitcnt lgkmcnt(2)
	v_mfma_f32_16x16x32_bf16 v[26:29], v[148:151], v[188:191], v[232:235]
	v_mfma_f32_16x16x32_bf16 v[26:29], v[152:155], v[192:195], v[26:29]
	ds_read_b128 v[148:151], v164 offset:18432
	ds_read_b128 v[152:155], v164 offset:19456
	s_waitcnt lgkmcnt(2)
	v_mfma_f32_16x16x32_bf16 v[30:33], v[156:159], v[188:191], v[90:93]
	v_mfma_f32_16x16x32_bf16 v[30:33], v[160:163], v[192:195], v[30:33]
	ds_read_b128 v[156:159], v164 offset:20480
	ds_read_b128 v[160:163], v164 offset:21504
	v_sub_f32_e64 v86, -v94, v174
	v_sub_f32_e64 v87, -v95, v174
	v_sub_f32_e64 v88, -v96, v174
	v_sub_f32_e64 v89, -v97, v174
	s_waitcnt lgkmcnt(2)
	v_mfma_f32_16x16x32_bf16 v[34:37], v[148:151], v[188:191], v[98:101]
	v_mfma_f32_16x16x32_bf16 v[34:37], v[152:155], v[192:195], v[34:37]
	ds_read_b128 v[148:151], v164 offset:22528
	ds_read_b128 v[152:155], v164 offset:23552
	v_sub_f32_e32 v90, v86, v174
	v_sub_f32_e32 v91, v87, v174
	v_sub_f32_e32 v92, v88, v174
	v_sub_f32_e32 v93, v89, v174
	s_waitcnt lgkmcnt(2)
	v_mfma_f32_16x16x32_bf16 v[38:41], v[156:159], v[188:191], v[86:89]
	v_mfma_f32_16x16x32_bf16 v[38:41], v[160:163], v[192:195], v[38:41]
	ds_read_b128 v[156:159], v164 offset:24576
	ds_read_b128 v[160:163], v164 offset:25600
	v_sub_f32_e32 v86, v90, v174
	v_sub_f32_e32 v87, v91, v174
	v_sub_f32_e32 v88, v92, v174
	v_sub_f32_e32 v89, v93, v174
	s_waitcnt lgkmcnt(2)
	v_mfma_f32_16x16x32_bf16 v[42:45], v[148:151], v[188:191], v[90:93]
	v_mfma_f32_16x16x32_bf16 v[42:45], v[152:155], v[192:195], v[42:45]
	ds_read_b128 v[148:151], v164 offset:26624
	ds_read_b128 v[152:155], v164 offset:27648
	v_sub_f32_e32 v90, v86, v174
	v_sub_f32_e32 v91, v87, v174
	v_sub_f32_e32 v92, v88, v174
	v_sub_f32_e32 v93, v89, v174
	s_cmp_lt_i32 s47, 4
	s_cselect_b64 vcc, -1, s[10:11]
	s_cmp_lt_i32 s47, -4
	s_cselect_b64 vcc, s[6:7], vcc
	v_cndmask_b32_e32 v236, v252, v86, vcc
	v_cndmask_b32_e32 v237, v252, v87, vcc
	v_cndmask_b32_e32 v238, v252, v88, vcc
	v_cndmask_b32_e32 v239, v252, v89, vcc
	s_waitcnt lgkmcnt(2)
; __device__ __forceinline__ f32x4 mfma16(bf16x8 a, bf16x8 b, f32x4 c) { return __builtin_amdgcn_mfma_f32_16x16x32_bf16(a, b, c, 0, 0, 0); }
; __device__ void att_phase(int wv, const Params& p, unsigned char* lds) {
;     ...
;             for (int cb = 0; cb < 24; ++cb) { f32x4 a = {0, 0, 0, 0};
; #pragma unroll
;                 for (int kk = 0; kk < 2; ++kk) { const bf16x8 kf = *(const bf16x8*)(KL + (16 * cb + lr) * KP + 32 * kk + 8 * lq); a = mfma16(kf, qf[kk], a); }
;                 sc[cb] = a; }
;             float mx = sink;
; #pragma unroll
;             for (int cb = 0; cb < 24; ++cb) { const int kb = B - 1 + (cb >> 3); const bool bval = (kb >= sb && kb < se);
; #pragma unroll
;                 for (int j = 0; j < 4; ++j) { const int krel = 16 * cb + 4 * lq + j - 128;
;                     int dist = qrow - krel; dist = dist < 0 ? -dist : dist;
;                     const float v = (bval && dist <= 128) ? sc[cb][j] * 0.125f - slope * (float)dist : -1e30f;
;                     sc[cb][j] = v; mx = fmaxf(mx, v); } }
;             mx = fmaxf(mx, __shfl_xor(mx, 16)); mx = fmaxf(mx, __shfl_xor(mx, 32));
	v_mfma_f32_16x16x32_bf16 v[46:49], v[156:159], v[188:191], v[236:239]
	v_mfma_f32_16x16x32_bf16 v[46:49], v[160:163], v[192:195], v[46:49]
	ds_read_b128 v[156:159], v164 offset:28672
	ds_read_b128 v[160:163], v164 offset:29696
	v_sub_f32_e32 v86, v90, v174
	v_sub_f32_e32 v87, v91, v174
	v_sub_f32_e32 v88, v92, v174
	v_sub_f32_e32 v89, v93, v174
	s_cmp_lt_i32 s47, 3
	s_cselect_b64 vcc, -1, s[10:11]
	s_cmp_lt_i32 s47, -5
	s_cselect_b64 vcc, s[6:7], vcc
	v_cndmask_b32_e32 v232, v252, v90, vcc
	v_cndmask_b32_e32 v233, v252, v91, vcc
	v_cndmask_b32_e32 v234, v252, v92, vcc
	v_cndmask_b32_e32 v235, v252, v93, vcc
	s_waitcnt lgkmcnt(2)
	v_mfma_f32_16x16x32_bf16 v[50:53], v[148:151], v[188:191], v[232:235]
	v_mfma_f32_16x16x32_bf16 v[50:53], v[152:155], v[192:195], v[50:53]
	ds_read_b128 v[148:151], v164 offset:30720
	ds_read_b128 v[152:155], v164 offset:31744
	v_sub_f32_e32 v90, v86, v174
	v_sub_f32_e32 v91, v87, v174
	v_sub_f32_e32 v92, v88, v174
	v_sub_f32_e32 v93, v89, v174
	s_cmp_lt_i32 s47, 2
	s_cselect_b64 vcc, -1, s[10:11]
	s_cmp_lt_i32 s47, -6
	s_cselect_b64 vcc, s[6:7], vcc
	v_cndmask_b32_e32 v236, v252, v86, vcc
	v_cndmask_b32_e32 v237, v252, v87, vcc
	v_cndmask_b32_e32 v238, v252, v88, vcc
	v_cndmask_b32_e32 v239, v252, v89, vcc
	s_waitcnt lgkmcnt(2)
	v_mfma_f32_16x16x32_bf16 v[54:57], v[156:159], v[188:191], v[236:239]
	v_mfma_f32_16x16x32_bf16 v[54:57], v[160:163], v[192:195], v[54:57]
	ds_read_b128 v[156:159], v164 offset:32768
	ds_read_b128 v[160:163], v164 offset:33792
	v_sub_f32_e32 v86, v90, v174
	v_sub_f32_e32 v87, v91, v174
	v_sub_f32_e32 v88, v92, v174
	v_sub_f32_e32 v89, v93, v174
	s_cmp_lt_i32 s47, 1
	s_cselect_b64 vcc, -1, s[10:11]
	s_cmp_lt_i32 s47, -7
	s_cselect_b64 vcc, s[6:7], vcc
	v_cndmask_b32_e32 v232, v252, v90, vcc
	v_cndmask_b32_e32 v233, v252, v91, vcc
	v_cndmask_b32_e32 v234, v252, v92, vcc
	v_cndmask_b32_e32 v235, v252, v93, vcc
	s_waitcnt lgkmcnt(2)
	v_mfma_f32_16x16x32_bf16 v[58:61], v[148:151], v[188:191], v[232:235]
	v_mfma_f32_16x16x32_bf16 v[58:61], v[152:155], v[192:195], v[58:61]
	ds_read_b128 v[148:151], v164 offset:34816
	ds_read_b128 v[152:155], v164 offset:35840
	v_sub_f32_e32 v90, v86, v174
	v_sub_f32_e32 v91, v87, v174
	v_sub_f32_e32 v92, v88, v174
	v_sub_f32_e32 v93, v89, v174
	v_cmp_le_i32_e32 vcc, 0, v108
	s_nop 1
	v_cndmask_b32_e32 v212, v252, v90, vcc
	v_cmp_le_i32_e32 vcc, 0, v110
	s_nop 1
	v_cndmask_b32_e32 v213, v252, v91, vcc
	v_cmp_le_i32_e32 vcc, 0, v111
	s_nop 1
	v_cndmask_b32_e32 v214, v252, v92, vcc
	v_cmp_le_i32_e32 vcc, 0, v177
	s_nop 1
	v_cndmask_b32_e32 v215, v252, v93, vcc
	s_cmp_lt_i32 s47, 0
	s_cselect_b64 vcc, -1, s[10:11]
	s_cmp_lt_i32 s47, -8
	s_cselect_b64 vcc, s[6:7], vcc
	v_cndmask_b32_e32 v236, v252, v86, vcc
	v_cndmask_b32_e32 v237, v252, v87, vcc
	v_cndmask_b32_e32 v238, v252, v88, vcc
	v_cndmask_b32_e32 v239, v252, v89, vcc
	s_waitcnt lgkmcnt(2)
	v_mfma_f32_16x16x32_bf16 v[62:65], v[156:159], v[188:191], v[236:239]
	v_mfma_f32_16x16x32_bf16 v[62:65], v[160:163], v[192:195], v[62:65]
	s_cmp_lt_i32 s47, -1
	s_cselect_b64 vcc, -1, s[10:11]
	s_cmp_lt_i32 s47, -9
	s_cselect_b64 vcc, s[6:7], vcc
	v_cndmask_b32_e32 v232, v252, v212, vcc
	v_cndmask_b32_e32 v233, v252, v213, vcc
	v_cndmask_b32_e32 v234, v252, v214, vcc
	v_cndmask_b32_e32 v235, v252, v215, vcc
	s_waitcnt lgkmcnt(0)
	v_mfma_f32_16x16x32_bf16 v[66:69], v[148:151], v[188:191], v[232:235]
	v_mfma_f32_16x16x32_bf16 v[66:69], v[152:155], v[192:195], v[66:69]
	s_waitcnt lgkmcnt(7)
	ds_read_b64_tr_b16 v[216:217], v165 offset:2560
	ds_read_b64_tr_b16 v[218:219], v165 offset:5120
	ds_read_b64_tr_b16 v[220:221], v165 offset:2592
	ds_read_b64_tr_b16 v[222:223], v165 offset:5152
	ds_read_b64_tr_b16 v[224:225], v165 offset:2624
	ds_read_b64_tr_b16 v[226:227], v165 offset:5184
	ds_read_b64_tr_b16 v[228:229], v165 offset:2656
	ds_read_b64_tr_b16 v[230:231], v165 offset:5216
	v_max3_f32 v169, v2, v3, v4
	v_max3_f32 v172, v5, v6, v7
	v_max3_f32 v169, v8, v9, v169
	v_max3_f32 v172, v10, v11, v172
	v_max3_f32 v169, v12, v13, v169
	v_max3_f32 v172, v14, v15, v172
	v_max3_f32 v169, v16, v17, v169
	v_max3_f32 v172, v18, v19, v172
	v_max3_f32 v169, v20, v21, v169
	v_max3_f32 v172, v22, v23, v172
	v_max3_f32 v169, v24, v25, v169
	v_max3_f32 v172, v26, v27, v172
	v_max3_f32 v169, v28, v29, v169
	v_max3_f32 v172, v30, v31, v172
	v_max3_f32 v169, v32, v33, v169
	v_max3_f32 v172, v34, v35, v172
	v_max3_f32 v169, v36, v37, v169
	v_max3_f32 v172, v38, v39, v172
	v_max3_f32 v169, v40, v41, v169
	v_max3_f32 v172, v42, v43, v172
	v_max3_f32 v169, v44, v45, v169
	v_max3_f32 v172, v46, v47, v172
	v_max3_f32 v169, v48, v49, v169
	v_max3_f32 v172, v50, v51, v172
	v_max3_f32 v169, v52, v53, v169
	v_max3_f32 v172, v54, v55, v172
	v_max3_f32 v169, v56, v57, v169
	v_max3_f32 v172, v58, v59, v172
	v_max3_f32 v169, v60, v61, v169
	v_max3_f32 v172, v62, v63, v172
	v_max3_f32 v169, v64, v65, v169
	v_max3_f32 v172, v66, v67, v172
	v_max3_f32 v169, v68, v69, v169
	v_max_f32_e32 v169, v169, v172
	v_mul_f32_e32 v169, 0x3e000000, v169
	v_max_f32_e32 v169, v169, v146
	ds_bpermute_b32 v172, v1, v169
	s_waitcnt lgkmcnt(0)
	v_max_f32_e32 v169, v169, v172
	ds_bpermute_b32 v172, v114, v169
	s_waitcnt lgkmcnt(0)
; __device__ void att_phase(int wv, const Params& p, unsigned char* lds) {
;     ...
;             float sum = 0.f;
; #pragma unroll
;             for (int cb = 0; cb < 24; ++cb)
; #pragma unroll
;                 for (int j = 0; j < 4; ++j) { const float e = __expf(sc[cb][j] - mx); sc[cb][j] = e; sum += e; }
	v_max_f32_e32 v169, v169, v172
	v_mul_f32_e32 v175, 0xbfb8aa3b, v169
	v_mov_b32_e32 v170, 0
	v_mov_b32_e32 v171, 0
	v_fma_f32 v2, v2, s46, v175
	v_fma_f32 v3, v3, s46, v175
	v_fma_f32 v4, v4, s46, v175
	v_fma_f32 v5, v5, s46, v175
	v_exp_f32_e32 v2, v2
	v_exp_f32_e32 v3, v3
	v_exp_f32_e32 v4, v4
	v_exp_f32_e32 v5, v5
	v_fma_f32 v6, v6, s46, v175
	v_fma_f32 v7, v7, s46, v175
	v_fma_f32 v8, v8, s46, v175
	v_fma_f32 v9, v9, s46, v175
	v_exp_f32_e32 v6, v6
	v_exp_f32_e32 v7, v7
	v_exp_f32_e32 v8, v8
	v_exp_f32_e32 v9, v9
	v_add_f32_e32 v171, v171, v2
	v_add_f32_e32 v170, v170, v3
	v_add_f32_e32 v171, v171, v4
	v_add_f32_e32 v170, v170, v5
	v_fma_f32 v10, v10, s46, v175
	v_fma_f32 v11, v11, s46, v175
	v_fma_f32 v12, v12, s46, v175
	v_fma_f32 v13, v13, s46, v175
	v_exp_f32_e32 v10, v10
	v_exp_f32_e32 v11, v11
	v_exp_f32_e32 v12, v12
	v_exp_f32_e32 v13, v13
	v_add_f32_e32 v171, v171, v6
	v_add_f32_e32 v170, v170, v7
	v_add_f32_e32 v171, v171, v8
	v_add_f32_e32 v170, v170, v9
	v_fma_f32 v14, v14, s46, v175
	v_fma_f32 v15, v15, s46, v175
	v_fma_f32 v16, v16, s46, v175
	v_fma_f32 v17, v17, s46, v175
	v_exp_f32_e32 v14, v14
	v_exp_f32_e32 v15, v15
	v_exp_f32_e32 v16, v16
	v_exp_f32_e32 v17, v17
	v_add_f32_e32 v171, v171, v10
	v_add_f32_e32 v170, v170, v11
	v_add_f32_e32 v171, v171, v12
	v_add_f32_e32 v170, v170, v13
	v_fma_f32 v18, v18, s46, v175
	v_fma_f32 v19, v19, s46, v175
	v_fma_f32 v20, v20, s46, v175
	v_fma_f32 v21, v21, s46, v175
	v_exp_f32_e32 v18, v18
	v_exp_f32_e32 v19, v19
	v_exp_f32_e32 v20, v20
	v_exp_f32_e32 v21, v21
	v_add_f32_e32 v171, v171, v14
	v_add_f32_e32 v170, v170, v15
	v_add_f32_e32 v171, v171, v16
	v_add_f32_e32 v170, v170, v17
	v_fma_f32 v22, v22, s46, v175
	v_fma_f32 v23, v23, s46, v175
	v_fma_f32 v24, v24, s46, v175
	v_fma_f32 v25, v25, s46, v175
	v_exp_f32_e32 v22, v22
	v_exp_f32_e32 v23, v23
	v_exp_f32_e32 v24, v24
	v_exp_f32_e32 v25, v25
	v_add_f32_e32 v171, v171, v18
	v_add_f32_e32 v170, v170, v19
	v_add_f32_e32 v171, v171, v20
	v_add_f32_e32 v170, v170, v21
	v_fma_f32 v26, v26, s46, v175
	v_fma_f32 v27, v27, s46, v175
	v_fma_f32 v28, v28, s46, v175
	v_fma_f32 v29, v29, s46, v175
	v_exp_f32_e32 v26, v26
	v_exp_f32_e32 v27, v27
	v_exp_f32_e32 v28, v28
	v_exp_f32_e32 v29, v29
	v_add_f32_e32 v171, v171, v22
	v_add_f32_e32 v170, v170, v23
	v_add_f32_e32 v171, v171, v24
	v_add_f32_e32 v170, v170, v25
	v_fma_f32 v30, v30, s46, v175
	v_fma_f32 v31, v31, s46, v175
	v_fma_f32 v32, v32, s46, v175
	v_fma_f32 v33, v33, s46, v175
	v_exp_f32_e32 v30, v30
	v_exp_f32_e32 v31, v31
	v_exp_f32_e32 v32, v32
	v_exp_f32_e32 v33, v33
	v_add_f32_e32 v171, v171, v26
	v_add_f32_e32 v170, v170, v27
	v_add_f32_e32 v171, v171, v28
	v_add_f32_e32 v170, v170, v29
	v_fma_f32 v34, v34, s46, v175
	v_fma_f32 v35, v35, s46, v175
	v_fma_f32 v36, v36, s46, v175
	v_fma_f32 v37, v37, s46, v175
	v_exp_f32_e32 v34, v34
	v_exp_f32_e32 v35, v35
	v_exp_f32_e32 v36, v36
	v_exp_f32_e32 v37, v37
	v_add_f32_e32 v171, v171, v30
	v_add_f32_e32 v170, v170, v31
	v_add_f32_e32 v171, v171, v32
	v_add_f32_e32 v170, v170, v33
	v_fma_f32 v38, v38, s46, v175
	v_fma_f32 v39, v39, s46, v175
	v_fma_f32 v40, v40, s46, v175
	v_fma_f32 v41, v41, s46, v175
	v_exp_f32_e32 v38, v38
	v_exp_f32_e32 v39, v39
	v_exp_f32_e32 v40, v40
	v_exp_f32_e32 v41, v41
	v_add_f32_e32 v171, v171, v34
	v_add_f32_e32 v170, v170, v35
	v_add_f32_e32 v171, v171, v36
	v_add_f32_e32 v170, v170, v37
	v_fma_f32 v42, v42, s46, v175
	v_fma_f32 v43, v43, s46, v175
	v_fma_f32 v44, v44, s46, v175
	v_fma_f32 v45, v45, s46, v175
	v_exp_f32_e32 v42, v42
	v_exp_f32_e32 v43, v43
	v_exp_f32_e32 v44, v44
	v_exp_f32_e32 v45, v45
	v_add_f32_e32 v171, v171, v38
	v_add_f32_e32 v170, v170, v39
	v_add_f32_e32 v171, v171, v40
	v_add_f32_e32 v170, v170, v41
	v_fma_f32 v46, v46, s46, v175
	v_fma_f32 v47, v47, s46, v175
	v_fma_f32 v48, v48, s46, v175
	v_fma_f32 v49, v49, s46, v175
	v_exp_f32_e32 v46, v46
	v_exp_f32_e32 v47, v47
	v_exp_f32_e32 v48, v48
	v_exp_f32_e32 v49, v49
	v_add_f32_e32 v171, v171, v42
	v_add_f32_e32 v170, v170, v43
	v_add_f32_e32 v171, v171, v44
	v_add_f32_e32 v170, v170, v45
	v_fma_f32 v50, v50, s46, v175
	v_fma_f32 v51, v51, s46, v175
	v_fma_f32 v52, v52, s46, v175
	v_fma_f32 v53, v53, s46, v175
	v_exp_f32_e32 v50, v50
	v_exp_f32_e32 v51, v51
	v_exp_f32_e32 v52, v52
	v_exp_f32_e32 v53, v53
	v_add_f32_e32 v171, v171, v46
	v_add_f32_e32 v170, v170, v47
	v_add_f32_e32 v171, v171, v48
	v_add_f32_e32 v170, v170, v49
	v_fma_f32 v54, v54, s46, v175
	v_fma_f32 v55, v55, s46, v175
	v_fma_f32 v56, v56, s46, v175
	v_fma_f32 v57, v57, s46, v175
	v_exp_f32_e32 v54, v54
	v_exp_f32_e32 v55, v55
	v_exp_f32_e32 v56, v56
	v_exp_f32_e32 v57, v57
	v_add_f32_e32 v171, v171, v50
	v_add_f32_e32 v170, v170, v51
	v_add_f32_e32 v171, v171, v52
	v_add_f32_e32 v170, v170, v53
	v_fma_f32 v58, v58, s46, v175
	v_fma_f32 v59, v59, s46, v175
	v_fma_f32 v60, v60, s46, v175
	v_fma_f32 v61, v61, s46, v175
	v_exp_f32_e32 v58, v58
	v_exp_f32_e32 v59, v59
	v_exp_f32_e32 v60, v60
	v_exp_f32_e32 v61, v61
	v_add_f32_e32 v171, v171, v54
	v_add_f32_e32 v170, v170, v55
	v_add_f32_e32 v171, v171, v56
	v_add_f32_e32 v170, v170, v57
	v_fma_f32 v62, v62, s46, v175
	v_fma_f32 v63, v63, s46, v175
	v_fma_f32 v64, v64, s46, v175
	v_fma_f32 v65, v65, s46, v175
	v_exp_f32_e32 v62, v62
	v_exp_f32_e32 v63, v63
	v_exp_f32_e32 v64, v64
	v_exp_f32_e32 v65, v65
	v_add_f32_e32 v171, v171, v58
	v_add_f32_e32 v170, v170, v59
	v_add_f32_e32 v171, v171, v60
	v_add_f32_e32 v170, v170, v61
	v_fma_f32 v66, v66, s46, v175
	v_fma_f32 v67, v67, s46, v175
	v_fma_f32 v68, v68, s46, v175
	v_fma_f32 v69, v69, s46, v175
	v_exp_f32_e32 v66, v66
	v_exp_f32_e32 v67, v67
; __device__ __forceinline__ unsigned cvt_pk_bf16_asm(float lo, float hi) { unsigned r; asm volatile("v_cvt_pk_bf16_f32 %0, %1, %2" : "=v"(r) : "v"(lo), "v"(hi)); return r; }
; __device__ __forceinline__ f32x4 mfma16(bf16x8 a, bf16x8 b, f32x4 c) { return __builtin_amdgcn_mfma_f32_16x16x32_bf16(a, b, c, 0, 0, 0); }
; __device__ void att_phase(int wv, const Params& p, unsigned char* lds) {
;     ...
;             for (int cb = 0; cb < 24; ++cb)
; #pragma unroll
;                 for (int j = 0; j < 4; ++j) { const float e = __expf(sc[cb][j] - mx); sc[cb][j] = e; sum += e; }
;             sum += __shfl_xor(sum, 16); sum += __shfl_xor(sum, 32);
;             sum += __expf(sink - mx);
;             const float inv = 1.0f / sum;
;             f32x4 oa[4];
; #pragma unroll
;             for (int db = 0; db < 4; ++db) oa[db] = (f32x4){0, 0, 0, 0};
; #pragma unroll
;             for (int ks = 0; ks < 12; ++ks) {
;                 union { bf16x8 v; unsigned u[4]; } pf;
;                 pf.u[0] = cvt_pk_bf16_asm(sc[2 * ks][0], sc[2 * ks][1]); pf.u[1] = cvt_pk_bf16_asm(sc[2 * ks][2], sc[2 * ks][3]);
;                 pf.u[2] = cvt_pk_bf16_asm(sc[2 * ks + 1][0], sc[2 * ks + 1][1]); pf.u[3] = cvt_pk_bf16_asm(sc[2 * ks + 1][2], sc[2 * ks + 1][3]);
; #pragma unroll
;                 for (int db = 0; db < 4; ++db) {
;                     union { bf16x8 v; u32x2 h2[2]; } vf;
;                     const bf16_t* vp = VTL + (16 * db + lr) * VP + 32 * ks + 4 * lq;
;                     vf.h2[0] = *(const u32x2*)vp; vf.h2[1] = *(const u32x2*)(vp + 16);
;                     oa[db] = mfma16(vf.v, pf.v, oa[db]); } }
	v_exp_f32_e32 v68, v68
	v_exp_f32_e32 v69, v69
	v_add_f32_e32 v171, v171, v62
	v_add_f32_e32 v170, v170, v63
	v_add_f32_e32 v171, v171, v64
	v_add_f32_e32 v170, v170, v65
	v_add_f32_e32 v171, v171, v66
	v_add_f32_e32 v170, v170, v67
	v_add_f32_e32 v171, v171, v68
	v_add_f32_e32 v170, v170, v69
	v_add_f32_e32 v170, v170, v171
	v_cvt_pk_bf16_f32 v2, v2, v3
	v_cvt_pk_bf16_f32 v3, v4, v5
	v_cvt_pk_bf16_f32 v4, v6, v7
	v_cvt_pk_bf16_f32 v5, v8, v9
	v_cvt_pk_bf16_f32 v10, v10, v11
	v_cvt_pk_bf16_f32 v11, v12, v13
	v_cvt_pk_bf16_f32 v12, v14, v15
	v_cvt_pk_bf16_f32 v13, v16, v17
	v_cvt_pk_bf16_f32 v18, v18, v19
	v_cvt_pk_bf16_f32 v19, v20, v21
	v_cvt_pk_bf16_f32 v20, v22, v23
	v_cvt_pk_bf16_f32 v21, v24, v25
	v_cvt_pk_bf16_f32 v26, v26, v27
	v_cvt_pk_bf16_f32 v27, v28, v29
	v_cvt_pk_bf16_f32 v28, v30, v31
	v_cvt_pk_bf16_f32 v29, v32, v33
	v_cvt_pk_bf16_f32 v34, v34, v35
	v_cvt_pk_bf16_f32 v35, v36, v37
	v_cvt_pk_bf16_f32 v36, v38, v39
	v_cvt_pk_bf16_f32 v37, v40, v41
	v_cvt_pk_bf16_f32 v42, v42, v43
	v_cvt_pk_bf16_f32 v43, v44, v45
	v_cvt_pk_bf16_f32 v44, v46, v47
	v_cvt_pk_bf16_f32 v45, v48, v49
	v_cvt_pk_bf16_f32 v50, v50, v51
	v_cvt_pk_bf16_f32 v51, v52, v53
	v_cvt_pk_bf16_f32 v52, v54, v55
	v_cvt_pk_bf16_f32 v53, v56, v57
	v_cvt_pk_bf16_f32 v58, v58, v59
	v_cvt_pk_bf16_f32 v59, v60, v61
	v_cvt_pk_bf16_f32 v60, v62, v63
	v_cvt_pk_bf16_f32 v61, v64, v65
	v_cvt_pk_bf16_f32 v66, v66, v67
	v_cvt_pk_bf16_f32 v67, v68, v69
	v_mov_b32_e32 v68, 0
	v_mov_b32_e32 v69, 0
	ds_bpermute_b32 v172, v1, v170
	v_sub_f32_e32 v173, v146, v169
	v_mul_f32_e32 v173, 0x3fb8aa3b, v173
	v_exp_f32_e32 v173, v173
	s_waitcnt lgkmcnt(0)
	v_add_f32_e32 v170, v170, v172
	ds_bpermute_b32 v172, v114, v170
	s_waitcnt lgkmcnt(7)
	ds_read_b64_tr_b16 v[232:233], v165 offset:7680
	ds_read_b64_tr_b16 v[234:235], v165 offset:10240
	ds_read_b64_tr_b16 v[236:237], v165 offset:7712
	ds_read_b64_tr_b16 v[238:239], v165 offset:10272
	ds_read_b64_tr_b16 v[240:241], v165 offset:7744
	ds_read_b64_tr_b16 v[242:243], v165 offset:10304
	ds_read_b64_tr_b16 v[244:245], v165 offset:7776
	ds_read_b64_tr_b16 v[246:247], v165 offset:10336
	s_waitcnt lgkmcnt(8)
	v_mfma_f32_16x16x32_bf16 v[70:73], v[216:219], v[2:5], 0
	v_mfma_f32_16x16x32_bf16 v[74:77], v[220:223], v[2:5], 0
	v_mfma_f32_16x16x32_bf16 v[78:81], v[224:227], v[2:5], 0
	v_mfma_f32_16x16x32_bf16 v[82:85], v[228:231], v[2:5], 0
	v_add_f32_e32 v170, v170, v172
	v_add_f32_e32 v170, v170, v173
	v_rcp_f32_e32 v147, v170
	s_nop 0
	v_fma_f32 v179, -v170, v147, 1.0
	v_fmac_f32_e32 v147, v179, v147
	s_waitcnt lgkmcnt(7)
	ds_read_b64_tr_b16 v[216:217], v165 offset:12800
	ds_read_b64_tr_b16 v[218:219], v165 offset:15360
	ds_read_b64_tr_b16 v[220:221], v165 offset:12832
	ds_read_b64_tr_b16 v[222:223], v165 offset:15392
	ds_read_b64_tr_b16 v[224:225], v165 offset:12864
	ds_read_b64_tr_b16 v[226:227], v165 offset:15424
	ds_read_b64_tr_b16 v[228:229], v165 offset:12896
	ds_read_b64_tr_b16 v[230:231], v165 offset:15456
	s_waitcnt lgkmcnt(8)
	v_mfma_f32_16x16x32_bf16 v[70:73], v[232:235], v[10:13], v[70:73]
	v_mfma_f32_16x16x32_bf16 v[74:77], v[236:239], v[10:13], v[74:77]
	v_mfma_f32_16x16x32_bf16 v[78:81], v[240:243], v[10:13], v[78:81]
	v_mfma_f32_16x16x32_bf16 v[82:85], v[244:247], v[10:13], v[82:85]
	s_waitcnt lgkmcnt(7)
	ds_read_b64_tr_b16 v[232:233], v165 offset:17920
	ds_read_b64_tr_b16 v[234:235], v165 offset:20480
	ds_read_b64_tr_b16 v[236:237], v165 offset:17952
	ds_read_b64_tr_b16 v[238:239], v165 offset:20512
	ds_read_b64_tr_b16 v[240:241], v165 offset:17984
	ds_read_b64_tr_b16 v[242:243], v165 offset:20544
	ds_read_b64_tr_b16 v[244:245], v165 offset:18016
	ds_read_b64_tr_b16 v[246:247], v165 offset:20576
	s_waitcnt lgkmcnt(8)
	v_mfma_f32_16x16x32_bf16 v[70:73], v[216:219], v[18:21], v[70:73]
	v_mfma_f32_16x16x32_bf16 v[74:77], v[220:223], v[18:21], v[74:77]
	v_mfma_f32_16x16x32_bf16 v[78:81], v[224:227], v[18:21], v[78:81]
	v_mfma_f32_16x16x32_bf16 v[82:85], v[228:231], v[18:21], v[82:85]
	s_waitcnt lgkmcnt(7)
	ds_read_b64_tr_b16 v[216:217], v165 offset:23040
	ds_read_b64_tr_b16 v[218:219], v165 offset:25600
	ds_read_b64_tr_b16 v[220:221], v165 offset:23072
	ds_read_b64_tr_b16 v[222:223], v165 offset:25632
	ds_read_b64_tr_b16 v[224:225], v165 offset:23104
	ds_read_b64_tr_b16 v[226:227], v165 offset:25664
	ds_read_b64_tr_b16 v[228:229], v165 offset:23136
	ds_read_b64_tr_b16 v[230:231], v165 offset:25696
	s_waitcnt lgkmcnt(8)
	v_mfma_f32_16x16x32_bf16 v[70:73], v[232:235], v[26:29], v[70:73]
	v_mfma_f32_16x16x32_bf16 v[74:77], v[236:239], v[26:29], v[74:77]
	v_mfma_f32_16x16x32_bf16 v[78:81], v[240:243], v[26:29], v[78:81]
	v_mfma_f32_16x16x32_bf16 v[82:85], v[244:247], v[26:29], v[82:85]
	s_waitcnt lgkmcnt(7)
	ds_read_b64_tr_b16 v[232:233], v165 offset:28160
	ds_read_b64_tr_b16 v[234:235], v165 offset:30720
	ds_read_b64_tr_b16 v[236:237], v165 offset:28192
	ds_read_b64_tr_b16 v[238:239], v165 offset:30752
	ds_read_b64_tr_b16 v[240:241], v165 offset:28224
	ds_read_b64_tr_b16 v[242:243], v165 offset:30784
	ds_read_b64_tr_b16 v[244:245], v165 offset:28256
	ds_read_b64_tr_b16 v[246:247], v165 offset:30816
	s_waitcnt lgkmcnt(8)
	v_mfma_f32_16x16x32_bf16 v[70:73], v[216:219], v[34:37], v[70:73]
	v_mfma_f32_16x16x32_bf16 v[74:77], v[220:223], v[34:37], v[74:77]
	v_mfma_f32_16x16x32_bf16 v[78:81], v[224:227], v[34:37], v[78:81]
	v_mfma_f32_16x16x32_bf16 v[82:85], v[228:231], v[34:37], v[82:85]
	s_waitcnt lgkmcnt(7)
	ds_read_b64_tr_b16 v[216:217], v165 offset:33280
	ds_read_b64_tr_b16 v[218:219], v165 offset:35840
	ds_read_b64_tr_b16 v[220:221], v165 offset:33312
	ds_read_b64_tr_b16 v[222:223], v165 offset:35872
	ds_read_b64_tr_b16 v[224:225], v165 offset:33344
	ds_read_b64_tr_b16 v[226:227], v165 offset:35904
	ds_read_b64_tr_b16 v[228:229], v165 offset:33376
	ds_read_b64_tr_b16 v[230:231], v165 offset:35936
	s_waitcnt lgkmcnt(8)
; __device__ __forceinline__ unsigned cvt_pk_bf16_asm(float lo, float hi) { unsigned r; asm volatile("v_cvt_pk_bf16_f32 %0, %1, %2" : "=v"(r) : "v"(lo), "v"(hi)); return r; }
; __device__ __forceinline__ f32x4 mfma16(bf16x8 a, bf16x8 b, f32x4 c) { return __builtin_amdgcn_mfma_f32_16x16x32_bf16(a, b, c, 0, 0, 0); }
; __device__ void att_phase(int wv, const Params& p, unsigned char* lds) {
;     ...
;             for (int cb = 0; cb < 24; ++cb) { f32x4 a = {0, 0, 0, 0};
; #pragma unroll
;                 for (int kk = 0; kk < 2; ++kk) { const bf16x8 kf = *(const bf16x8*)(KL + (16 * cb + lr) * KP + 32 * kk + 8 * lq); a = mfma16(kf, qf[kk], a); }
;                 sc[cb] = a; }
;             float mx = sink;
; #pragma unroll
;             for (int cb = 0; cb < 24; ++cb) { const int kb = B - 1 + (cb >> 3); const bool bval = (kb >= sb && kb < se);
; #pragma unroll
;                 for (int j = 0; j < 4; ++j) { const int krel = 16 * cb + 4 * lq + j - 128;
;                     int dist = qrow - krel; dist = dist < 0 ? -dist : dist;
;                     const float v = (bval && dist <= 128) ? sc[cb][j] * 0.125f - slope * (float)dist : -1e30f;
;     ...
;             for (int ks = 0; ks < 12; ++ks) {
;                 union { bf16x8 v; unsigned u[4]; } pf;
;                 pf.u[0] = cvt_pk_bf16_asm(sc[2 * ks][0], sc[2 * ks][1]); pf.u[1] = cvt_pk_bf16_asm(sc[2 * ks][2], sc[2 * ks][3]);
;                 pf.u[2] = cvt_pk_bf16_asm(sc[2 * ks + 1][0], sc[2 * ks + 1][1]); pf.u[3] = cvt_pk_bf16_asm(sc[2 * ks + 1][2], sc[2 * ks + 1][3]);
; #pragma unroll
;                 for (int db = 0; db < 4; ++db) {
;                     union { bf16x8 v; u32x2 h2[2]; } vf;
;                     const bf16_t* vp = VTL + (16 * db + lr) * VP + 32 * ks + 4 * lq;
;                     vf.h2[0] = *(const u32x2*)vp; vf.h2[1] = *(const u32x2*)(vp + 16);
;                     oa[db] = mfma16(vf.v, pf.v, oa[db]); } }
; #pragma unroll
;             for (int db = 0; db < 4; ++db) { const f32x4 o = oa[db] * inv; u32x2 wv; wv.x = cvt_pk_bf16_asm(o[0], o[1]); wv.y = cvt_pk_bf16_asm(o[2], o[3]);
;                 *(u32x2*)(qkv + tokq * 1536 + 64 * h + 16 * db + 4 * lq) = wv; }
	v_mfma_f32_16x16x32_bf16 v[70:73], v[232:235], v[42:45], v[70:73]
	v_mfma_f32_16x16x32_bf16 v[74:77], v[236:239], v[42:45], v[74:77]
	v_mfma_f32_16x16x32_bf16 v[78:81], v[240:243], v[42:45], v[78:81]
	v_mfma_f32_16x16x32_bf16 v[82:85], v[244:247], v[42:45], v[82:85]
	s_waitcnt lgkmcnt(7)
	ds_read_b64_tr_b16 v[232:233], v165 offset:38400
	ds_read_b64_tr_b16 v[234:235], v165 offset:40960
	ds_read_b64_tr_b16 v[236:237], v165 offset:38432
	ds_read_b64_tr_b16 v[238:239], v165 offset:40992
	ds_read_b64_tr_b16 v[240:241], v165 offset:38464
	ds_read_b64_tr_b16 v[242:243], v165 offset:41024
	ds_read_b64_tr_b16 v[244:245], v165 offset:38496
	ds_read_b64_tr_b16 v[246:247], v165 offset:41056
	s_waitcnt lgkmcnt(8)
	v_mfma_f32_16x16x32_bf16 v[70:73], v[216:219], v[50:53], v[70:73]
	v_mfma_f32_16x16x32_bf16 v[74:77], v[220:223], v[50:53], v[74:77]
	v_mfma_f32_16x16x32_bf16 v[78:81], v[224:227], v[50:53], v[78:81]
	v_mfma_f32_16x16x32_bf16 v[82:85], v[228:231], v[50:53], v[82:85]
	s_waitcnt lgkmcnt(7)
	ds_read_b64_tr_b16 v[216:217], v165 offset:43520
	ds_read_b64_tr_b16 v[218:219], v165 offset:43520
	ds_read_b64_tr_b16 v[220:221], v165 offset:43552
	ds_read_b64_tr_b16 v[222:223], v165 offset:43552
	ds_read_b64_tr_b16 v[224:225], v165 offset:43584
	ds_read_b64_tr_b16 v[226:227], v165 offset:43584
	ds_read_b64_tr_b16 v[228:229], v165 offset:43616
	ds_read_b64_tr_b16 v[230:231], v165 offset:43616
	s_waitcnt lgkmcnt(8)
	v_mfma_f32_16x16x32_bf16 v[70:73], v[232:235], v[58:61], v[70:73]
	v_mfma_f32_16x16x32_bf16 v[74:77], v[236:239], v[58:61], v[74:77]
	v_mfma_f32_16x16x32_bf16 v[78:81], v[240:243], v[58:61], v[78:81]
	v_mfma_f32_16x16x32_bf16 v[82:85], v[244:247], v[58:61], v[82:85]
	s_waitcnt lgkmcnt(0)
	v_mfma_f32_16x16x32_bf16 v[70:73], v[216:219], v[66:69], v[70:73]
	v_mfma_f32_16x16x32_bf16 v[74:77], v[220:223], v[66:69], v[74:77]
	v_mfma_f32_16x16x32_bf16 v[78:81], v[224:227], v[66:69], v[78:81]
	v_mfma_f32_16x16x32_bf16 v[82:85], v[228:231], v[66:69], v[82:85]
	s_nop 7
	s_nop 1
	v_mul_f32_e32 v70, v70, v147
	v_mul_f32_e32 v71, v71, v147
	v_mul_f32_e32 v72, v72, v147
	v_mul_f32_e32 v73, v73, v147
	v_mul_f32_e32 v74, v74, v147
	v_mul_f32_e32 v75, v75, v147
	v_mul_f32_e32 v76, v76, v147
	v_mul_f32_e32 v77, v77, v147
	v_mul_f32_e32 v78, v78, v147
	v_mul_f32_e32 v79, v79, v147
	v_mul_f32_e32 v80, v80, v147
	v_mul_f32_e32 v81, v81, v147
	v_mul_f32_e32 v82, v82, v147
	v_mul_f32_e32 v83, v83, v147
	v_mul_f32_e32 v84, v84, v147
	v_mul_f32_e32 v85, v85, v147
	v_cvt_pk_bf16_f32 v70, v70, v71
	v_cvt_pk_bf16_f32 v71, v72, v73
	v_cvt_pk_bf16_f32 v74, v74, v75
	v_cvt_pk_bf16_f32 v75, v76, v77
	v_cvt_pk_bf16_f32 v78, v78, v79
	v_cvt_pk_bf16_f32 v79, v80, v81
	v_cvt_pk_bf16_f32 v82, v82, v83
	v_cvt_pk_bf16_f32 v83, v84, v85
	global_store_dwordx2 v[248:249], v[70:71], off offset:-64
	global_store_dwordx2 v[248:249], v[74:75], off offset:-32
	global_store_dwordx2 v[248:249], v[78:79], off
	global_store_dwordx2 v[248:249], v[82:83], off offset:32
	v_lshl_add_u64 v[248:249], v[248:249], 0, s[48:49]
	v_sub_f32_e32 v86, v94, v176
	v_sub_f32_e32 v87, v95, v176
	v_sub_f32_e32 v88, v96, v176
	v_sub_f32_e32 v89, v97, v176
	v_cmp_ge_i32_e32 vcc, 0, v108
	s_nop 1
	v_cndmask_b32_e32 v212, v252, v86, vcc
	v_cmp_ge_i32_e32 vcc, 0, v110
	s_nop 1
	v_cndmask_b32_e32 v213, v252, v87, vcc
	v_cmp_ge_i32_e32 vcc, 0, v111
	s_nop 1
	v_cndmask_b32_e32 v214, v252, v88, vcc
	v_cmp_ge_i32_e32 vcc, 0, v177
	s_nop 1
	v_cndmask_b32_e32 v215, v252, v89, vcc
	ds_read_b128 v[148:151], v164 offset:4096
	ds_read_b128 v[152:155], v164 offset:5120
	ds_read_b128 v[156:159], v164 offset:6144
	ds_read_b128 v[160:163], v164 offset:7168
	v_add_f32_e32 v90, v86, v174
	v_add_f32_e32 v91, v87, v174
	v_add_f32_e32 v92, v88, v174
	v_add_f32_e32 v93, v89, v174
	s_cmp_lt_i32 s47, 14
	s_cselect_b64 vcc, -1, s[10:11]
	s_cmp_lt_i32 s47, 6
	s_cselect_b64 vcc, s[6:7], vcc
	v_cndmask_b32_e32 v232, v252, v212, vcc
	v_cndmask_b32_e32 v233, v252, v213, vcc
	v_cndmask_b32_e32 v234, v252, v214, vcc
	v_cndmask_b32_e32 v235, v252, v215, vcc
	s_waitcnt lgkmcnt(2)
	v_mfma_f32_16x16x32_bf16 v[2:5], v[148:151], v[196:199], v[232:235]
	v_mfma_f32_16x16x32_bf16 v[2:5], v[152:155], v[200:203], v[2:5]
	ds_read_b128 v[148:151], v164 offset:8192
	ds_read_b128 v[152:155], v164 offset:9216
	v_add_f32_e32 v86, v90, v174
	v_add_f32_e32 v87, v91, v174
	v_add_f32_e32 v88, v92, v174
	v_add_f32_e32 v89, v93, v174
	s_cmp_lt_i32 s47, 13
	s_cselect_b64 vcc, -1, s[10:11]
	s_cmp_lt_i32 s47, 5
	s_cselect_b64 vcc, s[6:7], vcc
	v_cndmask_b32_e32 v236, v252, v90, vcc
	v_cndmask_b32_e32 v237, v252, v91, vcc
	v_cndmask_b32_e32 v238, v252, v92, vcc
	v_cndmask_b32_e32 v239, v252, v93, vcc
	s_waitcnt lgkmcnt(2)
	v_mfma_f32_16x16x32_bf16 v[6:9], v[156:159], v[196:199], v[236:239]
	v_mfma_f32_16x16x32_bf16 v[6:9], v[160:163], v[200:203], v[6:9]
	ds_read_b128 v[156:159], v164 offset:10240
	ds_read_b128 v[160:163], v164 offset:11264
	v_add_f32_e32 v90, v86, v174
	v_add_f32_e32 v91, v87, v174
	v_add_f32_e32 v92, v88, v174
	v_add_f32_e32 v93, v89, v174
	s_cmp_lt_i32 s47, 12
	s_cselect_b64 vcc, -1, s[10:11]
	s_cmp_lt_i32 s47, 4
	s_cselect_b64 vcc, s[6:7], vcc
	v_cndmask_b32_e32 v232, v252, v86, vcc
	v_cndmask_b32_e32 v233, v252, v87, vcc
	v_cndmask_b32_e32 v234, v252, v88, vcc
	v_cndmask_b32_e32 v235, v252, v89, vcc
	s_waitcnt lgkmcnt(2)
	v_mfma_f32_16x16x32_bf16 v[10:13], v[148:151], v[196:199], v[232:235]
	v_mfma_f32_16x16x32_bf16 v[10:13], v[152:155], v[200:203], v[10:13]
	ds_read_b128 v[148:151], v164 offset:12288
	ds_read_b128 v[152:155], v164 offset:13312
	v_add_f32_e32 v86, v90, v174
	v_add_f32_e32 v87, v91, v174
	v_add_f32_e32 v88, v92, v174
	v_add_f32_e32 v89, v93, v174
	s_cmp_lt_i32 s47, 11
	s_cselect_b64 vcc, -1, s[10:11]
	s_cmp_lt_i32 s47, 3
	s_cselect_b64 vcc, s[6:7], vcc
	v_cndmask_b32_e32 v236, v252, v90, vcc
	v_cndmask_b32_e32 v237, v252, v91, vcc
	v_cndmask_b32_e32 v238, v252, v92, vcc
	v_cndmask_b32_e32 v239, v252, v93, vcc
	s_waitcnt lgkmcnt(2)
; __device__ __forceinline__ f32x4 mfma16(bf16x8 a, bf16x8 b, f32x4 c) { return __builtin_amdgcn_mfma_f32_16x16x32_bf16(a, b, c, 0, 0, 0); }
; __device__ void att_phase(int wv, const Params& p, unsigned char* lds) {
;     ...
;             for (int cb = 0; cb < 24; ++cb) { f32x4 a = {0, 0, 0, 0};
; #pragma unroll
;                 for (int kk = 0; kk < 2; ++kk) { const bf16x8 kf = *(const bf16x8*)(KL + (16 * cb + lr) * KP + 32 * kk + 8 * lq); a = mfma16(kf, qf[kk], a); }
;                 sc[cb] = a; }
;             float mx = sink;
; #pragma unroll
;             for (int cb = 0; cb < 24; ++cb) { const int kb = B - 1 + (cb >> 3); const bool bval = (kb >= sb && kb < se);
; #pragma unroll
;                 for (int j = 0; j < 4; ++j) { const int krel = 16 * cb + 4 * lq + j - 128;
;                     int dist = qrow - krel; dist = dist < 0 ? -dist : dist;
;                     const float v = (bval && dist <= 128) ? sc[cb][j] * 0.125f - slope * (float)dist : -1e30f;
	v_mfma_f32_16x16x32_bf16 v[14:17], v[156:159], v[196:199], v[236:239]
	v_mfma_f32_16x16x32_bf16 v[14:17], v[160:163], v[200:203], v[14:17]
	ds_read_b128 v[156:159], v164 offset:14336
	ds_read_b128 v[160:163], v164 offset:15360
	v_add_f32_e32 v90, v86, v174
	v_add_f32_e32 v91, v87, v174
	v_add_f32_e32 v92, v88, v174
	v_add_f32_e32 v93, v89, v174
	s_cmp_lt_i32 s47, 10
	s_cselect_b64 vcc, -1, s[10:11]
	s_cmp_lt_i32 s47, 2
	s_cselect_b64 vcc, s[6:7], vcc
	v_cndmask_b32_e32 v232, v252, v86, vcc
	v_cndmask_b32_e32 v233, v252, v87, vcc
	v_cndmask_b32_e32 v234, v252, v88, vcc
	v_cndmask_b32_e32 v235, v252, v89, vcc
	s_waitcnt lgkmcnt(2)
	v_mfma_f32_16x16x32_bf16 v[18:21], v[148:151], v[196:199], v[232:235]
	v_mfma_f32_16x16x32_bf16 v[18:21], v[152:155], v[200:203], v[18:21]
	ds_read_b128 v[148:151], v164 offset:16384
	ds_read_b128 v[152:155], v164 offset:17408
	v_add_f32_e32 v86, v90, v174
	v_add_f32_e32 v87, v91, v174
	v_add_f32_e32 v88, v92, v174
	v_add_f32_e32 v89, v93, v174
	s_cmp_lt_i32 s47, 9
	s_cselect_b64 vcc, -1, s[10:11]
	s_cmp_lt_i32 s47, 1
	s_cselect_b64 vcc, s[6:7], vcc
	v_cndmask_b32_e32 v236, v252, v90, vcc
	v_cndmask_b32_e32 v237, v252, v91, vcc
	v_cndmask_b32_e32 v238, v252, v92, vcc
	v_cndmask_b32_e32 v239, v252, v93, vcc
	s_waitcnt lgkmcnt(2)
	v_mfma_f32_16x16x32_bf16 v[22:25], v[156:159], v[196:199], v[236:239]
	v_mfma_f32_16x16x32_bf16 v[22:25], v[160:163], v[200:203], v[22:25]
	ds_read_b128 v[156:159], v164 offset:18432
	ds_read_b128 v[160:163], v164 offset:19456
	v_add_f32_e32 v90, v86, v174
	v_add_f32_e32 v91, v87, v174
	v_add_f32_e32 v92, v88, v174
	v_add_f32_e32 v93, v89, v174
	s_waitcnt lgkmcnt(2)
	v_mfma_f32_16x16x32_bf16 v[26:29], v[148:151], v[196:199], v[86:89]
	v_mfma_f32_16x16x32_bf16 v[26:29], v[152:155], v[200:203], v[26:29]
	ds_read_b128 v[148:151], v164 offset:20480
	ds_read_b128 v[152:155], v164 offset:21504
	s_waitcnt lgkmcnt(2)
	v_mfma_f32_16x16x32_bf16 v[30:33], v[156:159], v[196:199], v[90:93]
	v_mfma_f32_16x16x32_bf16 v[30:33], v[160:163], v[200:203], v[30:33]
	ds_read_b128 v[156:159], v164 offset:22528
	ds_read_b128 v[160:163], v164 offset:23552
	v_sub_f32_e64 v86, -v94, v174
	v_sub_f32_e64 v87, -v95, v174
	v_sub_f32_e64 v88, -v96, v174
	v_sub_f32_e64 v89, -v97, v174
	s_waitcnt lgkmcnt(2)
	v_mfma_f32_16x16x32_bf16 v[34:37], v[148:151], v[196:199], v[98:101]
	v_mfma_f32_16x16x32_bf16 v[34:37], v[152:155], v[200:203], v[34:37]
	ds_read_b128 v[148:151], v164 offset:24576
	ds_read_b128 v[152:155], v164 offset:25600
	v_sub_f32_e32 v90, v86, v174
	v_sub_f32_e32 v91, v87, v174
	v_sub_f32_e32 v92, v88, v174
	v_sub_f32_e32 v93, v89, v174
	s_waitcnt lgkmcnt(2)
	v_mfma_f32_16x16x32_bf16 v[38:41], v[156:159], v[196:199], v[86:89]
	v_mfma_f32_16x16x32_bf16 v[38:41], v[160:163], v[200:203], v[38:41]
	ds_read_b128 v[156:159], v164 offset:26624
	ds_read_b128 v[160:163], v164 offset:27648
	v_sub_f32_e32 v86, v90, v174
	v_sub_f32_e32 v87, v91, v174
	v_sub_f32_e32 v88, v92, v174
	v_sub_f32_e32 v89, v93, v174
	s_cmp_lt_i32 s47, 4
	s_cselect_b64 vcc, -1, s[10:11]
	s_cmp_lt_i32 s47, -4
	s_cselect_b64 vcc, s[6:7], vcc
	v_cndmask_b32_e32 v232, v252, v90, vcc
	v_cndmask_b32_e32 v233, v252, v91, vcc
	v_cndmask_b32_e32 v234, v252, v92, vcc
	v_cndmask_b32_e32 v235, v252, v93, vcc
	s_waitcnt lgkmcnt(2)
	v_mfma_f32_16x16x32_bf16 v[42:45], v[148:151], v[196:199], v[232:235]
	v_mfma_f32_16x16x32_bf16 v[42:45], v[152:155], v[200:203], v[42:45]
	ds_read_b128 v[148:151], v164 offset:28672
	ds_read_b128 v[152:155], v164 offset:29696
	v_sub_f32_e32 v90, v86, v174
	v_sub_f32_e32 v91, v87, v174
	v_sub_f32_e32 v92, v88, v174
	v_sub_f32_e32 v93, v89, v174
	s_cmp_lt_i32 s47, 3
	s_cselect_b64 vcc, -1, s[10:11]
	s_cmp_lt_i32 s47, -5
	s_cselect_b64 vcc, s[6:7], vcc
	v_cndmask_b32_e32 v236, v252, v86, vcc
	v_cndmask_b32_e32 v237, v252, v87, vcc
	v_cndmask_b32_e32 v238, v252, v88, vcc
	v_cndmask_b32_e32 v239, v252, v89, vcc
	s_waitcnt lgkmcnt(2)
	v_mfma_f32_16x16x32_bf16 v[46:49], v[156:159], v[196:199], v[236:239]
	v_mfma_f32_16x16x32_bf16 v[46:49], v[160:163], v[200:203], v[46:49]
	ds_read_b128 v[156:159], v164 offset:30720
	ds_read_b128 v[160:163], v164 offset:31744
	v_sub_f32_e32 v86, v90, v174
	v_sub_f32_e32 v87, v91, v174
	v_sub_f32_e32 v88, v92, v174
	v_sub_f32_e32 v89, v93, v174
	s_cmp_lt_i32 s47, 2
	s_cselect_b64 vcc, -1, s[10:11]
	s_cmp_lt_i32 s47, -6
	s_cselect_b64 vcc, s[6:7], vcc
	v_cndmask_b32_e32 v232, v252, v90, vcc
	v_cndmask_b32_e32 v233, v252, v91, vcc
	v_cndmask_b32_e32 v234, v252, v92, vcc
	v_cndmask_b32_e32 v235, v252, v93, vcc
	s_waitcnt lgkmcnt(2)
	v_mfma_f32_16x16x32_bf16 v[50:53], v[148:151], v[196:199], v[232:235]
	v_mfma_f32_16x16x32_bf16 v[50:53], v[152:155], v[200:203], v[50:53]
	ds_read_b128 v[148:151], v164 offset:32768
	ds_read_b128 v[152:155], v164 offset:33792
	v_sub_f32_e32 v90, v86, v174
	v_sub_f32_e32 v91, v87, v174
	v_sub_f32_e32 v92, v88, v174
	v_sub_f32_e32 v93, v89, v174
	s_cmp_lt_i32 s47, 1
	s_cselect_b64 vcc, -1, s[10:11]
	s_cmp_lt_i32 s47, -7
	s_cselect_b64 vcc, s[6:7], vcc
	v_cndmask_b32_e32 v236, v252, v86, vcc
	v_cndmask_b32_e32 v237, v252, v87, vcc
	v_cndmask_b32_e32 v238, v252, v88, vcc
	v_cndmask_b32_e32 v239, v252, v89, vcc
	s_waitcnt lgkmcnt(2)
	v_mfma_f32_16x16x32_bf16 v[54:57], v[156:159], v[196:199], v[236:239]
	v_mfma_f32_16x16x32_bf16 v[54:57], v[160:163], v[200:203], v[54:57]
	ds_read_b128 v[156:159], v164 offset:34816
	ds_read_b128 v[160:163], v164 offset:35840
	v_sub_f32_e32 v86, v90, v174
	v_sub_f32_e32 v87, v91, v174
	v_sub_f32_e32 v88, v92, v174
	v_sub_f32_e32 v89, v93, v174
	s_cmp_lt_i32 s47, 0
	s_cselect_b64 vcc, -1, s[10:11]
	s_cmp_lt_i32 s47, -8
	s_cselect_b64 vcc, s[6:7], vcc
	v_cndmask_b32_e32 v232, v252, v90, vcc
	v_cndmask_b32_e32 v233, v252, v91, vcc
	v_cndmask_b32_e32 v234, v252, v92, vcc
	v_cndmask_b32_e32 v235, v252, v93, vcc
	s_waitcnt lgkmcnt(2)
; __device__ __forceinline__ f32x4 mfma16(bf16x8 a, bf16x8 b, f32x4 c) { return __builtin_amdgcn_mfma_f32_16x16x32_bf16(a, b, c, 0, 0, 0); }
; __device__ void att_phase(int wv, const Params& p, unsigned char* lds) {
;     ...
;             for (int cb = 0; cb < 24; ++cb) { f32x4 a = {0, 0, 0, 0};
; #pragma unroll
;                 for (int kk = 0; kk < 2; ++kk) { const bf16x8 kf = *(const bf16x8*)(KL + (16 * cb + lr) * KP + 32 * kk + 8 * lq); a = mfma16(kf, qf[kk], a); }
;                 sc[cb] = a; }
;             float mx = sink;
; #pragma unroll
;             for (int cb = 0; cb < 24; ++cb) { const int kb = B - 1 + (cb >> 3); const bool bval = (kb >= sb && kb < se);
; #pragma unroll
;                 for (int j = 0; j < 4; ++j) { const int krel = 16 * cb + 4 * lq + j - 128;
;                     int dist = qrow - krel; dist = dist < 0 ? -dist : dist;
;                     const float v = (bval && dist <= 128) ? sc[cb][j] * 0.125f - slope * (float)dist : -1e30f;
;                     sc[cb][j] = v; mx = fmaxf(mx, v); } }
;             mx = fmaxf(mx, __shfl_xor(mx, 16)); mx = fmaxf(mx, __shfl_xor(mx, 32));
;             float sum = 0.f;
; #pragma unroll
;             for (int cb = 0; cb < 24; ++cb)
; #pragma unroll
;                 for (int j = 0; j < 4; ++j) { const float e = __expf(sc[cb][j] - mx); sc[cb][j] = e; sum += e; }
	v_mfma_f32_16x16x32_bf16 v[58:61], v[148:151], v[196:199], v[232:235]
	v_mfma_f32_16x16x32_bf16 v[58:61], v[152:155], v[200:203], v[58:61]
	ds_read_b128 v[148:151], v164 offset:36864
	ds_read_b128 v[152:155], v164 offset:37888
	v_sub_f32_e32 v90, v86, v174
	v_sub_f32_e32 v91, v87, v174
	v_sub_f32_e32 v92, v88, v174
	v_sub_f32_e32 v93, v89, v174
	v_cmp_le_i32_e32 vcc, 0, v108
	s_nop 1
	v_cndmask_b32_e32 v212, v252, v90, vcc
	v_cmp_le_i32_e32 vcc, 0, v110
	s_nop 1
	v_cndmask_b32_e32 v213, v252, v91, vcc
	v_cmp_le_i32_e32 vcc, 0, v111
	s_nop 1
	v_cndmask_b32_e32 v214, v252, v92, vcc
	v_cmp_le_i32_e32 vcc, 0, v177
	s_nop 1
	v_cndmask_b32_e32 v215, v252, v93, vcc
	s_cmp_lt_i32 s47, -1
	s_cselect_b64 vcc, -1, s[10:11]
	s_cmp_lt_i32 s47, -9
	s_cselect_b64 vcc, s[6:7], vcc
	v_cndmask_b32_e32 v236, v252, v86, vcc
	v_cndmask_b32_e32 v237, v252, v87, vcc
	v_cndmask_b32_e32 v238, v252, v88, vcc
	v_cndmask_b32_e32 v239, v252, v89, vcc
	s_waitcnt lgkmcnt(2)
	v_mfma_f32_16x16x32_bf16 v[62:65], v[156:159], v[196:199], v[236:239]
	v_mfma_f32_16x16x32_bf16 v[62:65], v[160:163], v[200:203], v[62:65]
	s_cmp_lt_i32 s47, -2
	s_cselect_b64 vcc, -1, s[10:11]
	s_cmp_lt_i32 s47, -10
	s_cselect_b64 vcc, s[6:7], vcc
	v_cndmask_b32_e32 v232, v252, v212, vcc
	v_cndmask_b32_e32 v233, v252, v213, vcc
	v_cndmask_b32_e32 v234, v252, v214, vcc
	v_cndmask_b32_e32 v235, v252, v215, vcc
	s_waitcnt lgkmcnt(0)
	v_mfma_f32_16x16x32_bf16 v[66:69], v[148:151], v[196:199], v[232:235]
	v_mfma_f32_16x16x32_bf16 v[66:69], v[152:155], v[200:203], v[66:69]
	s_waitcnt lgkmcnt(7)
	ds_read_b64_tr_b16 v[216:217], v165 offset:5120
	ds_read_b64_tr_b16 v[218:219], v165 offset:7680
	ds_read_b64_tr_b16 v[220:221], v165 offset:5152
	ds_read_b64_tr_b16 v[222:223], v165 offset:7712
	ds_read_b64_tr_b16 v[224:225], v165 offset:5184
	ds_read_b64_tr_b16 v[226:227], v165 offset:7744
	ds_read_b64_tr_b16 v[228:229], v165 offset:5216
	ds_read_b64_tr_b16 v[230:231], v165 offset:7776
	v_max3_f32 v169, v2, v3, v4
	v_max3_f32 v172, v5, v6, v7
	v_max3_f32 v169, v8, v9, v169
	v_max3_f32 v172, v10, v11, v172
	v_max3_f32 v169, v12, v13, v169
	v_max3_f32 v172, v14, v15, v172
	v_max3_f32 v169, v16, v17, v169
	v_max3_f32 v172, v18, v19, v172
	v_max3_f32 v169, v20, v21, v169
	v_max3_f32 v172, v22, v23, v172
	v_max3_f32 v169, v24, v25, v169
	v_max3_f32 v172, v26, v27, v172
	v_max3_f32 v169, v28, v29, v169
	v_max3_f32 v172, v30, v31, v172
	v_max3_f32 v169, v32, v33, v169
	v_max3_f32 v172, v34, v35, v172
	v_max3_f32 v169, v36, v37, v169
	v_max3_f32 v172, v38, v39, v172
	v_max3_f32 v169, v40, v41, v169
	v_max3_f32 v172, v42, v43, v172
	v_max3_f32 v169, v44, v45, v169
	v_max3_f32 v172, v46, v47, v172
	v_max3_f32 v169, v48, v49, v169
	v_max3_f32 v172, v50, v51, v172
	v_max3_f32 v169, v52, v53, v169
	v_max3_f32 v172, v54, v55, v172
	v_max3_f32 v169, v56, v57, v169
	v_max3_f32 v172, v58, v59, v172
	v_max3_f32 v169, v60, v61, v169
	v_max3_f32 v172, v62, v63, v172
	v_max3_f32 v169, v64, v65, v169
	v_max3_f32 v172, v66, v67, v172
	v_max3_f32 v169, v68, v69, v169
	v_max_f32_e32 v169, v169, v172
	v_mul_f32_e32 v169, 0x3e000000, v169
	v_max_f32_e32 v169, v169, v146
	ds_bpermute_b32 v172, v1, v169
	s_waitcnt lgkmcnt(0)
	v_max_f32_e32 v169, v169, v172
	ds_bpermute_b32 v172, v114, v169
	s_waitcnt lgkmcnt(0)
	v_max_f32_e32 v169, v169, v172
	v_mul_f32_e32 v175, 0xbfb8aa3b, v169
	v_mov_b32_e32 v170, 0
	v_mov_b32_e32 v171, 0
	v_fma_f32 v2, v2, s46, v175
	v_fma_f32 v3, v3, s46, v175
	v_fma_f32 v4, v4, s46, v175
	v_fma_f32 v5, v5, s46, v175
	v_exp_f32_e32 v2, v2
	v_exp_f32_e32 v3, v3
	v_exp_f32_e32 v4, v4
	v_exp_f32_e32 v5, v5
	v_fma_f32 v6, v6, s46, v175
	v_fma_f32 v7, v7, s46, v175
	v_fma_f32 v8, v8, s46, v175
	v_fma_f32 v9, v9, s46, v175
	v_exp_f32_e32 v6, v6
	v_exp_f32_e32 v7, v7
	v_exp_f32_e32 v8, v8
	v_exp_f32_e32 v9, v9
	v_add_f32_e32 v171, v171, v2
	v_add_f32_e32 v170, v170, v3
	v_add_f32_e32 v171, v171, v4
	v_add_f32_e32 v170, v170, v5
	v_fma_f32 v10, v10, s46, v175
	v_fma_f32 v11, v11, s46, v175
	v_fma_f32 v12, v12, s46, v175
	v_fma_f32 v13, v13, s46, v175
	v_exp_f32_e32 v10, v10
	v_exp_f32_e32 v11, v11
	v_exp_f32_e32 v12, v12
	v_exp_f32_e32 v13, v13
	v_add_f32_e32 v171, v171, v6
	v_add_f32_e32 v170, v170, v7
	v_add_f32_e32 v171, v171, v8
	v_add_f32_e32 v170, v170, v9
	v_fma_f32 v14, v14, s46, v175
	v_fma_f32 v15, v15, s46, v175
	v_fma_f32 v16, v16, s46, v175
	v_fma_f32 v17, v17, s46, v175
	v_exp_f32_e32 v14, v14
	v_exp_f32_e32 v15, v15
	v_exp_f32_e32 v16, v16
	v_exp_f32_e32 v17, v17
	v_add_f32_e32 v171, v171, v10
	v_add_f32_e32 v170, v170, v11
	v_add_f32_e32 v171, v171, v12
	v_add_f32_e32 v170, v170, v13
	v_fma_f32 v18, v18, s46, v175
	v_fma_f32 v19, v19, s46, v175
	v_fma_f32 v20, v20, s46, v175
	v_fma_f32 v21, v21, s46, v175
	v_exp_f32_e32 v18, v18
	v_exp_f32_e32 v19, v19
	v_exp_f32_e32 v20, v20
	v_exp_f32_e32 v21, v21
	v_add_f32_e32 v171, v171, v14
	v_add_f32_e32 v170, v170, v15
	v_add_f32_e32 v171, v171, v16
	v_add_f32_e32 v170, v170, v17
	v_fma_f32 v22, v22, s46, v175
	v_fma_f32 v23, v23, s46, v175
	v_fma_f32 v24, v24, s46, v175
	v_fma_f32 v25, v25, s46, v175
	v_exp_f32_e32 v22, v22
	v_exp_f32_e32 v23, v23
	v_exp_f32_e32 v24, v24
	v_exp_f32_e32 v25, v25
	v_add_f32_e32 v171, v171, v18
	v_add_f32_e32 v170, v170, v19
	v_add_f32_e32 v171, v171, v20
	v_add_f32_e32 v170, v170, v21
	v_fma_f32 v26, v26, s46, v175
	v_fma_f32 v27, v27, s46, v175
	v_fma_f32 v28, v28, s46, v175
	v_fma_f32 v29, v29, s46, v175
	v_exp_f32_e32 v26, v26
	v_exp_f32_e32 v27, v27
	v_exp_f32_e32 v28, v28
	v_exp_f32_e32 v29, v29
	v_add_f32_e32 v171, v171, v22
	v_add_f32_e32 v170, v170, v23
	v_add_f32_e32 v171, v171, v24
	v_add_f32_e32 v170, v170, v25
; __device__ __forceinline__ unsigned cvt_pk_bf16_asm(float lo, float hi) { unsigned r; asm volatile("v_cvt_pk_bf16_f32 %0, %1, %2" : "=v"(r) : "v"(lo), "v"(hi)); return r; }
; __device__ __forceinline__ f32x4 mfma16(bf16x8 a, bf16x8 b, f32x4 c) { return __builtin_amdgcn_mfma_f32_16x16x32_bf16(a, b, c, 0, 0, 0); }
; __device__ void att_phase(int wv, const Params& p, unsigned char* lds) {
;     ...
;             for (int cb = 0; cb < 24; ++cb)
; #pragma unroll
;                 for (int j = 0; j < 4; ++j) { const float e = __expf(sc[cb][j] - mx); sc[cb][j] = e; sum += e; }
;             sum += __shfl_xor(sum, 16); sum += __shfl_xor(sum, 32);
;             sum += __expf(sink - mx);
;             const float inv = 1.0f / sum;
;             f32x4 oa[4];
; #pragma unroll
;             for (int db = 0; db < 4; ++db) oa[db] = (f32x4){0, 0, 0, 0};
; #pragma unroll
;             for (int ks = 0; ks < 12; ++ks) {
;                 union { bf16x8 v; unsigned u[4]; } pf;
;                 pf.u[0] = cvt_pk_bf16_asm(sc[2 * ks][0], sc[2 * ks][1]); pf.u[1] = cvt_pk_bf16_asm(sc[2 * ks][2], sc[2 * ks][3]);
;                 pf.u[2] = cvt_pk_bf16_asm(sc[2 * ks + 1][0], sc[2 * ks + 1][1]); pf.u[3] = cvt_pk_bf16_asm(sc[2 * ks + 1][2], sc[2 * ks + 1][3]);
; #pragma unroll
;                 for (int db = 0; db < 4; ++db) {
;                     union { bf16x8 v; u32x2 h2[2]; } vf;
;                     const bf16_t* vp = VTL + (16 * db + lr) * VP + 32 * ks + 4 * lq;
;                     vf.h2[0] = *(const u32x2*)vp; vf.h2[1] = *(const u32x2*)(vp + 16);
;                     oa[db] = mfma16(vf.v, pf.v, oa[db]); } }
	v_fma_f32 v30, v30, s46, v175
	v_fma_f32 v31, v31, s46, v175
	v_fma_f32 v32, v32, s46, v175
	v_fma_f32 v33, v33, s46, v175
	v_exp_f32_e32 v30, v30
	v_exp_f32_e32 v31, v31
	v_exp_f32_e32 v32, v32
	v_exp_f32_e32 v33, v33
	v_add_f32_e32 v171, v171, v26
	v_add_f32_e32 v170, v170, v27
	v_add_f32_e32 v171, v171, v28
	v_add_f32_e32 v170, v170, v29
	v_fma_f32 v34, v34, s46, v175
	v_fma_f32 v35, v35, s46, v175
	v_fma_f32 v36, v36, s46, v175
	v_fma_f32 v37, v37, s46, v175
	v_exp_f32_e32 v34, v34
	v_exp_f32_e32 v35, v35
	v_exp_f32_e32 v36, v36
	v_exp_f32_e32 v37, v37
	v_add_f32_e32 v171, v171, v30
	v_add_f32_e32 v170, v170, v31
	v_add_f32_e32 v171, v171, v32
	v_add_f32_e32 v170, v170, v33
	v_fma_f32 v38, v38, s46, v175
	v_fma_f32 v39, v39, s46, v175
	v_fma_f32 v40, v40, s46, v175
	v_fma_f32 v41, v41, s46, v175
	v_exp_f32_e32 v38, v38
	v_exp_f32_e32 v39, v39
	v_exp_f32_e32 v40, v40
	v_exp_f32_e32 v41, v41
	v_add_f32_e32 v171, v171, v34
	v_add_f32_e32 v170, v170, v35
	v_add_f32_e32 v171, v171, v36
	v_add_f32_e32 v170, v170, v37
	v_fma_f32 v42, v42, s46, v175
	v_fma_f32 v43, v43, s46, v175
	v_fma_f32 v44, v44, s46, v175
	v_fma_f32 v45, v45, s46, v175
	v_exp_f32_e32 v42, v42
	v_exp_f32_e32 v43, v43
	v_exp_f32_e32 v44, v44
	v_exp_f32_e32 v45, v45
	v_add_f32_e32 v171, v171, v38
	v_add_f32_e32 v170, v170, v39
	v_add_f32_e32 v171, v171, v40
	v_add_f32_e32 v170, v170, v41
	v_fma_f32 v46, v46, s46, v175
	v_fma_f32 v47, v47, s46, v175
	v_fma_f32 v48, v48, s46, v175
	v_fma_f32 v49, v49, s46, v175
	v_exp_f32_e32 v46, v46
	v_exp_f32_e32 v47, v47
	v_exp_f32_e32 v48, v48
	v_exp_f32_e32 v49, v49
	v_add_f32_e32 v171, v171, v42
	v_add_f32_e32 v170, v170, v43
	v_add_f32_e32 v171, v171, v44
	v_add_f32_e32 v170, v170, v45
	v_fma_f32 v50, v50, s46, v175
	v_fma_f32 v51, v51, s46, v175
	v_fma_f32 v52, v52, s46, v175
	v_fma_f32 v53, v53, s46, v175
	v_exp_f32_e32 v50, v50
	v_exp_f32_e32 v51, v51
	v_exp_f32_e32 v52, v52
	v_exp_f32_e32 v53, v53
	v_add_f32_e32 v171, v171, v46
	v_add_f32_e32 v170, v170, v47
	v_add_f32_e32 v171, v171, v48
	v_add_f32_e32 v170, v170, v49
	v_fma_f32 v54, v54, s46, v175
	v_fma_f32 v55, v55, s46, v175
	v_fma_f32 v56, v56, s46, v175
	v_fma_f32 v57, v57, s46, v175
	v_exp_f32_e32 v54, v54
	v_exp_f32_e32 v55, v55
	v_exp_f32_e32 v56, v56
	v_exp_f32_e32 v57, v57
	v_add_f32_e32 v171, v171, v50
	v_add_f32_e32 v170, v170, v51
	v_add_f32_e32 v171, v171, v52
	v_add_f32_e32 v170, v170, v53
	v_fma_f32 v58, v58, s46, v175
	v_fma_f32 v59, v59, s46, v175
	v_fma_f32 v60, v60, s46, v175
	v_fma_f32 v61, v61, s46, v175
	v_exp_f32_e32 v58, v58
	v_exp_f32_e32 v59, v59
	v_exp_f32_e32 v60, v60
	v_exp_f32_e32 v61, v61
	v_add_f32_e32 v171, v171, v54
	v_add_f32_e32 v170, v170, v55
	v_add_f32_e32 v171, v171, v56
	v_add_f32_e32 v170, v170, v57
	v_fma_f32 v62, v62, s46, v175
	v_fma_f32 v63, v63, s46, v175
	v_fma_f32 v64, v64, s46, v175
	v_fma_f32 v65, v65, s46, v175
	v_exp_f32_e32 v62, v62
	v_exp_f32_e32 v63, v63
	v_exp_f32_e32 v64, v64
	v_exp_f32_e32 v65, v65
	v_add_f32_e32 v171, v171, v58
	v_add_f32_e32 v170, v170, v59
	v_add_f32_e32 v171, v171, v60
	v_add_f32_e32 v170, v170, v61
	v_fma_f32 v66, v66, s46, v175
	v_fma_f32 v67, v67, s46, v175
	v_fma_f32 v68, v68, s46, v175
	v_fma_f32 v69, v69, s46, v175
	v_exp_f32_e32 v66, v66
	v_exp_f32_e32 v67, v67
	v_exp_f32_e32 v68, v68
	v_exp_f32_e32 v69, v69
	v_add_f32_e32 v171, v171, v62
	v_add_f32_e32 v170, v170, v63
	v_add_f32_e32 v171, v171, v64
	v_add_f32_e32 v170, v170, v65
	v_add_f32_e32 v171, v171, v66
	v_add_f32_e32 v170, v170, v67
	v_add_f32_e32 v171, v171, v68
	v_add_f32_e32 v170, v170, v69
	v_add_f32_e32 v170, v170, v171
	v_cvt_pk_bf16_f32 v2, v2, v3
	v_cvt_pk_bf16_f32 v3, v4, v5
	v_cvt_pk_bf16_f32 v4, v6, v7
	v_cvt_pk_bf16_f32 v5, v8, v9
	v_cvt_pk_bf16_f32 v10, v10, v11
	v_cvt_pk_bf16_f32 v11, v12, v13
	v_cvt_pk_bf16_f32 v12, v14, v15
	v_cvt_pk_bf16_f32 v13, v16, v17
	v_cvt_pk_bf16_f32 v18, v18, v19
	v_cvt_pk_bf16_f32 v19, v20, v21
	v_cvt_pk_bf16_f32 v20, v22, v23
	v_cvt_pk_bf16_f32 v21, v24, v25
	v_cvt_pk_bf16_f32 v26, v26, v27
	v_cvt_pk_bf16_f32 v27, v28, v29
	v_cvt_pk_bf16_f32 v28, v30, v31
	v_cvt_pk_bf16_f32 v29, v32, v33
	v_cvt_pk_bf16_f32 v34, v34, v35
	v_cvt_pk_bf16_f32 v35, v36, v37
	v_cvt_pk_bf16_f32 v36, v38, v39
	v_cvt_pk_bf16_f32 v37, v40, v41
	v_cvt_pk_bf16_f32 v42, v42, v43
	v_cvt_pk_bf16_f32 v43, v44, v45
	v_cvt_pk_bf16_f32 v44, v46, v47
	v_cvt_pk_bf16_f32 v45, v48, v49
	v_cvt_pk_bf16_f32 v50, v50, v51
	v_cvt_pk_bf16_f32 v51, v52, v53
	v_cvt_pk_bf16_f32 v52, v54, v55
	v_cvt_pk_bf16_f32 v53, v56, v57
	v_cvt_pk_bf16_f32 v58, v58, v59
	v_cvt_pk_bf16_f32 v59, v60, v61
	v_cvt_pk_bf16_f32 v60, v62, v63
	v_cvt_pk_bf16_f32 v61, v64, v65
	v_cvt_pk_bf16_f32 v66, v66, v67
	v_cvt_pk_bf16_f32 v67, v68, v69
	v_mov_b32_e32 v68, 0
	v_mov_b32_e32 v69, 0
	ds_bpermute_b32 v172, v1, v170
	v_sub_f32_e32 v173, v146, v169
	v_mul_f32_e32 v173, 0x3fb8aa3b, v173
	v_exp_f32_e32 v173, v173
	s_waitcnt lgkmcnt(0)
	v_add_f32_e32 v170, v170, v172
	ds_bpermute_b32 v172, v114, v170
	s_waitcnt lgkmcnt(7)
	ds_read_b64_tr_b16 v[232:233], v165 offset:10240
	ds_read_b64_tr_b16 v[234:235], v165 offset:12800
	ds_read_b64_tr_b16 v[236:237], v165 offset:10272
	ds_read_b64_tr_b16 v[238:239], v165 offset:12832
	ds_read_b64_tr_b16 v[240:241], v165 offset:10304
	ds_read_b64_tr_b16 v[242:243], v165 offset:12864
	ds_read_b64_tr_b16 v[244:245], v165 offset:10336
	ds_read_b64_tr_b16 v[246:247], v165 offset:12896
	s_waitcnt lgkmcnt(8)
	v_mfma_f32_16x16x32_bf16 v[70:73], v[216:219], v[2:5], 0
	v_mfma_f32_16x16x32_bf16 v[74:77], v[220:223], v[2:5], 0
	v_mfma_f32_16x16x32_bf16 v[78:81], v[224:227], v[2:5], 0
	v_mfma_f32_16x16x32_bf16 v[82:85], v[228:231], v[2:5], 0
	v_add_f32_e32 v170, v170, v172
	v_add_f32_e32 v170, v170, v173
	v_rcp_f32_e32 v147, v170
	s_nop 0
	v_fma_f32 v179, -v170, v147, 1.0
	v_fmac_f32_e32 v147, v179, v147
	s_waitcnt lgkmcnt(7)
; __device__ __forceinline__ unsigned cvt_pk_bf16_asm(float lo, float hi) { unsigned r; asm volatile("v_cvt_pk_bf16_f32 %0, %1, %2" : "=v"(r) : "v"(lo), "v"(hi)); return r; }
; __device__ __forceinline__ f32x4 mfma16(bf16x8 a, bf16x8 b, f32x4 c) { return __builtin_amdgcn_mfma_f32_16x16x32_bf16(a, b, c, 0, 0, 0); }
; __device__ void att_phase(int wv, const Params& p, unsigned char* lds) {
;     ...
;             for (int ks = 0; ks < 12; ++ks) {
;                 union { bf16x8 v; unsigned u[4]; } pf;
;                 pf.u[0] = cvt_pk_bf16_asm(sc[2 * ks][0], sc[2 * ks][1]); pf.u[1] = cvt_pk_bf16_asm(sc[2 * ks][2], sc[2 * ks][3]);
;                 pf.u[2] = cvt_pk_bf16_asm(sc[2 * ks + 1][0], sc[2 * ks + 1][1]); pf.u[3] = cvt_pk_bf16_asm(sc[2 * ks + 1][2], sc[2 * ks + 1][3]);
; #pragma unroll
;                 for (int db = 0; db < 4; ++db) {
;                     union { bf16x8 v; u32x2 h2[2]; } vf;
;                     const bf16_t* vp = VTL + (16 * db + lr) * VP + 32 * ks + 4 * lq;
;                     vf.h2[0] = *(const u32x2*)vp; vf.h2[1] = *(const u32x2*)(vp + 16);
;                     oa[db] = mfma16(vf.v, pf.v, oa[db]); } }
	ds_read_b64_tr_b16 v[216:217], v165 offset:15360
	ds_read_b64_tr_b16 v[218:219], v165 offset:17920
	ds_read_b64_tr_b16 v[220:221], v165 offset:15392
	ds_read_b64_tr_b16 v[222:223], v165 offset:17952
	ds_read_b64_tr_b16 v[224:225], v165 offset:15424
	ds_read_b64_tr_b16 v[226:227], v165 offset:17984
	ds_read_b64_tr_b16 v[228:229], v165 offset:15456
	ds_read_b64_tr_b16 v[230:231], v165 offset:18016
	s_waitcnt lgkmcnt(8)
	v_mfma_f32_16x16x32_bf16 v[70:73], v[232:235], v[10:13], v[70:73]
	v_mfma_f32_16x16x32_bf16 v[74:77], v[236:239], v[10:13], v[74:77]
	v_mfma_f32_16x16x32_bf16 v[78:81], v[240:243], v[10:13], v[78:81]
	v_mfma_f32_16x16x32_bf16 v[82:85], v[244:247], v[10:13], v[82:85]
	s_waitcnt lgkmcnt(7)
	ds_read_b64_tr_b16 v[232:233], v165 offset:20480
	ds_read_b64_tr_b16 v[234:235], v165 offset:23040
	ds_read_b64_tr_b16 v[236:237], v165 offset:20512
	ds_read_b64_tr_b16 v[238:239], v165 offset:23072
	ds_read_b64_tr_b16 v[240:241], v165 offset:20544
	ds_read_b64_tr_b16 v[242:243], v165 offset:23104
	ds_read_b64_tr_b16 v[244:245], v165 offset:20576
	ds_read_b64_tr_b16 v[246:247], v165 offset:23136
	s_waitcnt lgkmcnt(8)
	v_mfma_f32_16x16x32_bf16 v[70:73], v[216:219], v[18:21], v[70:73]
	v_mfma_f32_16x16x32_bf16 v[74:77], v[220:223], v[18:21], v[74:77]
	v_mfma_f32_16x16x32_bf16 v[78:81], v[224:227], v[18:21], v[78:81]
	v_mfma_f32_16x16x32_bf16 v[82:85], v[228:231], v[18:21], v[82:85]
	s_waitcnt lgkmcnt(7)
	ds_read_b64_tr_b16 v[216:217], v165 offset:25600
	ds_read_b64_tr_b16 v[218:219], v165 offset:28160
	ds_read_b64_tr_b16 v[220:221], v165 offset:25632
	ds_read_b64_tr_b16 v[222:223], v165 offset:28192
	ds_read_b64_tr_b16 v[224:225], v165 offset:25664
	ds_read_b64_tr_b16 v[226:227], v165 offset:28224
	ds_read_b64_tr_b16 v[228:229], v165 offset:25696
	ds_read_b64_tr_b16 v[230:231], v165 offset:28256
	s_waitcnt lgkmcnt(8)
	v_mfma_f32_16x16x32_bf16 v[70:73], v[232:235], v[26:29], v[70:73]
	v_mfma_f32_16x16x32_bf16 v[74:77], v[236:239], v[26:29], v[74:77]
	v_mfma_f32_16x16x32_bf16 v[78:81], v[240:243], v[26:29], v[78:81]
	v_mfma_f32_16x16x32_bf16 v[82:85], v[244:247], v[26:29], v[82:85]
	s_waitcnt lgkmcnt(7)
	ds_read_b64_tr_b16 v[232:233], v165 offset:30720
	ds_read_b64_tr_b16 v[234:235], v165 offset:33280
	ds_read_b64_tr_b16 v[236:237], v165 offset:30752
	ds_read_b64_tr_b16 v[238:239], v165 offset:33312
	ds_read_b64_tr_b16 v[240:241], v165 offset:30784
	ds_read_b64_tr_b16 v[242:243], v165 offset:33344
	ds_read_b64_tr_b16 v[244:245], v165 offset:30816
	ds_read_b64_tr_b16 v[246:247], v165 offset:33376
	s_waitcnt lgkmcnt(8)
	v_mfma_f32_16x16x32_bf16 v[70:73], v[216:219], v[34:37], v[70:73]
	v_mfma_f32_16x16x32_bf16 v[74:77], v[220:223], v[34:37], v[74:77]
	v_mfma_f32_16x16x32_bf16 v[78:81], v[224:227], v[34:37], v[78:81]
	v_mfma_f32_16x16x32_bf16 v[82:85], v[228:231], v[34:37], v[82:85]
	s_waitcnt lgkmcnt(7)
	ds_read_b64_tr_b16 v[216:217], v165 offset:35840
	ds_read_b64_tr_b16 v[218:219], v165 offset:38400
	ds_read_b64_tr_b16 v[220:221], v165 offset:35872
	ds_read_b64_tr_b16 v[222:223], v165 offset:38432
	ds_read_b64_tr_b16 v[224:225], v165 offset:35904
	ds_read_b64_tr_b16 v[226:227], v165 offset:38464
	ds_read_b64_tr_b16 v[228:229], v165 offset:35936
	ds_read_b64_tr_b16 v[230:231], v165 offset:38496
	s_waitcnt lgkmcnt(8)
	v_mfma_f32_16x16x32_bf16 v[70:73], v[232:235], v[42:45], v[70:73]
	v_mfma_f32_16x16x32_bf16 v[74:77], v[236:239], v[42:45], v[74:77]
	v_mfma_f32_16x16x32_bf16 v[78:81], v[240:243], v[42:45], v[78:81]
	v_mfma_f32_16x16x32_bf16 v[82:85], v[244:247], v[42:45], v[82:85]
	s_waitcnt lgkmcnt(7)
	ds_read_b64_tr_b16 v[232:233], v165 offset:40960
	ds_read_b64_tr_b16 v[234:235], v165 offset:43520
	ds_read_b64_tr_b16 v[236:237], v165 offset:40992
	ds_read_b64_tr_b16 v[238:239], v165 offset:43552
	ds_read_b64_tr_b16 v[240:241], v165 offset:41024
	ds_read_b64_tr_b16 v[242:243], v165 offset:43584
	ds_read_b64_tr_b16 v[244:245], v165 offset:41056
	ds_read_b64_tr_b16 v[246:247], v165 offset:43616
	s_waitcnt lgkmcnt(8)
	v_mfma_f32_16x16x32_bf16 v[70:73], v[216:219], v[50:53], v[70:73]
	v_mfma_f32_16x16x32_bf16 v[74:77], v[220:223], v[50:53], v[74:77]
	v_mfma_f32_16x16x32_bf16 v[78:81], v[224:227], v[50:53], v[78:81]
	v_mfma_f32_16x16x32_bf16 v[82:85], v[228:231], v[50:53], v[82:85]
	s_waitcnt lgkmcnt(7)
	ds_read_b64_tr_b16 v[216:217], v165 offset:46080
	ds_read_b64_tr_b16 v[218:219], v165 offset:46080
	ds_read_b64_tr_b16 v[220:221], v165 offset:46112
	ds_read_b64_tr_b16 v[222:223], v165 offset:46112
	ds_read_b64_tr_b16 v[224:225], v165 offset:46144
	ds_read_b64_tr_b16 v[226:227], v165 offset:46144
	ds_read_b64_tr_b16 v[228:229], v165 offset:46176
	ds_read_b64_tr_b16 v[230:231], v165 offset:46176
	s_waitcnt lgkmcnt(8)
	v_mfma_f32_16x16x32_bf16 v[70:73], v[232:235], v[58:61], v[70:73]
	v_mfma_f32_16x16x32_bf16 v[74:77], v[236:239], v[58:61], v[74:77]
	v_mfma_f32_16x16x32_bf16 v[78:81], v[240:243], v[58:61], v[78:81]
	v_mfma_f32_16x16x32_bf16 v[82:85], v[244:247], v[58:61], v[82:85]
	s_waitcnt lgkmcnt(0)
; __device__ __forceinline__ unsigned cvt_pk_bf16_asm(float lo, float hi) { unsigned r; asm volatile("v_cvt_pk_bf16_f32 %0, %1, %2" : "=v"(r) : "v"(lo), "v"(hi)); return r; }
; __device__ __forceinline__ f32x4 mfma16(bf16x8 a, bf16x8 b, f32x4 c) { return __builtin_amdgcn_mfma_f32_16x16x32_bf16(a, b, c, 0, 0, 0); }
; __device__ void att_phase(int wv, const Params& p, unsigned char* lds) {
;     ...
;             f32x4 sc[24];
; #pragma unroll
;             for (int cb = 0; cb < 24; ++cb) { f32x4 a = {0, 0, 0, 0};
; #pragma unroll
;                 for (int kk = 0; kk < 2; ++kk) { const bf16x8 kf = *(const bf16x8*)(KL + (16 * cb + lr) * KP + 32 * kk + 8 * lq); a = mfma16(kf, qf[kk], a); }
;                 sc[cb] = a; }
;             float mx = sink;
; #pragma unroll
;             for (int cb = 0; cb < 24; ++cb) { const int kb = B - 1 + (cb >> 3); const bool bval = (kb >= sb && kb < se);
; #pragma unroll
;                 for (int j = 0; j < 4; ++j) { const int krel = 16 * cb + 4 * lq + j - 128;
;                     int dist = qrow - krel; dist = dist < 0 ? -dist : dist;
;                     const float v = (bval && dist <= 128) ? sc[cb][j] * 0.125f - slope * (float)dist : -1e30f;
;                     sc[cb][j] = v; mx = fmaxf(mx, v); } }
;     ...
; #pragma unroll
;             for (int db = 0; db < 4; ++db) { const f32x4 o = oa[db] * inv; u32x2 wv; wv.x = cvt_pk_bf16_asm(o[0], o[1]); wv.y = cvt_pk_bf16_asm(o[2], o[3]);
;                 *(u32x2*)(qkv + tokq * 1536 + 64 * h + 16 * db + 4 * lq) = wv; }
	v_mfma_f32_16x16x32_bf16 v[70:73], v[216:219], v[66:69], v[70:73]
	v_mfma_f32_16x16x32_bf16 v[74:77], v[220:223], v[66:69], v[74:77]
	v_mfma_f32_16x16x32_bf16 v[78:81], v[224:227], v[66:69], v[78:81]
	v_mfma_f32_16x16x32_bf16 v[82:85], v[228:231], v[66:69], v[82:85]
	s_nop 7
	s_nop 1
	v_mul_f32_e32 v70, v70, v147
	v_mul_f32_e32 v71, v71, v147
	v_mul_f32_e32 v72, v72, v147
	v_mul_f32_e32 v73, v73, v147
	v_mul_f32_e32 v74, v74, v147
	v_mul_f32_e32 v75, v75, v147
	v_mul_f32_e32 v76, v76, v147
	v_mul_f32_e32 v77, v77, v147
	v_mul_f32_e32 v78, v78, v147
	v_mul_f32_e32 v79, v79, v147
	v_mul_f32_e32 v80, v80, v147
	v_mul_f32_e32 v81, v81, v147
	v_mul_f32_e32 v82, v82, v147
	v_mul_f32_e32 v83, v83, v147
	v_mul_f32_e32 v84, v84, v147
	v_mul_f32_e32 v85, v85, v147
	v_cvt_pk_bf16_f32 v70, v70, v71
	v_cvt_pk_bf16_f32 v71, v72, v73
	v_cvt_pk_bf16_f32 v74, v74, v75
	v_cvt_pk_bf16_f32 v75, v76, v77
	v_cvt_pk_bf16_f32 v78, v78, v79
	v_cvt_pk_bf16_f32 v79, v80, v81
	v_cvt_pk_bf16_f32 v82, v82, v83
	v_cvt_pk_bf16_f32 v83, v84, v85
	global_store_dwordx2 v[248:249], v[70:71], off offset:-64
	global_store_dwordx2 v[248:249], v[74:75], off offset:-32
	global_store_dwordx2 v[248:249], v[78:79], off
	global_store_dwordx2 v[248:249], v[82:83], off offset:32
	v_lshl_add_u64 v[248:249], v[248:249], 0, s[48:49]
	v_sub_f32_e32 v86, v94, v176
	v_sub_f32_e32 v87, v95, v176
	v_sub_f32_e32 v88, v96, v176
	v_sub_f32_e32 v89, v97, v176
	v_cmp_ge_i32_e32 vcc, 0, v108
	s_nop 1
	v_cndmask_b32_e32 v212, v252, v86, vcc
	v_cmp_ge_i32_e32 vcc, 0, v110
	s_nop 1
	v_cndmask_b32_e32 v213, v252, v87, vcc
	v_cmp_ge_i32_e32 vcc, 0, v111
	s_nop 1
	v_cndmask_b32_e32 v214, v252, v88, vcc
	v_cmp_ge_i32_e32 vcc, 0, v177
	s_nop 1
	v_cndmask_b32_e32 v215, v252, v89, vcc
	ds_read_b128 v[148:151], v164 offset:6144
	ds_read_b128 v[152:155], v164 offset:7168
	ds_read_b128 v[156:159], v164 offset:8192
	ds_read_b128 v[160:163], v164 offset:9216
	v_add_f32_e32 v90, v86, v174
	v_add_f32_e32 v91, v87, v174
	v_add_f32_e32 v92, v88, v174
	v_add_f32_e32 v93, v89, v174
	s_cmp_lt_i32 s47, 13
	s_cselect_b64 vcc, -1, s[10:11]
	s_cmp_lt_i32 s47, 5
	s_cselect_b64 vcc, s[6:7], vcc
	v_cndmask_b32_e32 v232, v252, v212, vcc
	v_cndmask_b32_e32 v233, v252, v213, vcc
	v_cndmask_b32_e32 v234, v252, v214, vcc
	v_cndmask_b32_e32 v235, v252, v215, vcc
	s_waitcnt lgkmcnt(2)
	v_mfma_f32_16x16x32_bf16 v[2:5], v[148:151], v[204:207], v[232:235]
	v_mfma_f32_16x16x32_bf16 v[2:5], v[152:155], v[208:211], v[2:5]
	ds_read_b128 v[148:151], v164 offset:10240
	ds_read_b128 v[152:155], v164 offset:11264
	v_add_f32_e32 v86, v90, v174
	v_add_f32_e32 v87, v91, v174
	v_add_f32_e32 v88, v92, v174
	v_add_f32_e32 v89, v93, v174
	s_cmp_lt_i32 s47, 12
	s_cselect_b64 vcc, -1, s[10:11]
	s_cmp_lt_i32 s47, 4
	s_cselect_b64 vcc, s[6:7], vcc
	v_cndmask_b32_e32 v236, v252, v90, vcc
	v_cndmask_b32_e32 v237, v252, v91, vcc
	v_cndmask_b32_e32 v238, v252, v92, vcc
	v_cndmask_b32_e32 v239, v252, v93, vcc
	s_waitcnt lgkmcnt(2)
	v_mfma_f32_16x16x32_bf16 v[6:9], v[156:159], v[204:207], v[236:239]
	v_mfma_f32_16x16x32_bf16 v[6:9], v[160:163], v[208:211], v[6:9]
	ds_read_b128 v[156:159], v164 offset:12288
	ds_read_b128 v[160:163], v164 offset:13312
	v_add_f32_e32 v90, v86, v174
	v_add_f32_e32 v91, v87, v174
	v_add_f32_e32 v92, v88, v174
	v_add_f32_e32 v93, v89, v174
	s_cmp_lt_i32 s47, 11
	s_cselect_b64 vcc, -1, s[10:11]
	s_cmp_lt_i32 s47, 3
	s_cselect_b64 vcc, s[6:7], vcc
	v_cndmask_b32_e32 v232, v252, v86, vcc
	v_cndmask_b32_e32 v233, v252, v87, vcc
	v_cndmask_b32_e32 v234, v252, v88, vcc
	v_cndmask_b32_e32 v235, v252, v89, vcc
	s_waitcnt lgkmcnt(2)
	v_mfma_f32_16x16x32_bf16 v[10:13], v[148:151], v[204:207], v[232:235]
	v_mfma_f32_16x16x32_bf16 v[10:13], v[152:155], v[208:211], v[10:13]
	ds_read_b128 v[148:151], v164 offset:14336
	ds_read_b128 v[152:155], v164 offset:15360
	v_add_f32_e32 v86, v90, v174
	v_add_f32_e32 v87, v91, v174
	v_add_f32_e32 v88, v92, v174
	v_add_f32_e32 v89, v93, v174
	s_cmp_lt_i32 s47, 10
	s_cselect_b64 vcc, -1, s[10:11]
	s_cmp_lt_i32 s47, 2
	s_cselect_b64 vcc, s[6:7], vcc
	v_cndmask_b32_e32 v236, v252, v90, vcc
	v_cndmask_b32_e32 v237, v252, v91, vcc
	v_cndmask_b32_e32 v238, v252, v92, vcc
	v_cndmask_b32_e32 v239, v252, v93, vcc
	s_waitcnt lgkmcnt(2)
	v_mfma_f32_16x16x32_bf16 v[14:17], v[156:159], v[204:207], v[236:239]
	v_mfma_f32_16x16x32_bf16 v[14:17], v[160:163], v[208:211], v[14:17]
	ds_read_b128 v[156:159], v164 offset:16384
	ds_read_b128 v[160:163], v164 offset:17408
	v_add_f32_e32 v90, v86, v174
	v_add_f32_e32 v91, v87, v174
	v_add_f32_e32 v92, v88, v174
	v_add_f32_e32 v93, v89, v174
	s_cmp_lt_i32 s47, 9
	s_cselect_b64 vcc, -1, s[10:11]
	s_cmp_lt_i32 s47, 1
	s_cselect_b64 vcc, s[6:7], vcc
	v_cndmask_b32_e32 v232, v252, v86, vcc
	v_cndmask_b32_e32 v233, v252, v87, vcc
	v_cndmask_b32_e32 v234, v252, v88, vcc
	v_cndmask_b32_e32 v235, v252, v89, vcc
	s_waitcnt lgkmcnt(2)
	v_mfma_f32_16x16x32_bf16 v[18:21], v[148:151], v[204:207], v[232:235]
	v_mfma_f32_16x16x32_bf16 v[18:21], v[152:155], v[208:211], v[18:21]
	ds_read_b128 v[148:151], v164 offset:18432
	ds_read_b128 v[152:155], v164 offset:19456
	v_add_f32_e32 v86, v90, v174
	v_add_f32_e32 v87, v91, v174
	v_add_f32_e32 v88, v92, v174
	v_add_f32_e32 v89, v93, v174
	s_waitcnt lgkmcnt(2)
	v_mfma_f32_16x16x32_bf16 v[22:25], v[156:159], v[204:207], v[90:93]
	v_mfma_f32_16x16x32_bf16 v[22:25], v[160:163], v[208:211], v[22:25]
	ds_read_b128 v[156:159], v164 offset:20480
	ds_read_b128 v[160:163], v164 offset:21504
	v_add_f32_e32 v90, v86, v174
	v_add_f32_e32 v91, v87, v174
	v_add_f32_e32 v92, v88, v174
	v_add_f32_e32 v93, v89, v174
	s_waitcnt lgkmcnt(2)
; __device__ __forceinline__ f32x4 mfma16(bf16x8 a, bf16x8 b, f32x4 c) { return __builtin_amdgcn_mfma_f32_16x16x32_bf16(a, b, c, 0, 0, 0); }
; __device__ void att_phase(int wv, const Params& p, unsigned char* lds) {
;     ...
;             f32x4 sc[24];
; #pragma unroll
;             for (int cb = 0; cb < 24; ++cb) { f32x4 a = {0, 0, 0, 0};
; #pragma unroll
;                 for (int kk = 0; kk < 2; ++kk) { const bf16x8 kf = *(const bf16x8*)(KL + (16 * cb + lr) * KP + 32 * kk + 8 * lq); a = mfma16(kf, qf[kk], a); }
;                 sc[cb] = a; }
;             float mx = sink;
; #pragma unroll
;             for (int cb = 0; cb < 24; ++cb) { const int kb = B - 1 + (cb >> 3); const bool bval = (kb >= sb && kb < se);
; #pragma unroll
;                 for (int j = 0; j < 4; ++j) { const int krel = 16 * cb + 4 * lq + j - 128;
;                     int dist = qrow - krel; dist = dist < 0 ? -dist : dist;
;                     const float v = (bval && dist <= 128) ? sc[cb][j] * 0.125f - slope * (float)dist : -1e30f;
;                     sc[cb][j] = v; mx = fmaxf(mx, v); } }
	v_mfma_f32_16x16x32_bf16 v[26:29], v[148:151], v[204:207], v[86:89]
	v_mfma_f32_16x16x32_bf16 v[26:29], v[152:155], v[208:211], v[26:29]
	ds_read_b128 v[148:151], v164 offset:22528
	ds_read_b128 v[152:155], v164 offset:23552
	s_waitcnt lgkmcnt(2)
	v_mfma_f32_16x16x32_bf16 v[30:33], v[156:159], v[204:207], v[90:93]
	v_mfma_f32_16x16x32_bf16 v[30:33], v[160:163], v[208:211], v[30:33]
	ds_read_b128 v[156:159], v164 offset:24576
	ds_read_b128 v[160:163], v164 offset:25600
	v_sub_f32_e64 v86, -v94, v174
	v_sub_f32_e64 v87, -v95, v174
	v_sub_f32_e64 v88, -v96, v174
	v_sub_f32_e64 v89, -v97, v174
	s_waitcnt lgkmcnt(2)
	v_mfma_f32_16x16x32_bf16 v[34:37], v[148:151], v[204:207], v[98:101]
	v_mfma_f32_16x16x32_bf16 v[34:37], v[152:155], v[208:211], v[34:37]
	ds_read_b128 v[148:151], v164 offset:26624
	ds_read_b128 v[152:155], v164 offset:27648
	v_sub_f32_e32 v90, v86, v174
	v_sub_f32_e32 v91, v87, v174
	v_sub_f32_e32 v92, v88, v174
	v_sub_f32_e32 v93, v89, v174
	s_cmp_lt_i32 s47, 4
	s_cselect_b64 vcc, -1, s[10:11]
	s_cmp_lt_i32 s47, -4
	s_cselect_b64 vcc, s[6:7], vcc
	v_cndmask_b32_e32 v236, v252, v86, vcc
	v_cndmask_b32_e32 v237, v252, v87, vcc
	v_cndmask_b32_e32 v238, v252, v88, vcc
	v_cndmask_b32_e32 v239, v252, v89, vcc
	s_waitcnt lgkmcnt(2)
	v_mfma_f32_16x16x32_bf16 v[38:41], v[156:159], v[204:207], v[236:239]
	v_mfma_f32_16x16x32_bf16 v[38:41], v[160:163], v[208:211], v[38:41]
	ds_read_b128 v[156:159], v164 offset:28672
	ds_read_b128 v[160:163], v164 offset:29696
	v_sub_f32_e32 v86, v90, v174
	v_sub_f32_e32 v87, v91, v174
	v_sub_f32_e32 v88, v92, v174
	v_sub_f32_e32 v89, v93, v174
	s_cmp_lt_i32 s47, 3
	s_cselect_b64 vcc, -1, s[10:11]
	s_cmp_lt_i32 s47, -5
	s_cselect_b64 vcc, s[6:7], vcc
	v_cndmask_b32_e32 v232, v252, v90, vcc
	v_cndmask_b32_e32 v233, v252, v91, vcc
	v_cndmask_b32_e32 v234, v252, v92, vcc
	v_cndmask_b32_e32 v235, v252, v93, vcc
	s_waitcnt lgkmcnt(2)
	v_mfma_f32_16x16x32_bf16 v[42:45], v[148:151], v[204:207], v[232:235]
	v_mfma_f32_16x16x32_bf16 v[42:45], v[152:155], v[208:211], v[42:45]
	ds_read_b128 v[148:151], v164 offset:30720
	ds_read_b128 v[152:155], v164 offset:31744
	v_sub_f32_e32 v90, v86, v174
	v_sub_f32_e32 v91, v87, v174
	v_sub_f32_e32 v92, v88, v174
	v_sub_f32_e32 v93, v89, v174
	s_cmp_lt_i32 s47, 2
	s_cselect_b64 vcc, -1, s[10:11]
	s_cmp_lt_i32 s47, -6
	s_cselect_b64 vcc, s[6:7], vcc
	v_cndmask_b32_e32 v236, v252, v86, vcc
	v_cndmask_b32_e32 v237, v252, v87, vcc
	v_cndmask_b32_e32 v238, v252, v88, vcc
	v_cndmask_b32_e32 v239, v252, v89, vcc
	s_waitcnt lgkmcnt(2)
	v_mfma_f32_16x16x32_bf16 v[46:49], v[156:159], v[204:207], v[236:239]
	v_mfma_f32_16x16x32_bf16 v[46:49], v[160:163], v[208:211], v[46:49]
	ds_read_b128 v[156:159], v164 offset:32768
	ds_read_b128 v[160:163], v164 offset:33792
	v_sub_f32_e32 v86, v90, v174
	v_sub_f32_e32 v87, v91, v174
	v_sub_f32_e32 v88, v92, v174
	v_sub_f32_e32 v89, v93, v174
	s_cmp_lt_i32 s47, 1
	s_cselect_b64 vcc, -1, s[10:11]
	s_cmp_lt_i32 s47, -7
	s_cselect_b64 vcc, s[6:7], vcc
	v_cndmask_b32_e32 v232, v252, v90, vcc
	v_cndmask_b32_e32 v233, v252, v91, vcc
	v_cndmask_b32_e32 v234, v252, v92, vcc
	v_cndmask_b32_e32 v235, v252, v93, vcc
	s_waitcnt lgkmcnt(2)
	v_mfma_f32_16x16x32_bf16 v[50:53], v[148:151], v[204:207], v[232:235]
	v_mfma_f32_16x16x32_bf16 v[50:53], v[152:155], v[208:211], v[50:53]
	ds_read_b128 v[148:151], v164 offset:34816
	ds_read_b128 v[152:155], v164 offset:35840
	v_sub_f32_e32 v90, v86, v174
	v_sub_f32_e32 v91, v87, v174
	v_sub_f32_e32 v92, v88, v174
	v_sub_f32_e32 v93, v89, v174
	s_cmp_lt_i32 s47, 0
	s_cselect_b64 vcc, -1, s[10:11]
	s_cmp_lt_i32 s47, -8
	s_cselect_b64 vcc, s[6:7], vcc
	v_cndmask_b32_e32 v236, v252, v86, vcc
	v_cndmask_b32_e32 v237, v252, v87, vcc
	v_cndmask_b32_e32 v238, v252, v88, vcc
	v_cndmask_b32_e32 v239, v252, v89, vcc
	s_waitcnt lgkmcnt(2)
	v_mfma_f32_16x16x32_bf16 v[54:57], v[156:159], v[204:207], v[236:239]
	v_mfma_f32_16x16x32_bf16 v[54:57], v[160:163], v[208:211], v[54:57]
	ds_read_b128 v[156:159], v164 offset:36864
	ds_read_b128 v[160:163], v164 offset:37888
	v_sub_f32_e32 v86, v90, v174
	v_sub_f32_e32 v87, v91, v174
	v_sub_f32_e32 v88, v92, v174
	v_sub_f32_e32 v89, v93, v174
	s_cmp_lt_i32 s47, -1
	s_cselect_b64 vcc, -1, s[10:11]
	s_cmp_lt_i32 s47, -9
	s_cselect_b64 vcc, s[6:7], vcc
	v_cndmask_b32_e32 v232, v252, v90, vcc
	v_cndmask_b32_e32 v233, v252, v91, vcc
	v_cndmask_b32_e32 v234, v252, v92, vcc
	v_cndmask_b32_e32 v235, v252, v93, vcc
	s_waitcnt lgkmcnt(2)
	v_mfma_f32_16x16x32_bf16 v[58:61], v[148:151], v[204:207], v[232:235]
	v_mfma_f32_16x16x32_bf16 v[58:61], v[152:155], v[208:211], v[58:61]
	ds_read_b128 v[148:151], v164 offset:38912
	ds_read_b128 v[152:155], v164 offset:39936
	v_sub_f32_e32 v90, v86, v174
	v_sub_f32_e32 v91, v87, v174
	v_sub_f32_e32 v92, v88, v174
	v_sub_f32_e32 v93, v89, v174
	v_cmp_le_i32_e32 vcc, 0, v108
	s_nop 1
	v_cndmask_b32_e32 v212, v252, v90, vcc
	v_cmp_le_i32_e32 vcc, 0, v110
	s_nop 1
	v_cndmask_b32_e32 v213, v252, v91, vcc
	v_cmp_le_i32_e32 vcc, 0, v111
	s_nop 1
	v_cndmask_b32_e32 v214, v252, v92, vcc
	v_cmp_le_i32_e32 vcc, 0, v177
	s_nop 1
	v_cndmask_b32_e32 v215, v252, v93, vcc
	s_cmp_lt_i32 s47, -2
	s_cselect_b64 vcc, -1, s[10:11]
	s_cmp_lt_i32 s47, -10
	s_cselect_b64 vcc, s[6:7], vcc
	v_cndmask_b32_e32 v236, v252, v86, vcc
	v_cndmask_b32_e32 v237, v252, v87, vcc
	v_cndmask_b32_e32 v238, v252, v88, vcc
	v_cndmask_b32_e32 v239, v252, v89, vcc
	s_waitcnt lgkmcnt(2)
	v_mfma_f32_16x16x32_bf16 v[62:65], v[156:159], v[204:207], v[236:239]
	v_mfma_f32_16x16x32_bf16 v[62:65], v[160:163], v[208:211], v[62:65]
	s_cmp_lt_i32 s47, -3
	s_cselect_b64 vcc, -1, s[10:11]
	s_cmp_lt_i32 s47, -11
	s_cselect_b64 vcc, s[6:7], vcc
	v_cndmask_b32_e32 v232, v252, v212, vcc
	v_cndmask_b32_e32 v233, v252, v213, vcc
	v_cndmask_b32_e32 v234, v252, v214, vcc
	v_cndmask_b32_e32 v235, v252, v215, vcc
	s_waitcnt lgkmcnt(0)
; __device__ void att_phase(int wv, const Params& p, unsigned char* lds) {
;     ...
;             float mx = sink;
; #pragma unroll
;             for (int cb = 0; cb < 24; ++cb) { const int kb = B - 1 + (cb >> 3); const bool bval = (kb >= sb && kb < se);
; #pragma unroll
;                 for (int j = 0; j < 4; ++j) { const int krel = 16 * cb + 4 * lq + j - 128;
;                     int dist = qrow - krel; dist = dist < 0 ? -dist : dist;
;                     const float v = (bval && dist <= 128) ? sc[cb][j] * 0.125f - slope * (float)dist : -1e30f;
;                     sc[cb][j] = v; mx = fmaxf(mx, v); } }
;             mx = fmaxf(mx, __shfl_xor(mx, 16)); mx = fmaxf(mx, __shfl_xor(mx, 32));
;             float sum = 0.f;
; #pragma unroll
;             for (int cb = 0; cb < 24; ++cb)
; #pragma unroll
;                 for (int j = 0; j < 4; ++j) { const float e = __expf(sc[cb][j] - mx); sc[cb][j] = e; sum += e; }
	v_mfma_f32_16x16x32_bf16 v[66:69], v[148:151], v[204:207], v[232:235]
	v_mfma_f32_16x16x32_bf16 v[66:69], v[152:155], v[208:211], v[66:69]
	s_waitcnt lgkmcnt(7)
	ds_read_b64_tr_b16 v[216:217], v165 offset:7680
	ds_read_b64_tr_b16 v[218:219], v165 offset:10240
	ds_read_b64_tr_b16 v[220:221], v165 offset:7712
	ds_read_b64_tr_b16 v[222:223], v165 offset:10272
	ds_read_b64_tr_b16 v[224:225], v165 offset:7744
	ds_read_b64_tr_b16 v[226:227], v165 offset:10304
	ds_read_b64_tr_b16 v[228:229], v165 offset:7776
	ds_read_b64_tr_b16 v[230:231], v165 offset:10336
	v_max3_f32 v169, v2, v3, v4
	v_max3_f32 v172, v5, v6, v7
	v_max3_f32 v169, v8, v9, v169
	v_max3_f32 v172, v10, v11, v172
	v_max3_f32 v169, v12, v13, v169
	v_max3_f32 v172, v14, v15, v172
	v_max3_f32 v169, v16, v17, v169
	v_max3_f32 v172, v18, v19, v172
	v_max3_f32 v169, v20, v21, v169
	v_max3_f32 v172, v22, v23, v172
	v_max3_f32 v169, v24, v25, v169
	v_max3_f32 v172, v26, v27, v172
	v_max3_f32 v169, v28, v29, v169
	v_max3_f32 v172, v30, v31, v172
	v_max3_f32 v169, v32, v33, v169
	v_max3_f32 v172, v34, v35, v172
	v_max3_f32 v169, v36, v37, v169
	v_max3_f32 v172, v38, v39, v172
	v_max3_f32 v169, v40, v41, v169
	v_max3_f32 v172, v42, v43, v172
	v_max3_f32 v169, v44, v45, v169
	v_max3_f32 v172, v46, v47, v172
	v_max3_f32 v169, v48, v49, v169
	v_max3_f32 v172, v50, v51, v172
	v_max3_f32 v169, v52, v53, v169
	v_max3_f32 v172, v54, v55, v172
	v_max3_f32 v169, v56, v57, v169
	v_max3_f32 v172, v58, v59, v172
	v_max3_f32 v169, v60, v61, v169
	v_max3_f32 v172, v62, v63, v172
	v_max3_f32 v169, v64, v65, v169
	v_max3_f32 v172, v66, v67, v172
	v_max3_f32 v169, v68, v69, v169
	v_max_f32_e32 v169, v169, v172
	v_mul_f32_e32 v169, 0x3e000000, v169
	v_max_f32_e32 v169, v169, v146
	ds_bpermute_b32 v172, v1, v169
	s_waitcnt lgkmcnt(0)
	v_max_f32_e32 v169, v169, v172
	ds_bpermute_b32 v172, v114, v169
	s_waitcnt lgkmcnt(0)
	v_max_f32_e32 v169, v169, v172
	v_mul_f32_e32 v175, 0xbfb8aa3b, v169
	v_mov_b32_e32 v170, 0
	v_mov_b32_e32 v171, 0
	v_fma_f32 v2, v2, s46, v175
	v_fma_f32 v3, v3, s46, v175
	v_fma_f32 v4, v4, s46, v175
	v_fma_f32 v5, v5, s46, v175
	v_exp_f32_e32 v2, v2
	v_exp_f32_e32 v3, v3
	v_exp_f32_e32 v4, v4
	v_exp_f32_e32 v5, v5
	v_fma_f32 v6, v6, s46, v175
	v_fma_f32 v7, v7, s46, v175
	v_fma_f32 v8, v8, s46, v175
	v_fma_f32 v9, v9, s46, v175
	v_exp_f32_e32 v6, v6
	v_exp_f32_e32 v7, v7
	v_exp_f32_e32 v8, v8
	v_exp_f32_e32 v9, v9
	v_add_f32_e32 v171, v171, v2
	v_add_f32_e32 v170, v170, v3
	v_add_f32_e32 v171, v171, v4
	v_add_f32_e32 v170, v170, v5
	v_fma_f32 v10, v10, s46, v175
	v_fma_f32 v11, v11, s46, v175
	v_fma_f32 v12, v12, s46, v175
	v_fma_f32 v13, v13, s46, v175
	v_exp_f32_e32 v10, v10
	v_exp_f32_e32 v11, v11
	v_exp_f32_e32 v12, v12
	v_exp_f32_e32 v13, v13
	v_add_f32_e32 v171, v171, v6
	v_add_f32_e32 v170, v170, v7
	v_add_f32_e32 v171, v171, v8
	v_add_f32_e32 v170, v170, v9
	v_fma_f32 v14, v14, s46, v175
	v_fma_f32 v15, v15, s46, v175
	v_fma_f32 v16, v16, s46, v175
	v_fma_f32 v17, v17, s46, v175
	v_exp_f32_e32 v14, v14
	v_exp_f32_e32 v15, v15
	v_exp_f32_e32 v16, v16
	v_exp_f32_e32 v17, v17
	v_add_f32_e32 v171, v171, v10
	v_add_f32_e32 v170, v170, v11
	v_add_f32_e32 v171, v171, v12
	v_add_f32_e32 v170, v170, v13
	v_fma_f32 v18, v18, s46, v175
	v_fma_f32 v19, v19, s46, v175
	v_fma_f32 v20, v20, s46, v175
	v_fma_f32 v21, v21, s46, v175
	v_exp_f32_e32 v18, v18
	v_exp_f32_e32 v19, v19
	v_exp_f32_e32 v20, v20
	v_exp_f32_e32 v21, v21
	v_add_f32_e32 v171, v171, v14
	v_add_f32_e32 v170, v170, v15
	v_add_f32_e32 v171, v171, v16
	v_add_f32_e32 v170, v170, v17
	v_fma_f32 v22, v22, s46, v175
	v_fma_f32 v23, v23, s46, v175
	v_fma_f32 v24, v24, s46, v175
	v_fma_f32 v25, v25, s46, v175
	v_exp_f32_e32 v22, v22
	v_exp_f32_e32 v23, v23
	v_exp_f32_e32 v24, v24
	v_exp_f32_e32 v25, v25
	v_add_f32_e32 v171, v171, v18
	v_add_f32_e32 v170, v170, v19
	v_add_f32_e32 v171, v171, v20
	v_add_f32_e32 v170, v170, v21
	v_fma_f32 v26, v26, s46, v175
	v_fma_f32 v27, v27, s46, v175
	v_fma_f32 v28, v28, s46, v175
	v_fma_f32 v29, v29, s46, v175
	v_exp_f32_e32 v26, v26
	v_exp_f32_e32 v27, v27
	v_exp_f32_e32 v28, v28
	v_exp_f32_e32 v29, v29
	v_add_f32_e32 v171, v171, v22
	v_add_f32_e32 v170, v170, v23
	v_add_f32_e32 v171, v171, v24
	v_add_f32_e32 v170, v170, v25
	v_fma_f32 v30, v30, s46, v175
	v_fma_f32 v31, v31, s46, v175
	v_fma_f32 v32, v32, s46, v175
	v_fma_f32 v33, v33, s46, v175
	v_exp_f32_e32 v30, v30
	v_exp_f32_e32 v31, v31
	v_exp_f32_e32 v32, v32
	v_exp_f32_e32 v33, v33
	v_add_f32_e32 v171, v171, v26
	v_add_f32_e32 v170, v170, v27
	v_add_f32_e32 v171, v171, v28
	v_add_f32_e32 v170, v170, v29
	v_fma_f32 v34, v34, s46, v175
	v_fma_f32 v35, v35, s46, v175
	v_fma_f32 v36, v36, s46, v175
	v_fma_f32 v37, v37, s46, v175
	v_exp_f32_e32 v34, v34
	v_exp_f32_e32 v35, v35
	v_exp_f32_e32 v36, v36
	v_exp_f32_e32 v37, v37
	v_add_f32_e32 v171, v171, v30
	v_add_f32_e32 v170, v170, v31
	v_add_f32_e32 v171, v171, v32
	v_add_f32_e32 v170, v170, v33
	v_fma_f32 v38, v38, s46, v175
	v_fma_f32 v39, v39, s46, v175
	v_fma_f32 v40, v40, s46, v175
	v_fma_f32 v41, v41, s46, v175
	v_exp_f32_e32 v38, v38
	v_exp_f32_e32 v39, v39
	v_exp_f32_e32 v40, v40
	v_exp_f32_e32 v41, v41
	v_add_f32_e32 v171, v171, v34
	v_add_f32_e32 v170, v170, v35
	v_add_f32_e32 v171, v171, v36
	v_add_f32_e32 v170, v170, v37
	v_fma_f32 v42, v42, s46, v175
	v_fma_f32 v43, v43, s46, v175
	v_fma_f32 v44, v44, s46, v175
	v_fma_f32 v45, v45, s46, v175
	v_exp_f32_e32 v42, v42
	v_exp_f32_e32 v43, v43
	v_exp_f32_e32 v44, v44
	v_exp_f32_e32 v45, v45
	v_add_f32_e32 v171, v171, v38
	v_add_f32_e32 v170, v170, v39
	v_add_f32_e32 v171, v171, v40
	v_add_f32_e32 v170, v170, v41
	v_fma_f32 v46, v46, s46, v175
; __device__ __forceinline__ unsigned cvt_pk_bf16_asm(float lo, float hi) { unsigned r; asm volatile("v_cvt_pk_bf16_f32 %0, %1, %2" : "=v"(r) : "v"(lo), "v"(hi)); return r; }
; __device__ __forceinline__ f32x4 mfma16(bf16x8 a, bf16x8 b, f32x4 c) { return __builtin_amdgcn_mfma_f32_16x16x32_bf16(a, b, c, 0, 0, 0); }
; __device__ void att_phase(int wv, const Params& p, unsigned char* lds) {
;     ...
;             mx = fmaxf(mx, __shfl_xor(mx, 16)); mx = fmaxf(mx, __shfl_xor(mx, 32));
;             float sum = 0.f;
; #pragma unroll
;             for (int cb = 0; cb < 24; ++cb)
; #pragma unroll
;                 for (int j = 0; j < 4; ++j) { const float e = __expf(sc[cb][j] - mx); sc[cb][j] = e; sum += e; }
;             sum += __shfl_xor(sum, 16); sum += __shfl_xor(sum, 32);
;             sum += __expf(sink - mx);
;             const float inv = 1.0f / sum;
;             f32x4 oa[4];
; #pragma unroll
;             for (int db = 0; db < 4; ++db) oa[db] = (f32x4){0, 0, 0, 0};
; #pragma unroll
;             for (int ks = 0; ks < 12; ++ks) {
;                 union { bf16x8 v; unsigned u[4]; } pf;
;                 pf.u[0] = cvt_pk_bf16_asm(sc[2 * ks][0], sc[2 * ks][1]); pf.u[1] = cvt_pk_bf16_asm(sc[2 * ks][2], sc[2 * ks][3]);
;                 pf.u[2] = cvt_pk_bf16_asm(sc[2 * ks + 1][0], sc[2 * ks + 1][1]); pf.u[3] = cvt_pk_bf16_asm(sc[2 * ks + 1][2], sc[2 * ks + 1][3]);
; #pragma unroll
;                 for (int db = 0; db < 4; ++db) {
;                     union { bf16x8 v; u32x2 h2[2]; } vf;
;                     const bf16_t* vp = VTL + (16 * db + lr) * VP + 32 * ks + 4 * lq;
;                     vf.h2[0] = *(const u32x2*)vp; vf.h2[1] = *(const u32x2*)(vp + 16);
;                     oa[db] = mfma16(vf.v, pf.v, oa[db]); } }
	v_fma_f32 v47, v47, s46, v175
	v_fma_f32 v48, v48, s46, v175
	v_fma_f32 v49, v49, s46, v175
	v_exp_f32_e32 v46, v46
	v_exp_f32_e32 v47, v47
	v_exp_f32_e32 v48, v48
	v_exp_f32_e32 v49, v49
	v_add_f32_e32 v171, v171, v42
	v_add_f32_e32 v170, v170, v43
	v_add_f32_e32 v171, v171, v44
	v_add_f32_e32 v170, v170, v45
	v_fma_f32 v50, v50, s46, v175
	v_fma_f32 v51, v51, s46, v175
	v_fma_f32 v52, v52, s46, v175
	v_fma_f32 v53, v53, s46, v175
	v_exp_f32_e32 v50, v50
	v_exp_f32_e32 v51, v51
	v_exp_f32_e32 v52, v52
	v_exp_f32_e32 v53, v53
	v_add_f32_e32 v171, v171, v46
	v_add_f32_e32 v170, v170, v47
	v_add_f32_e32 v171, v171, v48
	v_add_f32_e32 v170, v170, v49
	v_fma_f32 v54, v54, s46, v175
	v_fma_f32 v55, v55, s46, v175
	v_fma_f32 v56, v56, s46, v175
	v_fma_f32 v57, v57, s46, v175
	v_exp_f32_e32 v54, v54
	v_exp_f32_e32 v55, v55
	v_exp_f32_e32 v56, v56
	v_exp_f32_e32 v57, v57
	v_add_f32_e32 v171, v171, v50
	v_add_f32_e32 v170, v170, v51
	v_add_f32_e32 v171, v171, v52
	v_add_f32_e32 v170, v170, v53
	v_fma_f32 v58, v58, s46, v175
	v_fma_f32 v59, v59, s46, v175
	v_fma_f32 v60, v60, s46, v175
	v_fma_f32 v61, v61, s46, v175
	v_exp_f32_e32 v58, v58
	v_exp_f32_e32 v59, v59
	v_exp_f32_e32 v60, v60
	v_exp_f32_e32 v61, v61
	v_add_f32_e32 v171, v171, v54
	v_add_f32_e32 v170, v170, v55
	v_add_f32_e32 v171, v171, v56
	v_add_f32_e32 v170, v170, v57
	v_fma_f32 v62, v62, s46, v175
	v_fma_f32 v63, v63, s46, v175
	v_fma_f32 v64, v64, s46, v175
	v_fma_f32 v65, v65, s46, v175
	v_exp_f32_e32 v62, v62
	v_exp_f32_e32 v63, v63
	v_exp_f32_e32 v64, v64
	v_exp_f32_e32 v65, v65
	v_add_f32_e32 v171, v171, v58
	v_add_f32_e32 v170, v170, v59
	v_add_f32_e32 v171, v171, v60
	v_add_f32_e32 v170, v170, v61
	v_fma_f32 v66, v66, s46, v175
	v_fma_f32 v67, v67, s46, v175
	v_fma_f32 v68, v68, s46, v175
	v_fma_f32 v69, v69, s46, v175
	v_exp_f32_e32 v66, v66
	v_exp_f32_e32 v67, v67
	v_exp_f32_e32 v68, v68
	v_exp_f32_e32 v69, v69
	v_add_f32_e32 v171, v171, v62
	v_add_f32_e32 v170, v170, v63
	v_add_f32_e32 v171, v171, v64
	v_add_f32_e32 v170, v170, v65
	v_add_f32_e32 v171, v171, v66
	v_add_f32_e32 v170, v170, v67
	v_add_f32_e32 v171, v171, v68
	v_add_f32_e32 v170, v170, v69
	v_add_f32_e32 v170, v170, v171
	v_cvt_pk_bf16_f32 v2, v2, v3
	v_cvt_pk_bf16_f32 v3, v4, v5
	v_cvt_pk_bf16_f32 v4, v6, v7
	v_cvt_pk_bf16_f32 v5, v8, v9
	v_cvt_pk_bf16_f32 v10, v10, v11
	v_cvt_pk_bf16_f32 v11, v12, v13
	v_cvt_pk_bf16_f32 v12, v14, v15
	v_cvt_pk_bf16_f32 v13, v16, v17
	v_cvt_pk_bf16_f32 v18, v18, v19
	v_cvt_pk_bf16_f32 v19, v20, v21
	v_cvt_pk_bf16_f32 v20, v22, v23
	v_cvt_pk_bf16_f32 v21, v24, v25
	v_cvt_pk_bf16_f32 v26, v26, v27
	v_cvt_pk_bf16_f32 v27, v28, v29
	v_cvt_pk_bf16_f32 v28, v30, v31
	v_cvt_pk_bf16_f32 v29, v32, v33
	v_cvt_pk_bf16_f32 v34, v34, v35
	v_cvt_pk_bf16_f32 v35, v36, v37
	v_cvt_pk_bf16_f32 v36, v38, v39
	v_cvt_pk_bf16_f32 v37, v40, v41
	v_cvt_pk_bf16_f32 v42, v42, v43
	v_cvt_pk_bf16_f32 v43, v44, v45
	v_cvt_pk_bf16_f32 v44, v46, v47
	v_cvt_pk_bf16_f32 v45, v48, v49
	v_cvt_pk_bf16_f32 v50, v50, v51
	v_cvt_pk_bf16_f32 v51, v52, v53
	v_cvt_pk_bf16_f32 v52, v54, v55
	v_cvt_pk_bf16_f32 v53, v56, v57
	v_cvt_pk_bf16_f32 v58, v58, v59
	v_cvt_pk_bf16_f32 v59, v60, v61
	v_cvt_pk_bf16_f32 v60, v62, v63
	v_cvt_pk_bf16_f32 v61, v64, v65
	v_cvt_pk_bf16_f32 v66, v66, v67
	v_cvt_pk_bf16_f32 v67, v68, v69
	v_mov_b32_e32 v68, 0
	v_mov_b32_e32 v69, 0
	ds_bpermute_b32 v172, v1, v170
	v_sub_f32_e32 v173, v146, v169
	v_mul_f32_e32 v173, 0x3fb8aa3b, v173
	v_exp_f32_e32 v173, v173
	s_waitcnt lgkmcnt(0)
	v_add_f32_e32 v170, v170, v172
	ds_bpermute_b32 v172, v114, v170
	s_waitcnt lgkmcnt(7)
	ds_read_b64_tr_b16 v[232:233], v165 offset:12800
	ds_read_b64_tr_b16 v[234:235], v165 offset:15360
	ds_read_b64_tr_b16 v[236:237], v165 offset:12832
	ds_read_b64_tr_b16 v[238:239], v165 offset:15392
	ds_read_b64_tr_b16 v[240:241], v165 offset:12864
	ds_read_b64_tr_b16 v[242:243], v165 offset:15424
	ds_read_b64_tr_b16 v[244:245], v165 offset:12896
	ds_read_b64_tr_b16 v[246:247], v165 offset:15456
	s_waitcnt lgkmcnt(8)
	v_mfma_f32_16x16x32_bf16 v[70:73], v[216:219], v[2:5], 0
	v_mfma_f32_16x16x32_bf16 v[74:77], v[220:223], v[2:5], 0
	v_mfma_f32_16x16x32_bf16 v[78:81], v[224:227], v[2:5], 0
	v_mfma_f32_16x16x32_bf16 v[82:85], v[228:231], v[2:5], 0
	v_add_f32_e32 v170, v170, v172
	v_add_f32_e32 v170, v170, v173
	v_rcp_f32_e32 v147, v170
	s_nop 0
	v_fma_f32 v179, -v170, v147, 1.0
	v_fmac_f32_e32 v147, v179, v147
	s_waitcnt lgkmcnt(7)
	ds_read_b64_tr_b16 v[216:217], v165 offset:17920
	ds_read_b64_tr_b16 v[218:219], v165 offset:20480
	ds_read_b64_tr_b16 v[220:221], v165 offset:17952
	ds_read_b64_tr_b16 v[222:223], v165 offset:20512
	ds_read_b64_tr_b16 v[224:225], v165 offset:17984
	ds_read_b64_tr_b16 v[226:227], v165 offset:20544
	ds_read_b64_tr_b16 v[228:229], v165 offset:18016
	ds_read_b64_tr_b16 v[230:231], v165 offset:20576
	s_waitcnt lgkmcnt(8)
	v_mfma_f32_16x16x32_bf16 v[70:73], v[232:235], v[10:13], v[70:73]
	v_mfma_f32_16x16x32_bf16 v[74:77], v[236:239], v[10:13], v[74:77]
	v_mfma_f32_16x16x32_bf16 v[78:81], v[240:243], v[10:13], v[78:81]
	v_mfma_f32_16x16x32_bf16 v[82:85], v[244:247], v[10:13], v[82:85]
	s_waitcnt lgkmcnt(7)
; __device__ __forceinline__ unsigned cvt_pk_bf16_asm(float lo, float hi) { unsigned r; asm volatile("v_cvt_pk_bf16_f32 %0, %1, %2" : "=v"(r) : "v"(lo), "v"(hi)); return r; }
; __device__ __forceinline__ f32x4 mfma16(bf16x8 a, bf16x8 b, f32x4 c) { return __builtin_amdgcn_mfma_f32_16x16x32_bf16(a, b, c, 0, 0, 0); }
; __device__ void att_phase(int wv, const Params& p, unsigned char* lds) {
;     ...
;             for (int ks = 0; ks < 12; ++ks) {
;                 union { bf16x8 v; unsigned u[4]; } pf;
;                 pf.u[0] = cvt_pk_bf16_asm(sc[2 * ks][0], sc[2 * ks][1]); pf.u[1] = cvt_pk_bf16_asm(sc[2 * ks][2], sc[2 * ks][3]);
;                 pf.u[2] = cvt_pk_bf16_asm(sc[2 * ks + 1][0], sc[2 * ks + 1][1]); pf.u[3] = cvt_pk_bf16_asm(sc[2 * ks + 1][2], sc[2 * ks + 1][3]);
; #pragma unroll
;                 for (int db = 0; db < 4; ++db) {
;                     union { bf16x8 v; u32x2 h2[2]; } vf;
;                     const bf16_t* vp = VTL + (16 * db + lr) * VP + 32 * ks + 4 * lq;
;                     vf.h2[0] = *(const u32x2*)vp; vf.h2[1] = *(const u32x2*)(vp + 16);
;                     oa[db] = mfma16(vf.v, pf.v, oa[db]); } }
; #pragma unroll
;             for (int db = 0; db < 4; ++db) { const f32x4 o = oa[db] * inv; u32x2 wv; wv.x = cvt_pk_bf16_asm(o[0], o[1]); wv.y = cvt_pk_bf16_asm(o[2], o[3]);
;                 *(u32x2*)(qkv + tokq * 1536 + 64 * h + 16 * db + 4 * lq) = wv; }
	ds_read_b64_tr_b16 v[232:233], v165 offset:23040
	ds_read_b64_tr_b16 v[234:235], v165 offset:25600
	ds_read_b64_tr_b16 v[236:237], v165 offset:23072
	ds_read_b64_tr_b16 v[238:239], v165 offset:25632
	ds_read_b64_tr_b16 v[240:241], v165 offset:23104
	ds_read_b64_tr_b16 v[242:243], v165 offset:25664
	ds_read_b64_tr_b16 v[244:245], v165 offset:23136
	ds_read_b64_tr_b16 v[246:247], v165 offset:25696
	s_waitcnt lgkmcnt(8)
	v_mfma_f32_16x16x32_bf16 v[70:73], v[216:219], v[18:21], v[70:73]
	v_mfma_f32_16x16x32_bf16 v[74:77], v[220:223], v[18:21], v[74:77]
	v_mfma_f32_16x16x32_bf16 v[78:81], v[224:227], v[18:21], v[78:81]
	v_mfma_f32_16x16x32_bf16 v[82:85], v[228:231], v[18:21], v[82:85]
	s_waitcnt lgkmcnt(7)
	ds_read_b64_tr_b16 v[216:217], v165 offset:28160
	ds_read_b64_tr_b16 v[218:219], v165 offset:30720
	ds_read_b64_tr_b16 v[220:221], v165 offset:28192
	ds_read_b64_tr_b16 v[222:223], v165 offset:30752
	ds_read_b64_tr_b16 v[224:225], v165 offset:28224
	ds_read_b64_tr_b16 v[226:227], v165 offset:30784
	ds_read_b64_tr_b16 v[228:229], v165 offset:28256
	ds_read_b64_tr_b16 v[230:231], v165 offset:30816
	s_waitcnt lgkmcnt(8)
	v_mfma_f32_16x16x32_bf16 v[70:73], v[232:235], v[26:29], v[70:73]
	v_mfma_f32_16x16x32_bf16 v[74:77], v[236:239], v[26:29], v[74:77]
	v_mfma_f32_16x16x32_bf16 v[78:81], v[240:243], v[26:29], v[78:81]
	v_mfma_f32_16x16x32_bf16 v[82:85], v[244:247], v[26:29], v[82:85]
	s_waitcnt lgkmcnt(7)
	ds_read_b64_tr_b16 v[232:233], v165 offset:33280
	ds_read_b64_tr_b16 v[234:235], v165 offset:35840
	ds_read_b64_tr_b16 v[236:237], v165 offset:33312
	ds_read_b64_tr_b16 v[238:239], v165 offset:35872
	ds_read_b64_tr_b16 v[240:241], v165 offset:33344
	ds_read_b64_tr_b16 v[242:243], v165 offset:35904
	ds_read_b64_tr_b16 v[244:245], v165 offset:33376
	ds_read_b64_tr_b16 v[246:247], v165 offset:35936
	s_waitcnt lgkmcnt(8)
	v_mfma_f32_16x16x32_bf16 v[70:73], v[216:219], v[34:37], v[70:73]
	v_mfma_f32_16x16x32_bf16 v[74:77], v[220:223], v[34:37], v[74:77]
	v_mfma_f32_16x16x32_bf16 v[78:81], v[224:227], v[34:37], v[78:81]
	v_mfma_f32_16x16x32_bf16 v[82:85], v[228:231], v[34:37], v[82:85]
	s_waitcnt lgkmcnt(7)
	ds_read_b64_tr_b16 v[216:217], v165 offset:38400
	ds_read_b64_tr_b16 v[218:219], v165 offset:40960
	ds_read_b64_tr_b16 v[220:221], v165 offset:38432
	ds_read_b64_tr_b16 v[222:223], v165 offset:40992
	ds_read_b64_tr_b16 v[224:225], v165 offset:38464
	ds_read_b64_tr_b16 v[226:227], v165 offset:41024
	ds_read_b64_tr_b16 v[228:229], v165 offset:38496
	ds_read_b64_tr_b16 v[230:231], v165 offset:41056
	s_waitcnt lgkmcnt(8)
	v_mfma_f32_16x16x32_bf16 v[70:73], v[232:235], v[42:45], v[70:73]
	v_mfma_f32_16x16x32_bf16 v[74:77], v[236:239], v[42:45], v[74:77]
	v_mfma_f32_16x16x32_bf16 v[78:81], v[240:243], v[42:45], v[78:81]
	v_mfma_f32_16x16x32_bf16 v[82:85], v[244:247], v[42:45], v[82:85]
	s_waitcnt lgkmcnt(7)
	ds_read_b64_tr_b16 v[232:233], v165 offset:43520
	ds_read_b64_tr_b16 v[234:235], v165 offset:46080
	ds_read_b64_tr_b16 v[236:237], v165 offset:43552
	ds_read_b64_tr_b16 v[238:239], v165 offset:46112
	ds_read_b64_tr_b16 v[240:241], v165 offset:43584
	ds_read_b64_tr_b16 v[242:243], v165 offset:46144
	ds_read_b64_tr_b16 v[244:245], v165 offset:43616
	ds_read_b64_tr_b16 v[246:247], v165 offset:46176
	s_waitcnt lgkmcnt(8)
	v_mfma_f32_16x16x32_bf16 v[70:73], v[216:219], v[50:53], v[70:73]
	v_mfma_f32_16x16x32_bf16 v[74:77], v[220:223], v[50:53], v[74:77]
	v_mfma_f32_16x16x32_bf16 v[78:81], v[224:227], v[50:53], v[78:81]
	v_mfma_f32_16x16x32_bf16 v[82:85], v[228:231], v[50:53], v[82:85]
	s_waitcnt lgkmcnt(7)
	ds_read_b64_tr_b16 v[216:217], v165 offset:48640
	ds_read_b64_tr_b16 v[218:219], v165 offset:48640
	ds_read_b64_tr_b16 v[220:221], v165 offset:48672
	ds_read_b64_tr_b16 v[222:223], v165 offset:48672
	ds_read_b64_tr_b16 v[224:225], v165 offset:48704
	ds_read_b64_tr_b16 v[226:227], v165 offset:48704
	ds_read_b64_tr_b16 v[228:229], v165 offset:48736
	ds_read_b64_tr_b16 v[230:231], v165 offset:48736
	s_waitcnt lgkmcnt(8)
	v_mfma_f32_16x16x32_bf16 v[70:73], v[232:235], v[58:61], v[70:73]
	v_mfma_f32_16x16x32_bf16 v[74:77], v[236:239], v[58:61], v[74:77]
	v_mfma_f32_16x16x32_bf16 v[78:81], v[240:243], v[58:61], v[78:81]
	v_mfma_f32_16x16x32_bf16 v[82:85], v[244:247], v[58:61], v[82:85]
	s_waitcnt lgkmcnt(0)
	v_mfma_f32_16x16x32_bf16 v[70:73], v[216:219], v[66:69], v[70:73]
	v_mfma_f32_16x16x32_bf16 v[74:77], v[220:223], v[66:69], v[74:77]
	v_mfma_f32_16x16x32_bf16 v[78:81], v[224:227], v[66:69], v[78:81]
	v_mfma_f32_16x16x32_bf16 v[82:85], v[228:231], v[66:69], v[82:85]
	s_nop 7
	s_nop 1
	v_mul_f32_e32 v70, v70, v147
	v_mul_f32_e32 v71, v71, v147
	v_mul_f32_e32 v72, v72, v147
	v_mul_f32_e32 v73, v73, v147
	v_mul_f32_e32 v74, v74, v147
	v_mul_f32_e32 v75, v75, v147
	v_mul_f32_e32 v76, v76, v147
	v_mul_f32_e32 v77, v77, v147
	v_mul_f32_e32 v78, v78, v147
	v_mul_f32_e32 v79, v79, v147
	v_mul_f32_e32 v80, v80, v147
	v_mul_f32_e32 v81, v81, v147
	v_mul_f32_e32 v82, v82, v147
	v_mul_f32_e32 v83, v83, v147
	v_mul_f32_e32 v84, v84, v147
	v_mul_f32_e32 v85, v85, v147
	v_cvt_pk_bf16_f32 v70, v70, v71
	v_cvt_pk_bf16_f32 v71, v72, v73
	v_cvt_pk_bf16_f32 v74, v74, v75
	v_cvt_pk_bf16_f32 v75, v76, v77
	v_cvt_pk_bf16_f32 v78, v78, v79
	v_cvt_pk_bf16_f32 v79, v80, v81
	v_cvt_pk_bf16_f32 v82, v82, v83
	v_cvt_pk_bf16_f32 v83, v84, v85
	global_store_dwordx2 v[248:249], v[70:71], off offset:-64
	global_store_dwordx2 v[248:249], v[74:75], off offset:-32
	global_store_dwordx2 v[248:249], v[78:79], off
	global_store_dwordx2 v[248:249], v[82:83], off offset:32
	s_branch .Latt_done
